# RWKV pass 1: the L and P scan tasks of one (head, chunk) now run together in one workgroup (4 state rows per lane share the per-step LDS operands), one 256-step task per workgroup instead of two
# speedup vs baseline: 1.0307x; 1.0149x over previous
.LBB0_700:
	s_cmp_lt_i32 s42, 6
	s_cselect_b64 s[0:1], -1, 0
	s_cmp_gt_i32 s43, 5
	s_cselect_b64 s[2:3], -1, 0
	s_and_b64 s[0:1], s[0:1], s[2:3]
	s_andn2_b64 vcc, exec, s[0:1]
	s_cbranch_vccnz .LBB0_1123
	v_mbcnt_hi_u32_b32 v0, -1, v210
	v_add_u32_e32 v64, s91, v0
	s_load_dword s60, s[88:89], 0x160
	s_mov_b32 s61, s90
	s_mov_b64 s[44:45], s[88:89]
	s_add_u32 s38, s88, 0x160
	v_readfirstlane_b32 s0, v64
	s_waitcnt lgkmcnt(0)
	s_mov_b32 s62, s60
	s_load_dwordx2 s[46:47], s[44:45], 0x150
	s_addc_u32 s39, s89, 0
	s_ashr_i32 s63, s0, 6
	v_and_b32_e32 v66, 63, v64
	v_and_b32_e32 v67, 15, v64
	s_waitcnt lgkmcnt(0)
	s_add_u32 s56, s46, 0x6200000
	s_addc_u32 s57, s47, 0
	s_add_u32 s58, s46, 0xfa00000
	s_addc_u32 s59, s47, 0
	s_add_u32 s64, s46, 0xfe00000
	s_addc_u32 s65, s47, 0
	s_cmpk_gt_i32 s61, 0x1ff
	v_lshrrev_b32_e32 v39, 4, v66
	s_cbranch_scc1 .LBB0_765
	v_lshl_or_b32 v0, s63, 3, v39
	v_lshlrev_b32_e32 v2, 2, v67
	v_or_b32_e32 v1, 1, v2
	v_or_b32_e32 v5, 3, v2
	v_or_b32_e32 v4, 4, v0
	s_mov_b32 s1, 0x92492493
	v_cmp_eq_u32_e64 s[6:7], v1, v0
	v_cmp_eq_u32_e64 s[10:11], v5, v0
	v_cmp_eq_u32_e64 s[14:15], v1, v4
	v_cmp_eq_u32_e64 s[18:19], v5, v4
	v_mul_hi_i32 v1, v64, s1
	v_add_u32_e32 v5, 0x200, v64
	v_or_b32_e32 v3, 2, v2
	v_add_u32_e32 v1, v1, v64
	v_mul_hi_i32 v6, v5, s1
	v_cmp_eq_u32_e64 s[8:9], v3, v0
	v_cmp_eq_u32_e64 s[16:17], v3, v4
	v_lshrrev_b32_e32 v3, 31, v1
	v_ashrrev_i32_e32 v1, 5, v1
	v_add_u32_e32 v6, v6, v5
	v_add_u32_e32 v3, v1, v3
	v_lshrrev_b32_e32 v7, 31, v6
	v_ashrrev_i32_e32 v6, 5, v6
	v_mul_lo_u32 v1, v3, 56
	v_add_u32_e32 v6, v6, v7
	s_movk_i32 s0, 0x380
	v_sub_u32_e32 v1, v64, v1
	v_mul_lo_u32 v7, v6, 56
	s_movk_i32 s1, 0x600
	v_mad_i64_i32 v[24:25], s[2:3], v3, s0, 0
	v_lshlrev_b32_e32 v26, 4, v1
	v_sub_u32_e32 v52, v5, v7
	v_cmp_lt_i32_e64 s[26:27], 15, v1
	v_mul_lo_u32 v7, v3, s1
	v_lshlrev_b32_e32 v1, 5, v1
	s_movk_i32 s2, 0x180
	v_add_u32_e32 v53, 0, v7
	v_and_b32_e32 v7, 0xffffff00, v1
	v_and_b32_e32 v1, 0xe0, v1
	v_cmp_gt_i32_e64 s[22:23], s2, v64
	s_movk_i32 s2, 0x17f
	v_add3_u32 v54, v53, v7, v1
	v_mul_lo_u32 v56, v6, s1
	v_lshlrev_b32_e32 v1, 3, v52
	v_cmp_lt_i32_e64 s[24:25], s2, v64
	v_mad_i64_i32 v[28:29], s[2:3], v6, s0, 0
	v_add_u32_e32 v57, 0, v56
	v_and_b32_e32 v58, 0x7fffffc0, v1
	v_and_b32_e32 v59, 56, v1
	s_movk_i32 s2, 0xff00
	v_lshl_add_u32 v7, v58, 2, v57
	v_lshlrev_b32_e32 v1, 2, v59
	v_add3_u32 v60, v7, v1, s2
	v_add_u32_e32 v1, 16, v3
	v_mad_i64_i32 v[32:33], s[2:3], v1, s0, 0
	v_add_u32_e32 v1, 16, v6
	v_mad_i64_i32 v[34:35], s[2:3], v1, s0, 0
	v_add_u32_e32 v1, 32, v3
	v_mad_i64_i32 v[36:37], s[2:3], v1, s0, 0
	v_lshrrev_b32_e32 v1, 3, v5
	s_mov_b32 s2, 0x24924925
	v_mul_hi_u32 v38, v1, s2
	v_mul_lo_u32 v1, v38, 56
	v_sub_u32_e32 v61, v5, v1
	v_add_u32_e32 v1, 32, v6
	v_mad_i64_i32 v[44:45], s[2:3], v1, s0, 0
	v_ashrrev_i32_e32 v1, 31, v0
	v_cmp_eq_u32_e64 s[4:5], v2, v0
	v_ashrrev_i32_e32 v27, 31, v26
	v_lshlrev_b32_e32 v30, 4, v52
	v_mov_b32_e32 v43, 0
	v_lshl_add_u32 v63, v0, 2, 0
	v_ashrrev_i32_e32 v5, 31, v4
	v_lshlrev_b64 v[48:49], 8, v[0:1]
	v_lshlrev_b32_e32 v0, 3, v61
	v_cmp_eq_u32_e64 s[12:13], v2, v4
	v_cmp_gt_i32_e64 s[20:21], s0, v64
	v_ashrrev_i32_e32 v31, 31, v30
	v_add_u32_e32 v55, 0xffffff00, v54
	v_cmp_lt_i32_e64 s[28:29], 15, v52
	v_lshlrev_b32_e32 v40, 4, v61
	v_mov_b32_e32 v41, v43
	v_lshl_add_u32 v62, v67, 4, 0
	v_lshlrev_b64 v[46:47], 8, v[4:5]
	v_mul_lo_u32 v65, v38, s1
	v_and_b32_e32 v68, 0x1c0, v0
	v_and_b32_e32 v69, 56, v0
	v_mad_i64_i32 v[50:51], s[2:3], v3, s0, v[26:27]
	v_lshlrev_b32_e32 v42, 2, v2
	s_lshl_b32 s1, s61, 1
	s_branch .LBB0_705
.LBB0_703:
	v_mov_b32_e32 v16, v146
	v_mov_b32_e32 v21, v148
	v_mov_b32_e32 v70, v150
	v_mov_b32_e32 v71, v152
	v_mov_b32_e32 v20, v147
	v_mov_b32_e32 v72, v149
	v_mov_b32_e32 v73, v151
	v_mov_b32_e32 v74, v153
	s_and_b64 s[30:31], s[30:31], exec
	s_cselect_b32 s3, s65, s59
	s_cselect_b32 s33, s64, s58
	s_lshl_b64 s[30:31], s[48:49], 19
	s_add_u32 s30, s33, s30
	s_addc_u32 s3, s3, s31
	s_lshl_b32 s2, s2, 14
	s_add_u32 s2, s30, s2
	s_addc_u32 s3, s3, 0
	s_waitcnt vmcnt(0)
	v_lshl_add_u64 v[0:1], s[2:3], 0, v[42:43]
	v_lshl_add_u64 v[2:3], v[0:1], 0, v[46:47]
	v_lshl_add_u64 v[0:1], v[0:1], 0, v[48:49]
	v_mov_b32_e32 v17, v21
	v_mov_b32_e32 v18, v70
	v_mov_b32_e32 v19, v71
	v_mov_b32_e32 v21, v72
	v_mov_b32_e32 v22, v73
	v_mov_b32_e32 v23, v74
	global_store_dwordx4 v[0:1], v[16:19], off
	global_store_dwordx4 v[2:3], v[20:23], off
	s_mov_b32 s98, 0xffc00000
	s_mov_b32 s99, -1
	v_lshl_add_u64 v[0:1], v[0:1], 0, s[98:99]
	v_lshl_add_u64 v[2:3], v[2:3], 0, s[98:99]
	v_mov_b32_e32 v16, v170
	v_mov_b32_e32 v17, v172
	v_mov_b32_e32 v18, v174
	v_mov_b32_e32 v19, v176
	v_mov_b32_e32 v20, v171
	v_mov_b32_e32 v21, v173
	v_mov_b32_e32 v22, v175
	v_mov_b32_e32 v23, v177
	global_store_dwordx4 v[0:1], v[16:19], off
	global_store_dwordx4 v[2:3], v[20:23], off
	s_waitcnt lgkmcnt(0)
	s_barrier
.LBB0_704:
	s_add_i32 s1, s1, s62
	s_add_i32 s1, s1, s62
	s_cmpk_gt_i32 s1, 0x1ff
	s_cbranch_scc1 .LBB0_765

.LBB0_728:
	s_or_b64 exec, exec, s[34:35]
	s_lshr_b32 s3, s1, 1
	s_and_b32 s30, s1, 1
	s_bitcmp1_b32 s1, 0
	s_cselect_b64 s[34:35], -1, 0
	s_cmp_eq_u32 s30, 0
	s_cselect_b64 s[30:31], -1, 0
	s_and_b64 s[36:37], s[34:35], s[4:5]
	v_cndmask_b32_e64 v16, 0, 1.0, s[36:37]
	s_and_b64 s[36:37], s[34:35], s[6:7]
	v_cndmask_b32_e64 v21, 0, 1.0, s[36:37]
	s_and_b64 s[36:37], s[34:35], s[8:9]
	v_cndmask_b32_e64 v70, 0, 1.0, s[36:37]
	s_and_b64 s[36:37], s[34:35], s[10:11]
	v_cndmask_b32_e64 v71, 0, 1.0, s[36:37]
	s_and_b64 s[36:37], s[34:35], s[12:13]
	v_cndmask_b32_e64 v20, 0, 1.0, s[36:37]
	s_and_b64 s[36:37], s[34:35], s[14:15]
	v_cndmask_b32_e64 v72, 0, 1.0, s[36:37]
	s_and_b64 s[36:37], s[34:35], s[16:17]
	s_and_b32 s3, s3, 31
	v_cndmask_b32_e64 v73, 0, 1.0, s[36:37]
	s_and_b64 s[34:35], s[34:35], s[18:19]
	s_mul_i32 s3, s3, 0x38000
	s_mul_i32 s36, s48, 0x700000
	s_mul_hi_i32 s33, s48, 0x700000
	s_add_u32 s3, s36, s3
	s_waitcnt lgkmcnt(0)
	s_barrier
	v_add_u32_e32 v75, 0, v75
	v_lshlrev_b32_e32 v77, 2, v77
	v_lshlrev_b32_e32 v76, 2, v76
	s_addc_u32 s33, s33, 0
	v_add3_u32 v76, v75, v77, v76
	s_add_u32 s50, s46, s3
	v_cndmask_b32_e64 v74, 0, 1.0, s[34:35]
	v_cmp_lt_i32_e64 s[34:35], 15, v78
	v_add_u32_e32 v77, 0xffffff00, v76
	s_addc_u32 s51, s47, s33
	v_lshl_add_u64 v[18:19], v[22:23], 0, v[18:19]
	s_mov_b32 s33, -2
	v_mov_b32_e32 v146, v16
	v_mov_b32_e32 v148, v21
	v_mov_b32_e32 v150, v70
	v_mov_b32_e32 v152, v71
	v_mov_b32_e32 v147, v20
	v_mov_b32_e32 v149, v72
	v_mov_b32_e32 v151, v73
	v_mov_b32_e32 v153, v74
	v_cndmask_b32_e64 v170, 0, 1.0, s[4:5]
	v_cndmask_b32_e64 v172, 0, 1.0, s[6:7]
	v_cndmask_b32_e64 v174, 0, 1.0, s[8:9]
	v_cndmask_b32_e64 v176, 0, 1.0, s[10:11]
	v_cndmask_b32_e64 v171, 0, 1.0, s[12:13]
	v_cndmask_b32_e64 v173, 0, 1.0, s[14:15]
	v_cndmask_b32_e64 v175, 0, 1.0, s[16:17]
	v_cndmask_b32_e64 v177, 0, 1.0, s[18:19]
	s_branch .LBB0_731

.LBB0_730:
	v_add_u32_e32 v22, 0x6000, v63
	ds_read2_b32 v[22:23], v22 offset0:192 offset1:196
	ds_read_b128 v[78:81], v62 offset:26112
	ds_read_b128 v[82:85], v62 offset:26624
	ds_read_b128 v[86:89], v62 offset:27136
	ds_read_b128 v[90:93], v62 offset:27392
	ds_read_b128 v[94:97], v62 offset:25856
	ds_read_b128 v[98:101], v62 offset:25600
	ds_read_b128 v[102:105], v62 offset:25088
	ds_read_b128 v[106:109], v62 offset:24576
	v_add_u32_e32 v110, 0x6800, v63
	ds_read2_b32 v[110:111], v110 offset0:64 offset1:68
	s_waitcnt lgkmcnt(1)
	v_pk_mul_f32 v[154:155], v[146:147], v[98:99] op_sel:[0,0] op_sel_hi:[1,0]
	v_pk_fma_f32 v[154:155], v[148:149], v[98:99], v[154:155] op_sel:[0,1,0] op_sel_hi:[1,1,1]
	v_pk_fma_f32 v[154:155], v[150:151], v[100:101], v[154:155] op_sel:[0,0,0] op_sel_hi:[1,0,1]
	v_pk_fma_f32 v[154:155], v[152:153], v[100:101], v[154:155] op_sel:[0,1,0] op_sel_hi:[1,1,1]
	v_pk_mul_f32 v[178:179], v[170:171], v[98:99] op_sel:[0,0] op_sel_hi:[1,0]
	v_pk_fma_f32 v[178:179], v[172:173], v[98:99], v[178:179] op_sel:[0,1,0] op_sel_hi:[1,1,1]
	v_pk_fma_f32 v[178:179], v[174:175], v[100:101], v[178:179] op_sel:[0,0,0] op_sel_hi:[1,0,1]
	v_pk_fma_f32 v[178:179], v[176:177], v[100:101], v[178:179] op_sel:[0,1,0] op_sel_hi:[1,1,1]
	v_pk_mul_f32 v[156:157], v[22:23], v[102:103] op_sel:[0,0] op_sel_hi:[1,0]
	v_add_f32_dpp v154, v154, v154 quad_perm:[1,0,3,2] row_mask:0xf bank_mask:0xf bound_ctrl:1
	v_add_f32_dpp v155, v155, v155 quad_perm:[1,0,3,2] row_mask:0xf bank_mask:0xf bound_ctrl:1
	v_add_f32_dpp v178, v178, v178 quad_perm:[1,0,3,2] row_mask:0xf bank_mask:0xf bound_ctrl:1
	v_add_f32_dpp v179, v179, v179 quad_perm:[1,0,3,2] row_mask:0xf bank_mask:0xf bound_ctrl:1
	v_add_f32_dpp v154, v154, v154 quad_perm:[2,3,0,1] row_mask:0xf bank_mask:0xf bound_ctrl:1
	v_add_f32_dpp v155, v155, v155 quad_perm:[2,3,0,1] row_mask:0xf bank_mask:0xf bound_ctrl:1
	v_add_f32_dpp v178, v178, v178 quad_perm:[2,3,0,1] row_mask:0xf bank_mask:0xf bound_ctrl:1
	v_add_f32_dpp v179, v179, v179 quad_perm:[2,3,0,1] row_mask:0xf bank_mask:0xf bound_ctrl:1
	v_add_f32_dpp v154, v154, v154 row_half_mirror row_mask:0xf bank_mask:0xf bound_ctrl:1
	v_add_f32_dpp v155, v155, v155 row_half_mirror row_mask:0xf bank_mask:0xf bound_ctrl:1
	v_add_f32_dpp v178, v178, v178 row_half_mirror row_mask:0xf bank_mask:0xf bound_ctrl:1
	v_add_f32_dpp v179, v179, v179 row_half_mirror row_mask:0xf bank_mask:0xf bound_ctrl:1
	v_add_f32_dpp v154, v154, v154 row_mirror row_mask:0xf bank_mask:0xf bound_ctrl:1
	v_add_f32_dpp v155, v155, v155 row_mirror row_mask:0xf bank_mask:0xf bound_ctrl:1
	v_add_f32_dpp v178, v178, v178 row_mirror row_mask:0xf bank_mask:0xf bound_ctrl:1
	v_add_f32_dpp v179, v179, v179 row_mirror row_mask:0xf bank_mask:0xf bound_ctrl:1
	v_pk_mul_f32 v[158:159], v[22:23], v[102:103] op_sel:[0,1] op_sel_hi:[1,1]
	v_pk_mul_f32 v[160:161], v[22:23], v[104:105] op_sel:[0,0] op_sel_hi:[1,0]
	v_pk_mul_f32 v[162:163], v[22:23], v[104:105] op_sel:[0,1] op_sel_hi:[1,1]
	v_pk_fma_f32 v[156:157], v[154:155], v[94:95], v[156:157] op_sel:[0,0,0] op_sel_hi:[1,0,1] neg_lo:[1,0,0] neg_hi:[1,0,0]
	v_pk_fma_f32 v[158:159], v[154:155], v[94:95], v[158:159] op_sel:[0,1,0] op_sel_hi:[1,1,1] neg_lo:[1,0,0] neg_hi:[1,0,0]
	v_pk_fma_f32 v[160:161], v[154:155], v[96:97], v[160:161] op_sel:[0,0,0] op_sel_hi:[1,0,1] neg_lo:[1,0,0] neg_hi:[1,0,0]
	v_pk_fma_f32 v[162:163], v[154:155], v[96:97], v[162:163] op_sel:[0,1,0] op_sel_hi:[1,1,1] neg_lo:[1,0,0] neg_hi:[1,0,0]
	v_pk_mul_f32 v[180:181], v[178:179], v[94:95] op_sel:[0,0] op_sel_hi:[1,0] neg_lo:[1,0] neg_hi:[1,0]
	v_pk_mul_f32 v[182:183], v[178:179], v[94:95] op_sel:[0,1] op_sel_hi:[1,1] neg_lo:[1,0] neg_hi:[1,0]
	v_pk_mul_f32 v[184:185], v[178:179], v[96:97] op_sel:[0,0] op_sel_hi:[1,0] neg_lo:[1,0] neg_hi:[1,0]
	v_pk_mul_f32 v[186:187], v[178:179], v[96:97] op_sel:[0,1] op_sel_hi:[1,1] neg_lo:[1,0] neg_hi:[1,0]
	v_pk_fma_f32 v[146:147], v[146:147], v[106:107], v[156:157] op_sel:[0,0,0] op_sel_hi:[1,0,1]
	v_pk_fma_f32 v[148:149], v[148:149], v[106:107], v[158:159] op_sel:[0,1,0] op_sel_hi:[1,1,1]
	v_pk_fma_f32 v[150:151], v[150:151], v[108:109], v[160:161] op_sel:[0,0,0] op_sel_hi:[1,0,1]
	v_pk_fma_f32 v[152:153], v[152:153], v[108:109], v[162:163] op_sel:[0,1,0] op_sel_hi:[1,1,1]
	v_pk_fma_f32 v[170:171], v[170:171], v[106:107], v[180:181] op_sel:[0,0,0] op_sel_hi:[1,0,1]
	v_pk_fma_f32 v[172:173], v[172:173], v[106:107], v[182:183] op_sel:[0,1,0] op_sel_hi:[1,1,1]
	v_pk_fma_f32 v[174:175], v[174:175], v[108:109], v[184:185] op_sel:[0,0,0] op_sel_hi:[1,0,1]
	v_pk_fma_f32 v[176:177], v[176:177], v[108:109], v[186:187] op_sel:[0,1,0] op_sel_hi:[1,1,1]
	ds_read_b128 v[94:97], v62 offset:27648
	ds_read_b128 v[98:101], v62 offset:28160
	ds_read_b128 v[102:105], v62 offset:28672
	ds_read_b128 v[106:109], v62 offset:28928
	v_add_u32_e32 v22, 0x6c00, v63
	ds_read2_b32 v[22:23], v22 offset0:192 offset1:196
	s_waitcnt lgkmcnt(5)
	v_pk_mul_f32 v[154:155], v[146:147], v[86:87] op_sel:[0,0] op_sel_hi:[1,0]
	v_pk_fma_f32 v[154:155], v[148:149], v[86:87], v[154:155] op_sel:[0,1,0] op_sel_hi:[1,1,1]
	v_pk_fma_f32 v[154:155], v[150:151], v[88:89], v[154:155] op_sel:[0,0,0] op_sel_hi:[1,0,1]
	v_pk_fma_f32 v[154:155], v[152:153], v[88:89], v[154:155] op_sel:[0,1,0] op_sel_hi:[1,1,1]
	v_pk_mul_f32 v[178:179], v[170:171], v[86:87] op_sel:[0,0] op_sel_hi:[1,0]
	v_pk_fma_f32 v[178:179], v[172:173], v[86:87], v[178:179] op_sel:[0,1,0] op_sel_hi:[1,1,1]
	v_pk_fma_f32 v[178:179], v[174:175], v[88:89], v[178:179] op_sel:[0,0,0] op_sel_hi:[1,0,1]
	v_pk_fma_f32 v[178:179], v[176:177], v[88:89], v[178:179] op_sel:[0,1,0] op_sel_hi:[1,1,1]
	v_pk_mul_f32 v[156:157], v[110:111], v[82:83] op_sel:[0,0] op_sel_hi:[1,0]
	v_add_f32_dpp v154, v154, v154 quad_perm:[1,0,3,2] row_mask:0xf bank_mask:0xf bound_ctrl:1
	v_add_f32_dpp v155, v155, v155 quad_perm:[1,0,3,2] row_mask:0xf bank_mask:0xf bound_ctrl:1
	v_add_f32_dpp v178, v178, v178 quad_perm:[1,0,3,2] row_mask:0xf bank_mask:0xf bound_ctrl:1
	v_add_f32_dpp v179, v179, v179 quad_perm:[1,0,3,2] row_mask:0xf bank_mask:0xf bound_ctrl:1
	v_add_f32_dpp v154, v154, v154 quad_perm:[2,3,0,1] row_mask:0xf bank_mask:0xf bound_ctrl:1
	v_add_f32_dpp v155, v155, v155 quad_perm:[2,3,0,1] row_mask:0xf bank_mask:0xf bound_ctrl:1
	v_add_f32_dpp v178, v178, v178 quad_perm:[2,3,0,1] row_mask:0xf bank_mask:0xf bound_ctrl:1
	v_add_f32_dpp v179, v179, v179 quad_perm:[2,3,0,1] row_mask:0xf bank_mask:0xf bound_ctrl:1
	v_add_f32_dpp v154, v154, v154 row_half_mirror row_mask:0xf bank_mask:0xf bound_ctrl:1
	v_add_f32_dpp v155, v155, v155 row_half_mirror row_mask:0xf bank_mask:0xf bound_ctrl:1
	v_add_f32_dpp v178, v178, v178 row_half_mirror row_mask:0xf bank_mask:0xf bound_ctrl:1
	v_add_f32_dpp v179, v179, v179 row_half_mirror row_mask:0xf bank_mask:0xf bound_ctrl:1
	v_add_f32_dpp v154, v154, v154 row_mirror row_mask:0xf bank_mask:0xf bound_ctrl:1
	v_add_f32_dpp v155, v155, v155 row_mirror row_mask:0xf bank_mask:0xf bound_ctrl:1
	v_add_f32_dpp v178, v178, v178 row_mirror row_mask:0xf bank_mask:0xf bound_ctrl:1
	v_add_f32_dpp v179, v179, v179 row_mirror row_mask:0xf bank_mask:0xf bound_ctrl:1
	v_pk_mul_f32 v[158:159], v[110:111], v[82:83] op_sel:[0,1] op_sel_hi:[1,1]
	v_pk_mul_f32 v[160:161], v[110:111], v[84:85] op_sel:[0,0] op_sel_hi:[1,0]
	v_pk_mul_f32 v[162:163], v[110:111], v[84:85] op_sel:[0,1] op_sel_hi:[1,1]
	v_pk_fma_f32 v[156:157], v[154:155], v[90:91], v[156:157] op_sel:[0,0,0] op_sel_hi:[1,0,1] neg_lo:[1,0,0] neg_hi:[1,0,0]
	v_pk_fma_f32 v[158:159], v[154:155], v[90:91], v[158:159] op_sel:[0,1,0] op_sel_hi:[1,1,1] neg_lo:[1,0,0] neg_hi:[1,0,0]
	v_pk_fma_f32 v[160:161], v[154:155], v[92:93], v[160:161] op_sel:[0,0,0] op_sel_hi:[1,0,1] neg_lo:[1,0,0] neg_hi:[1,0,0]
	v_pk_fma_f32 v[162:163], v[154:155], v[92:93], v[162:163] op_sel:[0,1,0] op_sel_hi:[1,1,1] neg_lo:[1,0,0] neg_hi:[1,0,0]
	v_pk_mul_f32 v[180:181], v[178:179], v[90:91] op_sel:[0,0] op_sel_hi:[1,0] neg_lo:[1,0] neg_hi:[1,0]
	v_pk_mul_f32 v[182:183], v[178:179], v[90:91] op_sel:[0,1] op_sel_hi:[1,1] neg_lo:[1,0] neg_hi:[1,0]
	v_pk_mul_f32 v[184:185], v[178:179], v[92:93] op_sel:[0,0] op_sel_hi:[1,0] neg_lo:[1,0] neg_hi:[1,0]
	v_pk_mul_f32 v[186:187], v[178:179], v[92:93] op_sel:[0,1] op_sel_hi:[1,1] neg_lo:[1,0] neg_hi:[1,0]
	v_pk_fma_f32 v[146:147], v[146:147], v[78:79], v[156:157] op_sel:[0,0,0] op_sel_hi:[1,0,1]
	v_pk_fma_f32 v[148:149], v[148:149], v[78:79], v[158:159] op_sel:[0,1,0] op_sel_hi:[1,1,1]
	v_pk_fma_f32 v[150:151], v[150:151], v[80:81], v[160:161] op_sel:[0,0,0] op_sel_hi:[1,0,1]
	v_pk_fma_f32 v[152:153], v[152:153], v[80:81], v[162:163] op_sel:[0,1,0] op_sel_hi:[1,1,1]
	v_pk_fma_f32 v[170:171], v[170:171], v[78:79], v[180:181] op_sel:[0,0,0] op_sel_hi:[1,0,1]
	v_pk_fma_f32 v[172:173], v[172:173], v[78:79], v[182:183] op_sel:[0,1,0] op_sel_hi:[1,1,1]
	v_pk_fma_f32 v[174:175], v[174:175], v[80:81], v[184:185] op_sel:[0,0,0] op_sel_hi:[1,0,1]
	v_pk_fma_f32 v[176:177], v[176:177], v[80:81], v[186:187] op_sel:[0,1,0] op_sel_hi:[1,1,1]
	ds_read_b128 v[78:81], v62 offset:29184
	ds_read_b128 v[82:85], v62 offset:29696
	ds_read_b128 v[86:89], v62 offset:30208
	ds_read_b128 v[90:93], v62 offset:30464
	v_add_u32_e32 v110, 0x7400, v63
	ds_read2_b32 v[110:111], v110 offset0:64 offset1:68
	s_waitcnt lgkmcnt(5)
	v_pk_mul_f32 v[154:155], v[146:147], v[102:103] op_sel:[0,0] op_sel_hi:[1,0]
	v_pk_fma_f32 v[154:155], v[148:149], v[102:103], v[154:155] op_sel:[0,1,0] op_sel_hi:[1,1,1]
	v_pk_fma_f32 v[154:155], v[150:151], v[104:105], v[154:155] op_sel:[0,0,0] op_sel_hi:[1,0,1]
	v_pk_fma_f32 v[154:155], v[152:153], v[104:105], v[154:155] op_sel:[0,1,0] op_sel_hi:[1,1,1]
	v_pk_mul_f32 v[178:179], v[170:171], v[102:103] op_sel:[0,0] op_sel_hi:[1,0]
	v_pk_fma_f32 v[178:179], v[172:173], v[102:103], v[178:179] op_sel:[0,1,0] op_sel_hi:[1,1,1]
	v_pk_fma_f32 v[178:179], v[174:175], v[104:105], v[178:179] op_sel:[0,0,0] op_sel_hi:[1,0,1]
	v_pk_fma_f32 v[178:179], v[176:177], v[104:105], v[178:179] op_sel:[0,1,0] op_sel_hi:[1,1,1]
	v_pk_mul_f32 v[156:157], v[22:23], v[98:99] op_sel:[0,0] op_sel_hi:[1,0]
	v_add_f32_dpp v154, v154, v154 quad_perm:[1,0,3,2] row_mask:0xf bank_mask:0xf bound_ctrl:1
	v_add_f32_dpp v155, v155, v155 quad_perm:[1,0,3,2] row_mask:0xf bank_mask:0xf bound_ctrl:1
	v_add_f32_dpp v178, v178, v178 quad_perm:[1,0,3,2] row_mask:0xf bank_mask:0xf bound_ctrl:1
	v_add_f32_dpp v179, v179, v179 quad_perm:[1,0,3,2] row_mask:0xf bank_mask:0xf bound_ctrl:1
	v_add_f32_dpp v154, v154, v154 quad_perm:[2,3,0,1] row_mask:0xf bank_mask:0xf bound_ctrl:1
	v_add_f32_dpp v155, v155, v155 quad_perm:[2,3,0,1] row_mask:0xf bank_mask:0xf bound_ctrl:1
	v_add_f32_dpp v178, v178, v178 quad_perm:[2,3,0,1] row_mask:0xf bank_mask:0xf bound_ctrl:1
	v_add_f32_dpp v179, v179, v179 quad_perm:[2,3,0,1] row_mask:0xf bank_mask:0xf bound_ctrl:1
	v_add_f32_dpp v154, v154, v154 row_half_mirror row_mask:0xf bank_mask:0xf bound_ctrl:1
	v_add_f32_dpp v155, v155, v155 row_half_mirror row_mask:0xf bank_mask:0xf bound_ctrl:1
	v_add_f32_dpp v178, v178, v178 row_half_mirror row_mask:0xf bank_mask:0xf bound_ctrl:1
	v_add_f32_dpp v179, v179, v179 row_half_mirror row_mask:0xf bank_mask:0xf bound_ctrl:1
	v_add_f32_dpp v154, v154, v154 row_mirror row_mask:0xf bank_mask:0xf bound_ctrl:1
	v_add_f32_dpp v155, v155, v155 row_mirror row_mask:0xf bank_mask:0xf bound_ctrl:1
	v_add_f32_dpp v178, v178, v178 row_mirror row_mask:0xf bank_mask:0xf bound_ctrl:1
	v_add_f32_dpp v179, v179, v179 row_mirror row_mask:0xf bank_mask:0xf bound_ctrl:1
	v_pk_mul_f32 v[158:159], v[22:23], v[98:99] op_sel:[0,1] op_sel_hi:[1,1]
	v_pk_mul_f32 v[160:161], v[22:23], v[100:101] op_sel:[0,0] op_sel_hi:[1,0]
	v_pk_mul_f32 v[162:163], v[22:23], v[100:101] op_sel:[0,1] op_sel_hi:[1,1]
	v_pk_fma_f32 v[156:157], v[154:155], v[106:107], v[156:157] op_sel:[0,0,0] op_sel_hi:[1,0,1] neg_lo:[1,0,0] neg_hi:[1,0,0]
	v_pk_fma_f32 v[158:159], v[154:155], v[106:107], v[158:159] op_sel:[0,1,0] op_sel_hi:[1,1,1] neg_lo:[1,0,0] neg_hi:[1,0,0]
	v_pk_fma_f32 v[160:161], v[154:155], v[108:109], v[160:161] op_sel:[0,0,0] op_sel_hi:[1,0,1] neg_lo:[1,0,0] neg_hi:[1,0,0]
	v_pk_fma_f32 v[162:163], v[154:155], v[108:109], v[162:163] op_sel:[0,1,0] op_sel_hi:[1,1,1] neg_lo:[1,0,0] neg_hi:[1,0,0]
	v_pk_mul_f32 v[180:181], v[178:179], v[106:107] op_sel:[0,0] op_sel_hi:[1,0] neg_lo:[1,0] neg_hi:[1,0]
	v_pk_mul_f32 v[182:183], v[178:179], v[106:107] op_sel:[0,1] op_sel_hi:[1,1] neg_lo:[1,0] neg_hi:[1,0]
	v_pk_mul_f32 v[184:185], v[178:179], v[108:109] op_sel:[0,0] op_sel_hi:[1,0] neg_lo:[1,0] neg_hi:[1,0]
	v_pk_mul_f32 v[186:187], v[178:179], v[108:109] op_sel:[0,1] op_sel_hi:[1,1] neg_lo:[1,0] neg_hi:[1,0]
	v_pk_fma_f32 v[146:147], v[146:147], v[94:95], v[156:157] op_sel:[0,0,0] op_sel_hi:[1,0,1]
	v_pk_fma_f32 v[148:149], v[148:149], v[94:95], v[158:159] op_sel:[0,1,0] op_sel_hi:[1,1,1]
	v_pk_fma_f32 v[150:151], v[150:151], v[96:97], v[160:161] op_sel:[0,0,0] op_sel_hi:[1,0,1]
	v_pk_fma_f32 v[152:153], v[152:153], v[96:97], v[162:163] op_sel:[0,1,0] op_sel_hi:[1,1,1]
	v_pk_fma_f32 v[170:171], v[170:171], v[94:95], v[180:181] op_sel:[0,0,0] op_sel_hi:[1,0,1]
	v_pk_fma_f32 v[172:173], v[172:173], v[94:95], v[182:183] op_sel:[0,1,0] op_sel_hi:[1,1,1]
	v_pk_fma_f32 v[174:175], v[174:175], v[96:97], v[184:185] op_sel:[0,0,0] op_sel_hi:[1,0,1]
	v_pk_fma_f32 v[176:177], v[176:177], v[96:97], v[186:187] op_sel:[0,1,0] op_sel_hi:[1,1,1]
	ds_read_b128 v[94:97], v62 offset:30720
	ds_read_b128 v[98:101], v62 offset:31232
	ds_read_b128 v[102:105], v62 offset:31744
	ds_read_b128 v[106:109], v62 offset:32000
	v_add_u32_e32 v22, 0x7800, v63
	ds_read2_b32 v[22:23], v22 offset0:192 offset1:196
	s_waitcnt lgkmcnt(5)
	v_pk_mul_f32 v[154:155], v[146:147], v[86:87] op_sel:[0,0] op_sel_hi:[1,0]
	v_pk_fma_f32 v[154:155], v[148:149], v[86:87], v[154:155] op_sel:[0,1,0] op_sel_hi:[1,1,1]
	v_pk_fma_f32 v[154:155], v[150:151], v[88:89], v[154:155] op_sel:[0,0,0] op_sel_hi:[1,0,1]
	v_pk_fma_f32 v[154:155], v[152:153], v[88:89], v[154:155] op_sel:[0,1,0] op_sel_hi:[1,1,1]
	v_pk_mul_f32 v[178:179], v[170:171], v[86:87] op_sel:[0,0] op_sel_hi:[1,0]
	v_pk_fma_f32 v[178:179], v[172:173], v[86:87], v[178:179] op_sel:[0,1,0] op_sel_hi:[1,1,1]
	v_pk_fma_f32 v[178:179], v[174:175], v[88:89], v[178:179] op_sel:[0,0,0] op_sel_hi:[1,0,1]
	v_pk_fma_f32 v[178:179], v[176:177], v[88:89], v[178:179] op_sel:[0,1,0] op_sel_hi:[1,1,1]
	v_pk_mul_f32 v[156:157], v[110:111], v[82:83] op_sel:[0,0] op_sel_hi:[1,0]
	v_add_f32_dpp v154, v154, v154 quad_perm:[1,0,3,2] row_mask:0xf bank_mask:0xf bound_ctrl:1
	v_add_f32_dpp v155, v155, v155 quad_perm:[1,0,3,2] row_mask:0xf bank_mask:0xf bound_ctrl:1
	v_add_f32_dpp v178, v178, v178 quad_perm:[1,0,3,2] row_mask:0xf bank_mask:0xf bound_ctrl:1
	v_add_f32_dpp v179, v179, v179 quad_perm:[1,0,3,2] row_mask:0xf bank_mask:0xf bound_ctrl:1
	v_add_f32_dpp v154, v154, v154 quad_perm:[2,3,0,1] row_mask:0xf bank_mask:0xf bound_ctrl:1
	v_add_f32_dpp v155, v155, v155 quad_perm:[2,3,0,1] row_mask:0xf bank_mask:0xf bound_ctrl:1
	v_add_f32_dpp v178, v178, v178 quad_perm:[2,3,0,1] row_mask:0xf bank_mask:0xf bound_ctrl:1
	v_add_f32_dpp v179, v179, v179 quad_perm:[2,3,0,1] row_mask:0xf bank_mask:0xf bound_ctrl:1
	v_add_f32_dpp v154, v154, v154 row_half_mirror row_mask:0xf bank_mask:0xf bound_ctrl:1
	v_add_f32_dpp v155, v155, v155 row_half_mirror row_mask:0xf bank_mask:0xf bound_ctrl:1
	v_add_f32_dpp v178, v178, v178 row_half_mirror row_mask:0xf bank_mask:0xf bound_ctrl:1
	v_add_f32_dpp v179, v179, v179 row_half_mirror row_mask:0xf bank_mask:0xf bound_ctrl:1
	v_add_f32_dpp v154, v154, v154 row_mirror row_mask:0xf bank_mask:0xf bound_ctrl:1
	v_add_f32_dpp v155, v155, v155 row_mirror row_mask:0xf bank_mask:0xf bound_ctrl:1
	v_add_f32_dpp v178, v178, v178 row_mirror row_mask:0xf bank_mask:0xf bound_ctrl:1
	v_add_f32_dpp v179, v179, v179 row_mirror row_mask:0xf bank_mask:0xf bound_ctrl:1
	v_pk_mul_f32 v[158:159], v[110:111], v[82:83] op_sel:[0,1] op_sel_hi:[1,1]
	v_pk_mul_f32 v[160:161], v[110:111], v[84:85] op_sel:[0,0] op_sel_hi:[1,0]
	v_pk_mul_f32 v[162:163], v[110:111], v[84:85] op_sel:[0,1] op_sel_hi:[1,1]
	v_pk_fma_f32 v[156:157], v[154:155], v[90:91], v[156:157] op_sel:[0,0,0] op_sel_hi:[1,0,1] neg_lo:[1,0,0] neg_hi:[1,0,0]
	v_pk_fma_f32 v[158:159], v[154:155], v[90:91], v[158:159] op_sel:[0,1,0] op_sel_hi:[1,1,1] neg_lo:[1,0,0] neg_hi:[1,0,0]
	v_pk_fma_f32 v[160:161], v[154:155], v[92:93], v[160:161] op_sel:[0,0,0] op_sel_hi:[1,0,1] neg_lo:[1,0,0] neg_hi:[1,0,0]
	v_pk_fma_f32 v[162:163], v[154:155], v[92:93], v[162:163] op_sel:[0,1,0] op_sel_hi:[1,1,1] neg_lo:[1,0,0] neg_hi:[1,0,0]
	v_pk_mul_f32 v[180:181], v[178:179], v[90:91] op_sel:[0,0] op_sel_hi:[1,0] neg_lo:[1,0] neg_hi:[1,0]
	v_pk_mul_f32 v[182:183], v[178:179], v[90:91] op_sel:[0,1] op_sel_hi:[1,1] neg_lo:[1,0] neg_hi:[1,0]
	v_pk_mul_f32 v[184:185], v[178:179], v[92:93] op_sel:[0,0] op_sel_hi:[1,0] neg_lo:[1,0] neg_hi:[1,0]
	v_pk_mul_f32 v[186:187], v[178:179], v[92:93] op_sel:[0,1] op_sel_hi:[1,1] neg_lo:[1,0] neg_hi:[1,0]
	v_pk_fma_f32 v[146:147], v[146:147], v[78:79], v[156:157] op_sel:[0,0,0] op_sel_hi:[1,0,1]
	v_pk_fma_f32 v[148:149], v[148:149], v[78:79], v[158:159] op_sel:[0,1,0] op_sel_hi:[1,1,1]
	v_pk_fma_f32 v[150:151], v[150:151], v[80:81], v[160:161] op_sel:[0,0,0] op_sel_hi:[1,0,1]
	v_pk_fma_f32 v[152:153], v[152:153], v[80:81], v[162:163] op_sel:[0,1,0] op_sel_hi:[1,1,1]
	v_pk_fma_f32 v[170:171], v[170:171], v[78:79], v[180:181] op_sel:[0,0,0] op_sel_hi:[1,0,1]
	v_pk_fma_f32 v[172:173], v[172:173], v[78:79], v[182:183] op_sel:[0,1,0] op_sel_hi:[1,1,1]
	v_pk_fma_f32 v[174:175], v[174:175], v[80:81], v[184:185] op_sel:[0,0,0] op_sel_hi:[1,0,1]
	v_pk_fma_f32 v[176:177], v[176:177], v[80:81], v[186:187] op_sel:[0,1,0] op_sel_hi:[1,1,1]
	ds_read_b128 v[78:81], v62 offset:32768
	ds_read_b128 v[82:85], v62 offset:33280
	ds_read_b128 v[86:89], v62 offset:32256
	ds_read_b128 v[90:93], v62 offset:33536
	v_add_u32_e32 v110, 0x8000, v63
	ds_read2_b32 v[110:111], v110 offset0:64 offset1:68
	s_waitcnt lgkmcnt(5)
	v_pk_mul_f32 v[154:155], v[146:147], v[102:103] op_sel:[0,0] op_sel_hi:[1,0]
	v_pk_fma_f32 v[154:155], v[148:149], v[102:103], v[154:155] op_sel:[0,1,0] op_sel_hi:[1,1,1]
	v_pk_fma_f32 v[154:155], v[150:151], v[104:105], v[154:155] op_sel:[0,0,0] op_sel_hi:[1,0,1]
	v_pk_fma_f32 v[154:155], v[152:153], v[104:105], v[154:155] op_sel:[0,1,0] op_sel_hi:[1,1,1]
	v_pk_mul_f32 v[178:179], v[170:171], v[102:103] op_sel:[0,0] op_sel_hi:[1,0]
	v_pk_fma_f32 v[178:179], v[172:173], v[102:103], v[178:179] op_sel:[0,1,0] op_sel_hi:[1,1,1]
	v_pk_fma_f32 v[178:179], v[174:175], v[104:105], v[178:179] op_sel:[0,0,0] op_sel_hi:[1,0,1]
	v_pk_fma_f32 v[178:179], v[176:177], v[104:105], v[178:179] op_sel:[0,1,0] op_sel_hi:[1,1,1]
	v_pk_mul_f32 v[156:157], v[22:23], v[98:99] op_sel:[0,0] op_sel_hi:[1,0]
	v_add_f32_dpp v154, v154, v154 quad_perm:[1,0,3,2] row_mask:0xf bank_mask:0xf bound_ctrl:1
	v_add_f32_dpp v155, v155, v155 quad_perm:[1,0,3,2] row_mask:0xf bank_mask:0xf bound_ctrl:1
	v_add_f32_dpp v178, v178, v178 quad_perm:[1,0,3,2] row_mask:0xf bank_mask:0xf bound_ctrl:1
	v_add_f32_dpp v179, v179, v179 quad_perm:[1,0,3,2] row_mask:0xf bank_mask:0xf bound_ctrl:1
	v_add_f32_dpp v154, v154, v154 quad_perm:[2,3,0,1] row_mask:0xf bank_mask:0xf bound_ctrl:1
	v_add_f32_dpp v155, v155, v155 quad_perm:[2,3,0,1] row_mask:0xf bank_mask:0xf bound_ctrl:1
	v_add_f32_dpp v178, v178, v178 quad_perm:[2,3,0,1] row_mask:0xf bank_mask:0xf bound_ctrl:1
	v_add_f32_dpp v179, v179, v179 quad_perm:[2,3,0,1] row_mask:0xf bank_mask:0xf bound_ctrl:1
	v_add_f32_dpp v154, v154, v154 row_half_mirror row_mask:0xf bank_mask:0xf bound_ctrl:1
	v_add_f32_dpp v155, v155, v155 row_half_mirror row_mask:0xf bank_mask:0xf bound_ctrl:1
	v_add_f32_dpp v178, v178, v178 row_half_mirror row_mask:0xf bank_mask:0xf bound_ctrl:1
	v_add_f32_dpp v179, v179, v179 row_half_mirror row_mask:0xf bank_mask:0xf bound_ctrl:1
	v_add_f32_dpp v154, v154, v154 row_mirror row_mask:0xf bank_mask:0xf bound_ctrl:1
	v_add_f32_dpp v155, v155, v155 row_mirror row_mask:0xf bank_mask:0xf bound_ctrl:1
	v_add_f32_dpp v178, v178, v178 row_mirror row_mask:0xf bank_mask:0xf bound_ctrl:1
	v_add_f32_dpp v179, v179, v179 row_mirror row_mask:0xf bank_mask:0xf bound_ctrl:1
	v_pk_mul_f32 v[158:159], v[22:23], v[98:99] op_sel:[0,1] op_sel_hi:[1,1]
	v_pk_mul_f32 v[160:161], v[22:23], v[100:101] op_sel:[0,0] op_sel_hi:[1,0]
	v_pk_mul_f32 v[162:163], v[22:23], v[100:101] op_sel:[0,1] op_sel_hi:[1,1]
	v_pk_fma_f32 v[156:157], v[154:155], v[106:107], v[156:157] op_sel:[0,0,0] op_sel_hi:[1,0,1] neg_lo:[1,0,0] neg_hi:[1,0,0]
	v_pk_fma_f32 v[158:159], v[154:155], v[106:107], v[158:159] op_sel:[0,1,0] op_sel_hi:[1,1,1] neg_lo:[1,0,0] neg_hi:[1,0,0]
	v_pk_fma_f32 v[160:161], v[154:155], v[108:109], v[160:161] op_sel:[0,0,0] op_sel_hi:[1,0,1] neg_lo:[1,0,0] neg_hi:[1,0,0]
	v_pk_fma_f32 v[162:163], v[154:155], v[108:109], v[162:163] op_sel:[0,1,0] op_sel_hi:[1,1,1] neg_lo:[1,0,0] neg_hi:[1,0,0]
	v_pk_mul_f32 v[180:181], v[178:179], v[106:107] op_sel:[0,0] op_sel_hi:[1,0] neg_lo:[1,0] neg_hi:[1,0]
	v_pk_mul_f32 v[182:183], v[178:179], v[106:107] op_sel:[0,1] op_sel_hi:[1,1] neg_lo:[1,0] neg_hi:[1,0]
	v_pk_mul_f32 v[184:185], v[178:179], v[108:109] op_sel:[0,0] op_sel_hi:[1,0] neg_lo:[1,0] neg_hi:[1,0]
	v_pk_mul_f32 v[186:187], v[178:179], v[108:109] op_sel:[0,1] op_sel_hi:[1,1] neg_lo:[1,0] neg_hi:[1,0]
	v_pk_fma_f32 v[146:147], v[146:147], v[94:95], v[156:157] op_sel:[0,0,0] op_sel_hi:[1,0,1]
	v_pk_fma_f32 v[148:149], v[148:149], v[94:95], v[158:159] op_sel:[0,1,0] op_sel_hi:[1,1,1]
	v_pk_fma_f32 v[150:151], v[150:151], v[96:97], v[160:161] op_sel:[0,0,0] op_sel_hi:[1,0,1]
	v_pk_fma_f32 v[152:153], v[152:153], v[96:97], v[162:163] op_sel:[0,1,0] op_sel_hi:[1,1,1]
	v_pk_fma_f32 v[170:171], v[170:171], v[94:95], v[180:181] op_sel:[0,0,0] op_sel_hi:[1,0,1]
	v_pk_fma_f32 v[172:173], v[172:173], v[94:95], v[182:183] op_sel:[0,1,0] op_sel_hi:[1,1,1]
	v_pk_fma_f32 v[174:175], v[174:175], v[96:97], v[184:185] op_sel:[0,0,0] op_sel_hi:[1,0,1]
	v_pk_fma_f32 v[176:177], v[176:177], v[96:97], v[186:187] op_sel:[0,1,0] op_sel_hi:[1,1,1]
	ds_read_b128 v[94:97], v62 offset:33792
	ds_read_b128 v[98:101], v62 offset:34304
	ds_read_b128 v[102:105], v62 offset:34816
	ds_read_b128 v[106:109], v62 offset:35072
	v_add_u32_e32 v22, 0x8400, v63
	ds_read2_b32 v[22:23], v22 offset0:192 offset1:196
	s_waitcnt lgkmcnt(5)
	v_pk_mul_f32 v[154:155], v[146:147], v[82:83] op_sel:[0,0] op_sel_hi:[1,0]
	v_pk_fma_f32 v[154:155], v[148:149], v[82:83], v[154:155] op_sel:[0,1,0] op_sel_hi:[1,1,1]
	v_pk_fma_f32 v[154:155], v[150:151], v[84:85], v[154:155] op_sel:[0,0,0] op_sel_hi:[1,0,1]
	v_pk_fma_f32 v[154:155], v[152:153], v[84:85], v[154:155] op_sel:[0,1,0] op_sel_hi:[1,1,1]
	v_pk_mul_f32 v[178:179], v[170:171], v[82:83] op_sel:[0,0] op_sel_hi:[1,0]
	v_pk_fma_f32 v[178:179], v[172:173], v[82:83], v[178:179] op_sel:[0,1,0] op_sel_hi:[1,1,1]
	v_pk_fma_f32 v[178:179], v[174:175], v[84:85], v[178:179] op_sel:[0,0,0] op_sel_hi:[1,0,1]
	v_pk_fma_f32 v[178:179], v[176:177], v[84:85], v[178:179] op_sel:[0,1,0] op_sel_hi:[1,1,1]
	v_pk_mul_f32 v[156:157], v[110:111], v[78:79] op_sel:[0,0] op_sel_hi:[1,0]
	v_add_f32_dpp v154, v154, v154 quad_perm:[1,0,3,2] row_mask:0xf bank_mask:0xf bound_ctrl:1
	v_add_f32_dpp v155, v155, v155 quad_perm:[1,0,3,2] row_mask:0xf bank_mask:0xf bound_ctrl:1
	v_add_f32_dpp v178, v178, v178 quad_perm:[1,0,3,2] row_mask:0xf bank_mask:0xf bound_ctrl:1
	v_add_f32_dpp v179, v179, v179 quad_perm:[1,0,3,2] row_mask:0xf bank_mask:0xf bound_ctrl:1
	v_add_f32_dpp v154, v154, v154 quad_perm:[2,3,0,1] row_mask:0xf bank_mask:0xf bound_ctrl:1
	v_add_f32_dpp v155, v155, v155 quad_perm:[2,3,0,1] row_mask:0xf bank_mask:0xf bound_ctrl:1
	v_add_f32_dpp v178, v178, v178 quad_perm:[2,3,0,1] row_mask:0xf bank_mask:0xf bound_ctrl:1
	v_add_f32_dpp v179, v179, v179 quad_perm:[2,3,0,1] row_mask:0xf bank_mask:0xf bound_ctrl:1
	v_add_f32_dpp v154, v154, v154 row_half_mirror row_mask:0xf bank_mask:0xf bound_ctrl:1
	v_add_f32_dpp v155, v155, v155 row_half_mirror row_mask:0xf bank_mask:0xf bound_ctrl:1
	v_add_f32_dpp v178, v178, v178 row_half_mirror row_mask:0xf bank_mask:0xf bound_ctrl:1
	v_add_f32_dpp v179, v179, v179 row_half_mirror row_mask:0xf bank_mask:0xf bound_ctrl:1
	v_add_f32_dpp v154, v154, v154 row_mirror row_mask:0xf bank_mask:0xf bound_ctrl:1
	v_add_f32_dpp v155, v155, v155 row_mirror row_mask:0xf bank_mask:0xf bound_ctrl:1
	v_add_f32_dpp v178, v178, v178 row_mirror row_mask:0xf bank_mask:0xf bound_ctrl:1
	v_add_f32_dpp v179, v179, v179 row_mirror row_mask:0xf bank_mask:0xf bound_ctrl:1
	v_pk_mul_f32 v[158:159], v[110:111], v[78:79] op_sel:[0,1] op_sel_hi:[1,1]
	v_pk_mul_f32 v[160:161], v[110:111], v[80:81] op_sel:[0,0] op_sel_hi:[1,0]
	v_pk_mul_f32 v[162:163], v[110:111], v[80:81] op_sel:[0,1] op_sel_hi:[1,1]
	v_pk_fma_f32 v[156:157], v[154:155], v[90:91], v[156:157] op_sel:[0,0,0] op_sel_hi:[1,0,1] neg_lo:[1,0,0] neg_hi:[1,0,0]
	v_pk_fma_f32 v[158:159], v[154:155], v[90:91], v[158:159] op_sel:[0,1,0] op_sel_hi:[1,1,1] neg_lo:[1,0,0] neg_hi:[1,0,0]
	v_pk_fma_f32 v[160:161], v[154:155], v[92:93], v[160:161] op_sel:[0,0,0] op_sel_hi:[1,0,1] neg_lo:[1,0,0] neg_hi:[1,0,0]
	v_pk_fma_f32 v[162:163], v[154:155], v[92:93], v[162:163] op_sel:[0,1,0] op_sel_hi:[1,1,1] neg_lo:[1,0,0] neg_hi:[1,0,0]
	v_pk_mul_f32 v[180:181], v[178:179], v[90:91] op_sel:[0,0] op_sel_hi:[1,0] neg_lo:[1,0] neg_hi:[1,0]
	v_pk_mul_f32 v[182:183], v[178:179], v[90:91] op_sel:[0,1] op_sel_hi:[1,1] neg_lo:[1,0] neg_hi:[1,0]
	v_pk_mul_f32 v[184:185], v[178:179], v[92:93] op_sel:[0,0] op_sel_hi:[1,0] neg_lo:[1,0] neg_hi:[1,0]
	v_pk_mul_f32 v[186:187], v[178:179], v[92:93] op_sel:[0,1] op_sel_hi:[1,1] neg_lo:[1,0] neg_hi:[1,0]
	v_pk_fma_f32 v[146:147], v[146:147], v[86:87], v[156:157] op_sel:[0,0,0] op_sel_hi:[1,0,1]
	v_pk_fma_f32 v[148:149], v[148:149], v[86:87], v[158:159] op_sel:[0,1,0] op_sel_hi:[1,1,1]
	v_pk_fma_f32 v[150:151], v[150:151], v[88:89], v[160:161] op_sel:[0,0,0] op_sel_hi:[1,0,1]
	v_pk_fma_f32 v[152:153], v[152:153], v[88:89], v[162:163] op_sel:[0,1,0] op_sel_hi:[1,1,1]
	v_pk_fma_f32 v[170:171], v[170:171], v[86:87], v[180:181] op_sel:[0,0,0] op_sel_hi:[1,0,1]
	v_pk_fma_f32 v[172:173], v[172:173], v[86:87], v[182:183] op_sel:[0,1,0] op_sel_hi:[1,1,1]
	v_pk_fma_f32 v[174:175], v[174:175], v[88:89], v[184:185] op_sel:[0,0,0] op_sel_hi:[1,0,1]
	v_pk_fma_f32 v[176:177], v[176:177], v[88:89], v[186:187] op_sel:[0,1,0] op_sel_hi:[1,1,1]
	ds_read_b128 v[78:81], v62 offset:35328
	ds_read_b128 v[82:85], v62 offset:35840
	ds_read_b128 v[86:89], v62 offset:36352
	ds_read_b128 v[90:93], v62 offset:36608
	v_add_u32_e32 v110, 0x8c00, v63
	ds_read2_b32 v[110:111], v110 offset0:64 offset1:68
	s_waitcnt lgkmcnt(5)
	v_pk_mul_f32 v[154:155], v[146:147], v[102:103] op_sel:[0,0] op_sel_hi:[1,0]
	v_pk_fma_f32 v[154:155], v[148:149], v[102:103], v[154:155] op_sel:[0,1,0] op_sel_hi:[1,1,1]
	v_pk_fma_f32 v[154:155], v[150:151], v[104:105], v[154:155] op_sel:[0,0,0] op_sel_hi:[1,0,1]
	v_pk_fma_f32 v[154:155], v[152:153], v[104:105], v[154:155] op_sel:[0,1,0] op_sel_hi:[1,1,1]
	v_pk_mul_f32 v[178:179], v[170:171], v[102:103] op_sel:[0,0] op_sel_hi:[1,0]
	v_pk_fma_f32 v[178:179], v[172:173], v[102:103], v[178:179] op_sel:[0,1,0] op_sel_hi:[1,1,1]
	v_pk_fma_f32 v[178:179], v[174:175], v[104:105], v[178:179] op_sel:[0,0,0] op_sel_hi:[1,0,1]
	v_pk_fma_f32 v[178:179], v[176:177], v[104:105], v[178:179] op_sel:[0,1,0] op_sel_hi:[1,1,1]
	v_pk_mul_f32 v[156:157], v[22:23], v[98:99] op_sel:[0,0] op_sel_hi:[1,0]
	v_add_f32_dpp v154, v154, v154 quad_perm:[1,0,3,2] row_mask:0xf bank_mask:0xf bound_ctrl:1
	v_add_f32_dpp v155, v155, v155 quad_perm:[1,0,3,2] row_mask:0xf bank_mask:0xf bound_ctrl:1
	v_add_f32_dpp v178, v178, v178 quad_perm:[1,0,3,2] row_mask:0xf bank_mask:0xf bound_ctrl:1
	v_add_f32_dpp v179, v179, v179 quad_perm:[1,0,3,2] row_mask:0xf bank_mask:0xf bound_ctrl:1
	v_add_f32_dpp v154, v154, v154 quad_perm:[2,3,0,1] row_mask:0xf bank_mask:0xf bound_ctrl:1
	v_add_f32_dpp v155, v155, v155 quad_perm:[2,3,0,1] row_mask:0xf bank_mask:0xf bound_ctrl:1
	v_add_f32_dpp v178, v178, v178 quad_perm:[2,3,0,1] row_mask:0xf bank_mask:0xf bound_ctrl:1
	v_add_f32_dpp v179, v179, v179 quad_perm:[2,3,0,1] row_mask:0xf bank_mask:0xf bound_ctrl:1
	v_add_f32_dpp v154, v154, v154 row_half_mirror row_mask:0xf bank_mask:0xf bound_ctrl:1
	v_add_f32_dpp v155, v155, v155 row_half_mirror row_mask:0xf bank_mask:0xf bound_ctrl:1
	v_add_f32_dpp v178, v178, v178 row_half_mirror row_mask:0xf bank_mask:0xf bound_ctrl:1
	v_add_f32_dpp v179, v179, v179 row_half_mirror row_mask:0xf bank_mask:0xf bound_ctrl:1
	v_add_f32_dpp v154, v154, v154 row_mirror row_mask:0xf bank_mask:0xf bound_ctrl:1
	v_add_f32_dpp v155, v155, v155 row_mirror row_mask:0xf bank_mask:0xf bound_ctrl:1
	v_add_f32_dpp v178, v178, v178 row_mirror row_mask:0xf bank_mask:0xf bound_ctrl:1
	v_add_f32_dpp v179, v179, v179 row_mirror row_mask:0xf bank_mask:0xf bound_ctrl:1
	v_pk_mul_f32 v[158:159], v[22:23], v[98:99] op_sel:[0,1] op_sel_hi:[1,1]
	v_pk_mul_f32 v[160:161], v[22:23], v[100:101] op_sel:[0,0] op_sel_hi:[1,0]
	v_pk_mul_f32 v[162:163], v[22:23], v[100:101] op_sel:[0,1] op_sel_hi:[1,1]
	v_pk_fma_f32 v[156:157], v[154:155], v[106:107], v[156:157] op_sel:[0,0,0] op_sel_hi:[1,0,1] neg_lo:[1,0,0] neg_hi:[1,0,0]
	v_pk_fma_f32 v[158:159], v[154:155], v[106:107], v[158:159] op_sel:[0,1,0] op_sel_hi:[1,1,1] neg_lo:[1,0,0] neg_hi:[1,0,0]
	v_pk_fma_f32 v[160:161], v[154:155], v[108:109], v[160:161] op_sel:[0,0,0] op_sel_hi:[1,0,1] neg_lo:[1,0,0] neg_hi:[1,0,0]
	v_pk_fma_f32 v[162:163], v[154:155], v[108:109], v[162:163] op_sel:[0,1,0] op_sel_hi:[1,1,1] neg_lo:[1,0,0] neg_hi:[1,0,0]
	v_pk_mul_f32 v[180:181], v[178:179], v[106:107] op_sel:[0,0] op_sel_hi:[1,0] neg_lo:[1,0] neg_hi:[1,0]
	v_pk_mul_f32 v[182:183], v[178:179], v[106:107] op_sel:[0,1] op_sel_hi:[1,1] neg_lo:[1,0] neg_hi:[1,0]
	v_pk_mul_f32 v[184:185], v[178:179], v[108:109] op_sel:[0,0] op_sel_hi:[1,0] neg_lo:[1,0] neg_hi:[1,0]
	v_pk_mul_f32 v[186:187], v[178:179], v[108:109] op_sel:[0,1] op_sel_hi:[1,1] neg_lo:[1,0] neg_hi:[1,0]
	v_pk_fma_f32 v[146:147], v[146:147], v[94:95], v[156:157] op_sel:[0,0,0] op_sel_hi:[1,0,1]
	v_pk_fma_f32 v[148:149], v[148:149], v[94:95], v[158:159] op_sel:[0,1,0] op_sel_hi:[1,1,1]
	v_pk_fma_f32 v[150:151], v[150:151], v[96:97], v[160:161] op_sel:[0,0,0] op_sel_hi:[1,0,1]
	v_pk_fma_f32 v[152:153], v[152:153], v[96:97], v[162:163] op_sel:[0,1,0] op_sel_hi:[1,1,1]
	v_pk_fma_f32 v[170:171], v[170:171], v[94:95], v[180:181] op_sel:[0,0,0] op_sel_hi:[1,0,1]
	v_pk_fma_f32 v[172:173], v[172:173], v[94:95], v[182:183] op_sel:[0,1,0] op_sel_hi:[1,1,1]
	v_pk_fma_f32 v[174:175], v[174:175], v[96:97], v[184:185] op_sel:[0,0,0] op_sel_hi:[1,0,1]
	v_pk_fma_f32 v[176:177], v[176:177], v[96:97], v[186:187] op_sel:[0,1,0] op_sel_hi:[1,1,1]
	ds_read_b128 v[94:97], v62 offset:36864
	ds_read_b128 v[98:101], v62 offset:37376
	ds_read_b128 v[102:105], v62 offset:37888
	ds_read_b128 v[106:109], v62 offset:38144
	v_add_u32_e32 v22, 0x9000, v63
	ds_read2_b32 v[22:23], v22 offset0:192 offset1:196
	s_waitcnt lgkmcnt(5)
	v_pk_mul_f32 v[154:155], v[146:147], v[86:87] op_sel:[0,0] op_sel_hi:[1,0]
	v_pk_fma_f32 v[154:155], v[148:149], v[86:87], v[154:155] op_sel:[0,1,0] op_sel_hi:[1,1,1]
	v_pk_fma_f32 v[154:155], v[150:151], v[88:89], v[154:155] op_sel:[0,0,0] op_sel_hi:[1,0,1]
	v_pk_fma_f32 v[154:155], v[152:153], v[88:89], v[154:155] op_sel:[0,1,0] op_sel_hi:[1,1,1]
	v_pk_mul_f32 v[178:179], v[170:171], v[86:87] op_sel:[0,0] op_sel_hi:[1,0]
	v_pk_fma_f32 v[178:179], v[172:173], v[86:87], v[178:179] op_sel:[0,1,0] op_sel_hi:[1,1,1]
	v_pk_fma_f32 v[178:179], v[174:175], v[88:89], v[178:179] op_sel:[0,0,0] op_sel_hi:[1,0,1]
	v_pk_fma_f32 v[178:179], v[176:177], v[88:89], v[178:179] op_sel:[0,1,0] op_sel_hi:[1,1,1]
	v_pk_mul_f32 v[156:157], v[110:111], v[82:83] op_sel:[0,0] op_sel_hi:[1,0]
	v_add_f32_dpp v154, v154, v154 quad_perm:[1,0,3,2] row_mask:0xf bank_mask:0xf bound_ctrl:1
	v_add_f32_dpp v155, v155, v155 quad_perm:[1,0,3,2] row_mask:0xf bank_mask:0xf bound_ctrl:1
	v_add_f32_dpp v178, v178, v178 quad_perm:[1,0,3,2] row_mask:0xf bank_mask:0xf bound_ctrl:1
	v_add_f32_dpp v179, v179, v179 quad_perm:[1,0,3,2] row_mask:0xf bank_mask:0xf bound_ctrl:1
	v_add_f32_dpp v154, v154, v154 quad_perm:[2,3,0,1] row_mask:0xf bank_mask:0xf bound_ctrl:1
	v_add_f32_dpp v155, v155, v155 quad_perm:[2,3,0,1] row_mask:0xf bank_mask:0xf bound_ctrl:1
	v_add_f32_dpp v178, v178, v178 quad_perm:[2,3,0,1] row_mask:0xf bank_mask:0xf bound_ctrl:1
	v_add_f32_dpp v179, v179, v179 quad_perm:[2,3,0,1] row_mask:0xf bank_mask:0xf bound_ctrl:1
	v_add_f32_dpp v154, v154, v154 row_half_mirror row_mask:0xf bank_mask:0xf bound_ctrl:1
	v_add_f32_dpp v155, v155, v155 row_half_mirror row_mask:0xf bank_mask:0xf bound_ctrl:1
	v_add_f32_dpp v178, v178, v178 row_half_mirror row_mask:0xf bank_mask:0xf bound_ctrl:1
	v_add_f32_dpp v179, v179, v179 row_half_mirror row_mask:0xf bank_mask:0xf bound_ctrl:1
	v_add_f32_dpp v154, v154, v154 row_mirror row_mask:0xf bank_mask:0xf bound_ctrl:1
	v_add_f32_dpp v155, v155, v155 row_mirror row_mask:0xf bank_mask:0xf bound_ctrl:1
	v_add_f32_dpp v178, v178, v178 row_mirror row_mask:0xf bank_mask:0xf bound_ctrl:1
	v_add_f32_dpp v179, v179, v179 row_mirror row_mask:0xf bank_mask:0xf bound_ctrl:1
	v_pk_mul_f32 v[158:159], v[110:111], v[82:83] op_sel:[0,1] op_sel_hi:[1,1]
	v_pk_mul_f32 v[160:161], v[110:111], v[84:85] op_sel:[0,0] op_sel_hi:[1,0]
	v_pk_mul_f32 v[162:163], v[110:111], v[84:85] op_sel:[0,1] op_sel_hi:[1,1]
	v_pk_fma_f32 v[156:157], v[154:155], v[90:91], v[156:157] op_sel:[0,0,0] op_sel_hi:[1,0,1] neg_lo:[1,0,0] neg_hi:[1,0,0]
	v_pk_fma_f32 v[158:159], v[154:155], v[90:91], v[158:159] op_sel:[0,1,0] op_sel_hi:[1,1,1] neg_lo:[1,0,0] neg_hi:[1,0,0]
	v_pk_fma_f32 v[160:161], v[154:155], v[92:93], v[160:161] op_sel:[0,0,0] op_sel_hi:[1,0,1] neg_lo:[1,0,0] neg_hi:[1,0,0]
	v_pk_fma_f32 v[162:163], v[154:155], v[92:93], v[162:163] op_sel:[0,1,0] op_sel_hi:[1,1,1] neg_lo:[1,0,0] neg_hi:[1,0,0]
	v_pk_mul_f32 v[180:181], v[178:179], v[90:91] op_sel:[0,0] op_sel_hi:[1,0] neg_lo:[1,0] neg_hi:[1,0]
	v_pk_mul_f32 v[182:183], v[178:179], v[90:91] op_sel:[0,1] op_sel_hi:[1,1] neg_lo:[1,0] neg_hi:[1,0]
	v_pk_mul_f32 v[184:185], v[178:179], v[92:93] op_sel:[0,0] op_sel_hi:[1,0] neg_lo:[1,0] neg_hi:[1,0]
	v_pk_mul_f32 v[186:187], v[178:179], v[92:93] op_sel:[0,1] op_sel_hi:[1,1] neg_lo:[1,0] neg_hi:[1,0]
	v_pk_fma_f32 v[146:147], v[146:147], v[78:79], v[156:157] op_sel:[0,0,0] op_sel_hi:[1,0,1]
	v_pk_fma_f32 v[148:149], v[148:149], v[78:79], v[158:159] op_sel:[0,1,0] op_sel_hi:[1,1,1]
	v_pk_fma_f32 v[150:151], v[150:151], v[80:81], v[160:161] op_sel:[0,0,0] op_sel_hi:[1,0,1]
	v_pk_fma_f32 v[152:153], v[152:153], v[80:81], v[162:163] op_sel:[0,1,0] op_sel_hi:[1,1,1]
	v_pk_fma_f32 v[170:171], v[170:171], v[78:79], v[180:181] op_sel:[0,0,0] op_sel_hi:[1,0,1]
	v_pk_fma_f32 v[172:173], v[172:173], v[78:79], v[182:183] op_sel:[0,1,0] op_sel_hi:[1,1,1]
	v_pk_fma_f32 v[174:175], v[174:175], v[80:81], v[184:185] op_sel:[0,0,0] op_sel_hi:[1,0,1]
	v_pk_fma_f32 v[176:177], v[176:177], v[80:81], v[186:187] op_sel:[0,1,0] op_sel_hi:[1,1,1]
	ds_read_b128 v[78:81], v62 offset:38400
	ds_read_b128 v[82:85], v62 offset:38912
	ds_read_b128 v[86:89], v62 offset:39424
	ds_read_b128 v[90:93], v62 offset:39680
	v_add_u32_e32 v110, 0x9800, v63
	ds_read2_b32 v[110:111], v110 offset0:64 offset1:68
	s_waitcnt lgkmcnt(5)
	v_pk_mul_f32 v[154:155], v[146:147], v[102:103] op_sel:[0,0] op_sel_hi:[1,0]
	v_pk_fma_f32 v[154:155], v[148:149], v[102:103], v[154:155] op_sel:[0,1,0] op_sel_hi:[1,1,1]
	v_pk_fma_f32 v[154:155], v[150:151], v[104:105], v[154:155] op_sel:[0,0,0] op_sel_hi:[1,0,1]
	v_pk_fma_f32 v[154:155], v[152:153], v[104:105], v[154:155] op_sel:[0,1,0] op_sel_hi:[1,1,1]
	v_pk_mul_f32 v[178:179], v[170:171], v[102:103] op_sel:[0,0] op_sel_hi:[1,0]
	v_pk_fma_f32 v[178:179], v[172:173], v[102:103], v[178:179] op_sel:[0,1,0] op_sel_hi:[1,1,1]
	v_pk_fma_f32 v[178:179], v[174:175], v[104:105], v[178:179] op_sel:[0,0,0] op_sel_hi:[1,0,1]
	v_pk_fma_f32 v[178:179], v[176:177], v[104:105], v[178:179] op_sel:[0,1,0] op_sel_hi:[1,1,1]
	v_pk_mul_f32 v[156:157], v[22:23], v[98:99] op_sel:[0,0] op_sel_hi:[1,0]
	v_add_f32_dpp v154, v154, v154 quad_perm:[1,0,3,2] row_mask:0xf bank_mask:0xf bound_ctrl:1
	v_add_f32_dpp v155, v155, v155 quad_perm:[1,0,3,2] row_mask:0xf bank_mask:0xf bound_ctrl:1
	v_add_f32_dpp v178, v178, v178 quad_perm:[1,0,3,2] row_mask:0xf bank_mask:0xf bound_ctrl:1
	v_add_f32_dpp v179, v179, v179 quad_perm:[1,0,3,2] row_mask:0xf bank_mask:0xf bound_ctrl:1
	v_add_f32_dpp v154, v154, v154 quad_perm:[2,3,0,1] row_mask:0xf bank_mask:0xf bound_ctrl:1
	v_add_f32_dpp v155, v155, v155 quad_perm:[2,3,0,1] row_mask:0xf bank_mask:0xf bound_ctrl:1
	v_add_f32_dpp v178, v178, v178 quad_perm:[2,3,0,1] row_mask:0xf bank_mask:0xf bound_ctrl:1
	v_add_f32_dpp v179, v179, v179 quad_perm:[2,3,0,1] row_mask:0xf bank_mask:0xf bound_ctrl:1
	v_add_f32_dpp v154, v154, v154 row_half_mirror row_mask:0xf bank_mask:0xf bound_ctrl:1
	v_add_f32_dpp v155, v155, v155 row_half_mirror row_mask:0xf bank_mask:0xf bound_ctrl:1
	v_add_f32_dpp v178, v178, v178 row_half_mirror row_mask:0xf bank_mask:0xf bound_ctrl:1
	v_add_f32_dpp v179, v179, v179 row_half_mirror row_mask:0xf bank_mask:0xf bound_ctrl:1
	v_add_f32_dpp v154, v154, v154 row_mirror row_mask:0xf bank_mask:0xf bound_ctrl:1
	v_add_f32_dpp v155, v155, v155 row_mirror row_mask:0xf bank_mask:0xf bound_ctrl:1
	v_add_f32_dpp v178, v178, v178 row_mirror row_mask:0xf bank_mask:0xf bound_ctrl:1
	v_add_f32_dpp v179, v179, v179 row_mirror row_mask:0xf bank_mask:0xf bound_ctrl:1
	v_pk_mul_f32 v[158:159], v[22:23], v[98:99] op_sel:[0,1] op_sel_hi:[1,1]
	v_pk_mul_f32 v[160:161], v[22:23], v[100:101] op_sel:[0,0] op_sel_hi:[1,0]
	v_pk_mul_f32 v[162:163], v[22:23], v[100:101] op_sel:[0,1] op_sel_hi:[1,1]
	v_pk_fma_f32 v[156:157], v[154:155], v[106:107], v[156:157] op_sel:[0,0,0] op_sel_hi:[1,0,1] neg_lo:[1,0,0] neg_hi:[1,0,0]
	v_pk_fma_f32 v[158:159], v[154:155], v[106:107], v[158:159] op_sel:[0,1,0] op_sel_hi:[1,1,1] neg_lo:[1,0,0] neg_hi:[1,0,0]
	v_pk_fma_f32 v[160:161], v[154:155], v[108:109], v[160:161] op_sel:[0,0,0] op_sel_hi:[1,0,1] neg_lo:[1,0,0] neg_hi:[1,0,0]
	v_pk_fma_f32 v[162:163], v[154:155], v[108:109], v[162:163] op_sel:[0,1,0] op_sel_hi:[1,1,1] neg_lo:[1,0,0] neg_hi:[1,0,0]
	v_pk_mul_f32 v[180:181], v[178:179], v[106:107] op_sel:[0,0] op_sel_hi:[1,0] neg_lo:[1,0] neg_hi:[1,0]
	v_pk_mul_f32 v[182:183], v[178:179], v[106:107] op_sel:[0,1] op_sel_hi:[1,1] neg_lo:[1,0] neg_hi:[1,0]
	v_pk_mul_f32 v[184:185], v[178:179], v[108:109] op_sel:[0,0] op_sel_hi:[1,0] neg_lo:[1,0] neg_hi:[1,0]
	v_pk_mul_f32 v[186:187], v[178:179], v[108:109] op_sel:[0,1] op_sel_hi:[1,1] neg_lo:[1,0] neg_hi:[1,0]
	v_pk_fma_f32 v[146:147], v[146:147], v[94:95], v[156:157] op_sel:[0,0,0] op_sel_hi:[1,0,1]
	v_pk_fma_f32 v[148:149], v[148:149], v[94:95], v[158:159] op_sel:[0,1,0] op_sel_hi:[1,1,1]
	v_pk_fma_f32 v[150:151], v[150:151], v[96:97], v[160:161] op_sel:[0,0,0] op_sel_hi:[1,0,1]
	v_pk_fma_f32 v[152:153], v[152:153], v[96:97], v[162:163] op_sel:[0,1,0] op_sel_hi:[1,1,1]
	v_pk_fma_f32 v[170:171], v[170:171], v[94:95], v[180:181] op_sel:[0,0,0] op_sel_hi:[1,0,1]
	v_pk_fma_f32 v[172:173], v[172:173], v[94:95], v[182:183] op_sel:[0,1,0] op_sel_hi:[1,1,1]
	v_pk_fma_f32 v[174:175], v[174:175], v[96:97], v[184:185] op_sel:[0,0,0] op_sel_hi:[1,0,1]
	v_pk_fma_f32 v[176:177], v[176:177], v[96:97], v[186:187] op_sel:[0,1,0] op_sel_hi:[1,1,1]
	ds_read_b128 v[94:97], v62 offset:39936
	ds_read_b128 v[98:101], v62 offset:40448
	ds_read_b128 v[102:105], v62 offset:40960
	ds_read_b128 v[106:109], v62 offset:41216
	v_add_u32_e32 v22, 0x9c00, v63
	ds_read2_b32 v[22:23], v22 offset0:192 offset1:196
	s_waitcnt lgkmcnt(5)
	v_pk_mul_f32 v[154:155], v[146:147], v[86:87] op_sel:[0,0] op_sel_hi:[1,0]
	v_pk_fma_f32 v[154:155], v[148:149], v[86:87], v[154:155] op_sel:[0,1,0] op_sel_hi:[1,1,1]
	v_pk_fma_f32 v[154:155], v[150:151], v[88:89], v[154:155] op_sel:[0,0,0] op_sel_hi:[1,0,1]
	v_pk_fma_f32 v[154:155], v[152:153], v[88:89], v[154:155] op_sel:[0,1,0] op_sel_hi:[1,1,1]
	v_pk_mul_f32 v[178:179], v[170:171], v[86:87] op_sel:[0,0] op_sel_hi:[1,0]
	v_pk_fma_f32 v[178:179], v[172:173], v[86:87], v[178:179] op_sel:[0,1,0] op_sel_hi:[1,1,1]
	v_pk_fma_f32 v[178:179], v[174:175], v[88:89], v[178:179] op_sel:[0,0,0] op_sel_hi:[1,0,1]
	v_pk_fma_f32 v[178:179], v[176:177], v[88:89], v[178:179] op_sel:[0,1,0] op_sel_hi:[1,1,1]
	v_pk_mul_f32 v[156:157], v[110:111], v[82:83] op_sel:[0,0] op_sel_hi:[1,0]
	v_add_f32_dpp v154, v154, v154 quad_perm:[1,0,3,2] row_mask:0xf bank_mask:0xf bound_ctrl:1
	v_add_f32_dpp v155, v155, v155 quad_perm:[1,0,3,2] row_mask:0xf bank_mask:0xf bound_ctrl:1
	v_add_f32_dpp v178, v178, v178 quad_perm:[1,0,3,2] row_mask:0xf bank_mask:0xf bound_ctrl:1
	v_add_f32_dpp v179, v179, v179 quad_perm:[1,0,3,2] row_mask:0xf bank_mask:0xf bound_ctrl:1
	v_add_f32_dpp v154, v154, v154 quad_perm:[2,3,0,1] row_mask:0xf bank_mask:0xf bound_ctrl:1
	v_add_f32_dpp v155, v155, v155 quad_perm:[2,3,0,1] row_mask:0xf bank_mask:0xf bound_ctrl:1
	v_add_f32_dpp v178, v178, v178 quad_perm:[2,3,0,1] row_mask:0xf bank_mask:0xf bound_ctrl:1
	v_add_f32_dpp v179, v179, v179 quad_perm:[2,3,0,1] row_mask:0xf bank_mask:0xf bound_ctrl:1
	v_add_f32_dpp v154, v154, v154 row_half_mirror row_mask:0xf bank_mask:0xf bound_ctrl:1
	v_add_f32_dpp v155, v155, v155 row_half_mirror row_mask:0xf bank_mask:0xf bound_ctrl:1
	v_add_f32_dpp v178, v178, v178 row_half_mirror row_mask:0xf bank_mask:0xf bound_ctrl:1
	v_add_f32_dpp v179, v179, v179 row_half_mirror row_mask:0xf bank_mask:0xf bound_ctrl:1
	v_add_f32_dpp v154, v154, v154 row_mirror row_mask:0xf bank_mask:0xf bound_ctrl:1
	v_add_f32_dpp v155, v155, v155 row_mirror row_mask:0xf bank_mask:0xf bound_ctrl:1
	v_add_f32_dpp v178, v178, v178 row_mirror row_mask:0xf bank_mask:0xf bound_ctrl:1
	v_add_f32_dpp v179, v179, v179 row_mirror row_mask:0xf bank_mask:0xf bound_ctrl:1
	v_pk_mul_f32 v[158:159], v[110:111], v[82:83] op_sel:[0,1] op_sel_hi:[1,1]
	v_pk_mul_f32 v[160:161], v[110:111], v[84:85] op_sel:[0,0] op_sel_hi:[1,0]
	v_pk_mul_f32 v[162:163], v[110:111], v[84:85] op_sel:[0,1] op_sel_hi:[1,1]
	v_pk_fma_f32 v[156:157], v[154:155], v[90:91], v[156:157] op_sel:[0,0,0] op_sel_hi:[1,0,1] neg_lo:[1,0,0] neg_hi:[1,0,0]
	v_pk_fma_f32 v[158:159], v[154:155], v[90:91], v[158:159] op_sel:[0,1,0] op_sel_hi:[1,1,1] neg_lo:[1,0,0] neg_hi:[1,0,0]
	v_pk_fma_f32 v[160:161], v[154:155], v[92:93], v[160:161] op_sel:[0,0,0] op_sel_hi:[1,0,1] neg_lo:[1,0,0] neg_hi:[1,0,0]
	v_pk_fma_f32 v[162:163], v[154:155], v[92:93], v[162:163] op_sel:[0,1,0] op_sel_hi:[1,1,1] neg_lo:[1,0,0] neg_hi:[1,0,0]
	v_pk_mul_f32 v[180:181], v[178:179], v[90:91] op_sel:[0,0] op_sel_hi:[1,0] neg_lo:[1,0] neg_hi:[1,0]
	v_pk_mul_f32 v[182:183], v[178:179], v[90:91] op_sel:[0,1] op_sel_hi:[1,1] neg_lo:[1,0] neg_hi:[1,0]
	v_pk_mul_f32 v[184:185], v[178:179], v[92:93] op_sel:[0,0] op_sel_hi:[1,0] neg_lo:[1,0] neg_hi:[1,0]
	v_pk_mul_f32 v[186:187], v[178:179], v[92:93] op_sel:[0,1] op_sel_hi:[1,1] neg_lo:[1,0] neg_hi:[1,0]
	v_pk_fma_f32 v[146:147], v[146:147], v[78:79], v[156:157] op_sel:[0,0,0] op_sel_hi:[1,0,1]
	v_pk_fma_f32 v[148:149], v[148:149], v[78:79], v[158:159] op_sel:[0,1,0] op_sel_hi:[1,1,1]
	v_pk_fma_f32 v[150:151], v[150:151], v[80:81], v[160:161] op_sel:[0,0,0] op_sel_hi:[1,0,1]
	v_pk_fma_f32 v[152:153], v[152:153], v[80:81], v[162:163] op_sel:[0,1,0] op_sel_hi:[1,1,1]
	v_pk_fma_f32 v[170:171], v[170:171], v[78:79], v[180:181] op_sel:[0,0,0] op_sel_hi:[1,0,1]
	v_pk_fma_f32 v[172:173], v[172:173], v[78:79], v[182:183] op_sel:[0,1,0] op_sel_hi:[1,1,1]
	v_pk_fma_f32 v[174:175], v[174:175], v[80:81], v[184:185] op_sel:[0,0,0] op_sel_hi:[1,0,1]
	v_pk_fma_f32 v[176:177], v[176:177], v[80:81], v[186:187] op_sel:[0,1,0] op_sel_hi:[1,1,1]
	ds_read_b128 v[78:81], v62 offset:41472
	ds_read_b128 v[82:85], v62 offset:41984
	ds_read_b128 v[86:89], v62 offset:42496
	ds_read_b128 v[90:93], v62 offset:42752
	v_add_u32_e32 v110, 0xa400, v63
	ds_read2_b32 v[110:111], v110 offset0:64 offset1:68
	s_waitcnt lgkmcnt(5)
	v_pk_mul_f32 v[154:155], v[146:147], v[102:103] op_sel:[0,0] op_sel_hi:[1,0]
	v_pk_fma_f32 v[154:155], v[148:149], v[102:103], v[154:155] op_sel:[0,1,0] op_sel_hi:[1,1,1]
	v_pk_fma_f32 v[154:155], v[150:151], v[104:105], v[154:155] op_sel:[0,0,0] op_sel_hi:[1,0,1]
	v_pk_fma_f32 v[154:155], v[152:153], v[104:105], v[154:155] op_sel:[0,1,0] op_sel_hi:[1,1,1]
	v_pk_mul_f32 v[178:179], v[170:171], v[102:103] op_sel:[0,0] op_sel_hi:[1,0]
	v_pk_fma_f32 v[178:179], v[172:173], v[102:103], v[178:179] op_sel:[0,1,0] op_sel_hi:[1,1,1]
	v_pk_fma_f32 v[178:179], v[174:175], v[104:105], v[178:179] op_sel:[0,0,0] op_sel_hi:[1,0,1]
	v_pk_fma_f32 v[178:179], v[176:177], v[104:105], v[178:179] op_sel:[0,1,0] op_sel_hi:[1,1,1]
	v_pk_mul_f32 v[156:157], v[22:23], v[98:99] op_sel:[0,0] op_sel_hi:[1,0]
	v_add_f32_dpp v154, v154, v154 quad_perm:[1,0,3,2] row_mask:0xf bank_mask:0xf bound_ctrl:1
	v_add_f32_dpp v155, v155, v155 quad_perm:[1,0,3,2] row_mask:0xf bank_mask:0xf bound_ctrl:1
	v_add_f32_dpp v178, v178, v178 quad_perm:[1,0,3,2] row_mask:0xf bank_mask:0xf bound_ctrl:1
	v_add_f32_dpp v179, v179, v179 quad_perm:[1,0,3,2] row_mask:0xf bank_mask:0xf bound_ctrl:1
	v_add_f32_dpp v154, v154, v154 quad_perm:[2,3,0,1] row_mask:0xf bank_mask:0xf bound_ctrl:1
	v_add_f32_dpp v155, v155, v155 quad_perm:[2,3,0,1] row_mask:0xf bank_mask:0xf bound_ctrl:1
	v_add_f32_dpp v178, v178, v178 quad_perm:[2,3,0,1] row_mask:0xf bank_mask:0xf bound_ctrl:1
	v_add_f32_dpp v179, v179, v179 quad_perm:[2,3,0,1] row_mask:0xf bank_mask:0xf bound_ctrl:1
	v_add_f32_dpp v154, v154, v154 row_half_mirror row_mask:0xf bank_mask:0xf bound_ctrl:1
	v_add_f32_dpp v155, v155, v155 row_half_mirror row_mask:0xf bank_mask:0xf bound_ctrl:1
	v_add_f32_dpp v178, v178, v178 row_half_mirror row_mask:0xf bank_mask:0xf bound_ctrl:1
	v_add_f32_dpp v179, v179, v179 row_half_mirror row_mask:0xf bank_mask:0xf bound_ctrl:1
	v_add_f32_dpp v154, v154, v154 row_mirror row_mask:0xf bank_mask:0xf bound_ctrl:1
	v_add_f32_dpp v155, v155, v155 row_mirror row_mask:0xf bank_mask:0xf bound_ctrl:1
	v_add_f32_dpp v178, v178, v178 row_mirror row_mask:0xf bank_mask:0xf bound_ctrl:1
	v_add_f32_dpp v179, v179, v179 row_mirror row_mask:0xf bank_mask:0xf bound_ctrl:1
	v_pk_mul_f32 v[158:159], v[22:23], v[98:99] op_sel:[0,1] op_sel_hi:[1,1]
	v_pk_mul_f32 v[160:161], v[22:23], v[100:101] op_sel:[0,0] op_sel_hi:[1,0]
	v_pk_mul_f32 v[162:163], v[22:23], v[100:101] op_sel:[0,1] op_sel_hi:[1,1]
	v_pk_fma_f32 v[156:157], v[154:155], v[106:107], v[156:157] op_sel:[0,0,0] op_sel_hi:[1,0,1] neg_lo:[1,0,0] neg_hi:[1,0,0]
	v_pk_fma_f32 v[158:159], v[154:155], v[106:107], v[158:159] op_sel:[0,1,0] op_sel_hi:[1,1,1] neg_lo:[1,0,0] neg_hi:[1,0,0]
	v_pk_fma_f32 v[160:161], v[154:155], v[108:109], v[160:161] op_sel:[0,0,0] op_sel_hi:[1,0,1] neg_lo:[1,0,0] neg_hi:[1,0,0]
	v_pk_fma_f32 v[162:163], v[154:155], v[108:109], v[162:163] op_sel:[0,1,0] op_sel_hi:[1,1,1] neg_lo:[1,0,0] neg_hi:[1,0,0]
	v_pk_mul_f32 v[180:181], v[178:179], v[106:107] op_sel:[0,0] op_sel_hi:[1,0] neg_lo:[1,0] neg_hi:[1,0]
	v_pk_mul_f32 v[182:183], v[178:179], v[106:107] op_sel:[0,1] op_sel_hi:[1,1] neg_lo:[1,0] neg_hi:[1,0]
	v_pk_mul_f32 v[184:185], v[178:179], v[108:109] op_sel:[0,0] op_sel_hi:[1,0] neg_lo:[1,0] neg_hi:[1,0]
	v_pk_mul_f32 v[186:187], v[178:179], v[108:109] op_sel:[0,1] op_sel_hi:[1,1] neg_lo:[1,0] neg_hi:[1,0]
	v_pk_fma_f32 v[146:147], v[146:147], v[94:95], v[156:157] op_sel:[0,0,0] op_sel_hi:[1,0,1]
	v_pk_fma_f32 v[148:149], v[148:149], v[94:95], v[158:159] op_sel:[0,1,0] op_sel_hi:[1,1,1]
	v_pk_fma_f32 v[150:151], v[150:151], v[96:97], v[160:161] op_sel:[0,0,0] op_sel_hi:[1,0,1]
	v_pk_fma_f32 v[152:153], v[152:153], v[96:97], v[162:163] op_sel:[0,1,0] op_sel_hi:[1,1,1]
	v_pk_fma_f32 v[170:171], v[170:171], v[94:95], v[180:181] op_sel:[0,0,0] op_sel_hi:[1,0,1]
	v_pk_fma_f32 v[172:173], v[172:173], v[94:95], v[182:183] op_sel:[0,1,0] op_sel_hi:[1,1,1]
	v_pk_fma_f32 v[174:175], v[174:175], v[96:97], v[184:185] op_sel:[0,0,0] op_sel_hi:[1,0,1]
	v_pk_fma_f32 v[176:177], v[176:177], v[96:97], v[186:187] op_sel:[0,1,0] op_sel_hi:[1,1,1]
	ds_read_b128 v[94:97], v62 offset:43008
	ds_read_b128 v[98:101], v62 offset:43520
	ds_read_b128 v[102:105], v62 offset:44032
	ds_read_b128 v[106:109], v62 offset:44288
	v_add_u32_e32 v22, 0xa800, v63
	ds_read2_b32 v[22:23], v22 offset0:192 offset1:196
	s_waitcnt lgkmcnt(5)
	v_pk_mul_f32 v[154:155], v[146:147], v[86:87] op_sel:[0,0] op_sel_hi:[1,0]
	v_pk_fma_f32 v[154:155], v[148:149], v[86:87], v[154:155] op_sel:[0,1,0] op_sel_hi:[1,1,1]
	v_pk_fma_f32 v[154:155], v[150:151], v[88:89], v[154:155] op_sel:[0,0,0] op_sel_hi:[1,0,1]
	v_pk_fma_f32 v[154:155], v[152:153], v[88:89], v[154:155] op_sel:[0,1,0] op_sel_hi:[1,1,1]
	v_pk_mul_f32 v[178:179], v[170:171], v[86:87] op_sel:[0,0] op_sel_hi:[1,0]
	v_pk_fma_f32 v[178:179], v[172:173], v[86:87], v[178:179] op_sel:[0,1,0] op_sel_hi:[1,1,1]
	v_pk_fma_f32 v[178:179], v[174:175], v[88:89], v[178:179] op_sel:[0,0,0] op_sel_hi:[1,0,1]
	v_pk_fma_f32 v[178:179], v[176:177], v[88:89], v[178:179] op_sel:[0,1,0] op_sel_hi:[1,1,1]
	v_pk_mul_f32 v[156:157], v[110:111], v[82:83] op_sel:[0,0] op_sel_hi:[1,0]
	v_add_f32_dpp v154, v154, v154 quad_perm:[1,0,3,2] row_mask:0xf bank_mask:0xf bound_ctrl:1
	v_add_f32_dpp v155, v155, v155 quad_perm:[1,0,3,2] row_mask:0xf bank_mask:0xf bound_ctrl:1
	v_add_f32_dpp v178, v178, v178 quad_perm:[1,0,3,2] row_mask:0xf bank_mask:0xf bound_ctrl:1
	v_add_f32_dpp v179, v179, v179 quad_perm:[1,0,3,2] row_mask:0xf bank_mask:0xf bound_ctrl:1
	v_add_f32_dpp v154, v154, v154 quad_perm:[2,3,0,1] row_mask:0xf bank_mask:0xf bound_ctrl:1
	v_add_f32_dpp v155, v155, v155 quad_perm:[2,3,0,1] row_mask:0xf bank_mask:0xf bound_ctrl:1
	v_add_f32_dpp v178, v178, v178 quad_perm:[2,3,0,1] row_mask:0xf bank_mask:0xf bound_ctrl:1
	v_add_f32_dpp v179, v179, v179 quad_perm:[2,3,0,1] row_mask:0xf bank_mask:0xf bound_ctrl:1
	v_add_f32_dpp v154, v154, v154 row_half_mirror row_mask:0xf bank_mask:0xf bound_ctrl:1
	v_add_f32_dpp v155, v155, v155 row_half_mirror row_mask:0xf bank_mask:0xf bound_ctrl:1
	v_add_f32_dpp v178, v178, v178 row_half_mirror row_mask:0xf bank_mask:0xf bound_ctrl:1
	v_add_f32_dpp v179, v179, v179 row_half_mirror row_mask:0xf bank_mask:0xf bound_ctrl:1
	v_add_f32_dpp v154, v154, v154 row_mirror row_mask:0xf bank_mask:0xf bound_ctrl:1
	v_add_f32_dpp v155, v155, v155 row_mirror row_mask:0xf bank_mask:0xf bound_ctrl:1
	v_add_f32_dpp v178, v178, v178 row_mirror row_mask:0xf bank_mask:0xf bound_ctrl:1
	v_add_f32_dpp v179, v179, v179 row_mirror row_mask:0xf bank_mask:0xf bound_ctrl:1
	v_pk_mul_f32 v[158:159], v[110:111], v[82:83] op_sel:[0,1] op_sel_hi:[1,1]
	v_pk_mul_f32 v[160:161], v[110:111], v[84:85] op_sel:[0,0] op_sel_hi:[1,0]
	v_pk_mul_f32 v[162:163], v[110:111], v[84:85] op_sel:[0,1] op_sel_hi:[1,1]
	v_pk_fma_f32 v[156:157], v[154:155], v[90:91], v[156:157] op_sel:[0,0,0] op_sel_hi:[1,0,1] neg_lo:[1,0,0] neg_hi:[1,0,0]
	v_pk_fma_f32 v[158:159], v[154:155], v[90:91], v[158:159] op_sel:[0,1,0] op_sel_hi:[1,1,1] neg_lo:[1,0,0] neg_hi:[1,0,0]
	v_pk_fma_f32 v[160:161], v[154:155], v[92:93], v[160:161] op_sel:[0,0,0] op_sel_hi:[1,0,1] neg_lo:[1,0,0] neg_hi:[1,0,0]
	v_pk_fma_f32 v[162:163], v[154:155], v[92:93], v[162:163] op_sel:[0,1,0] op_sel_hi:[1,1,1] neg_lo:[1,0,0] neg_hi:[1,0,0]
	v_pk_mul_f32 v[180:181], v[178:179], v[90:91] op_sel:[0,0] op_sel_hi:[1,0] neg_lo:[1,0] neg_hi:[1,0]
	v_pk_mul_f32 v[182:183], v[178:179], v[90:91] op_sel:[0,1] op_sel_hi:[1,1] neg_lo:[1,0] neg_hi:[1,0]
	v_pk_mul_f32 v[184:185], v[178:179], v[92:93] op_sel:[0,0] op_sel_hi:[1,0] neg_lo:[1,0] neg_hi:[1,0]
	v_pk_mul_f32 v[186:187], v[178:179], v[92:93] op_sel:[0,1] op_sel_hi:[1,1] neg_lo:[1,0] neg_hi:[1,0]
	v_pk_fma_f32 v[146:147], v[146:147], v[78:79], v[156:157] op_sel:[0,0,0] op_sel_hi:[1,0,1]
	v_pk_fma_f32 v[148:149], v[148:149], v[78:79], v[158:159] op_sel:[0,1,0] op_sel_hi:[1,1,1]
	v_pk_fma_f32 v[150:151], v[150:151], v[80:81], v[160:161] op_sel:[0,0,0] op_sel_hi:[1,0,1]
	v_pk_fma_f32 v[152:153], v[152:153], v[80:81], v[162:163] op_sel:[0,1,0] op_sel_hi:[1,1,1]
	v_pk_fma_f32 v[170:171], v[170:171], v[78:79], v[180:181] op_sel:[0,0,0] op_sel_hi:[1,0,1]
	v_pk_fma_f32 v[172:173], v[172:173], v[78:79], v[182:183] op_sel:[0,1,0] op_sel_hi:[1,1,1]
	v_pk_fma_f32 v[174:175], v[174:175], v[80:81], v[184:185] op_sel:[0,0,0] op_sel_hi:[1,0,1]
	v_pk_fma_f32 v[176:177], v[176:177], v[80:81], v[186:187] op_sel:[0,1,0] op_sel_hi:[1,1,1]
	ds_read_b128 v[78:81], v62 offset:44544
	ds_read_b128 v[82:85], v62 offset:45056
	ds_read_b128 v[86:89], v62 offset:45568
	ds_read_b128 v[90:93], v62 offset:45824
	v_add_u32_e32 v110, 0xb000, v63
	ds_read2_b32 v[110:111], v110 offset0:64 offset1:68
	s_waitcnt lgkmcnt(5)
	v_pk_mul_f32 v[154:155], v[146:147], v[102:103] op_sel:[0,0] op_sel_hi:[1,0]
	v_pk_fma_f32 v[154:155], v[148:149], v[102:103], v[154:155] op_sel:[0,1,0] op_sel_hi:[1,1,1]
	v_pk_fma_f32 v[154:155], v[150:151], v[104:105], v[154:155] op_sel:[0,0,0] op_sel_hi:[1,0,1]
	v_pk_fma_f32 v[154:155], v[152:153], v[104:105], v[154:155] op_sel:[0,1,0] op_sel_hi:[1,1,1]
	v_pk_mul_f32 v[178:179], v[170:171], v[102:103] op_sel:[0,0] op_sel_hi:[1,0]
	v_pk_fma_f32 v[178:179], v[172:173], v[102:103], v[178:179] op_sel:[0,1,0] op_sel_hi:[1,1,1]
	v_pk_fma_f32 v[178:179], v[174:175], v[104:105], v[178:179] op_sel:[0,0,0] op_sel_hi:[1,0,1]
	v_pk_fma_f32 v[178:179], v[176:177], v[104:105], v[178:179] op_sel:[0,1,0] op_sel_hi:[1,1,1]
	v_pk_mul_f32 v[156:157], v[22:23], v[98:99] op_sel:[0,0] op_sel_hi:[1,0]
	v_add_f32_dpp v154, v154, v154 quad_perm:[1,0,3,2] row_mask:0xf bank_mask:0xf bound_ctrl:1
	v_add_f32_dpp v155, v155, v155 quad_perm:[1,0,3,2] row_mask:0xf bank_mask:0xf bound_ctrl:1
	v_add_f32_dpp v178, v178, v178 quad_perm:[1,0,3,2] row_mask:0xf bank_mask:0xf bound_ctrl:1
	v_add_f32_dpp v179, v179, v179 quad_perm:[1,0,3,2] row_mask:0xf bank_mask:0xf bound_ctrl:1
	v_add_f32_dpp v154, v154, v154 quad_perm:[2,3,0,1] row_mask:0xf bank_mask:0xf bound_ctrl:1
	v_add_f32_dpp v155, v155, v155 quad_perm:[2,3,0,1] row_mask:0xf bank_mask:0xf bound_ctrl:1
	v_add_f32_dpp v178, v178, v178 quad_perm:[2,3,0,1] row_mask:0xf bank_mask:0xf bound_ctrl:1
	v_add_f32_dpp v179, v179, v179 quad_perm:[2,3,0,1] row_mask:0xf bank_mask:0xf bound_ctrl:1
	v_add_f32_dpp v154, v154, v154 row_half_mirror row_mask:0xf bank_mask:0xf bound_ctrl:1
	v_add_f32_dpp v155, v155, v155 row_half_mirror row_mask:0xf bank_mask:0xf bound_ctrl:1
	v_add_f32_dpp v178, v178, v178 row_half_mirror row_mask:0xf bank_mask:0xf bound_ctrl:1
	v_add_f32_dpp v179, v179, v179 row_half_mirror row_mask:0xf bank_mask:0xf bound_ctrl:1
	v_add_f32_dpp v154, v154, v154 row_mirror row_mask:0xf bank_mask:0xf bound_ctrl:1
	v_add_f32_dpp v155, v155, v155 row_mirror row_mask:0xf bank_mask:0xf bound_ctrl:1
	v_add_f32_dpp v178, v178, v178 row_mirror row_mask:0xf bank_mask:0xf bound_ctrl:1
	v_add_f32_dpp v179, v179, v179 row_mirror row_mask:0xf bank_mask:0xf bound_ctrl:1
	v_pk_mul_f32 v[158:159], v[22:23], v[98:99] op_sel:[0,1] op_sel_hi:[1,1]
	v_pk_mul_f32 v[160:161], v[22:23], v[100:101] op_sel:[0,0] op_sel_hi:[1,0]
	v_pk_mul_f32 v[162:163], v[22:23], v[100:101] op_sel:[0,1] op_sel_hi:[1,1]
	v_pk_fma_f32 v[156:157], v[154:155], v[106:107], v[156:157] op_sel:[0,0,0] op_sel_hi:[1,0,1] neg_lo:[1,0,0] neg_hi:[1,0,0]
	v_pk_fma_f32 v[158:159], v[154:155], v[106:107], v[158:159] op_sel:[0,1,0] op_sel_hi:[1,1,1] neg_lo:[1,0,0] neg_hi:[1,0,0]
	v_pk_fma_f32 v[160:161], v[154:155], v[108:109], v[160:161] op_sel:[0,0,0] op_sel_hi:[1,0,1] neg_lo:[1,0,0] neg_hi:[1,0,0]
	v_pk_fma_f32 v[162:163], v[154:155], v[108:109], v[162:163] op_sel:[0,1,0] op_sel_hi:[1,1,1] neg_lo:[1,0,0] neg_hi:[1,0,0]
	v_pk_mul_f32 v[180:181], v[178:179], v[106:107] op_sel:[0,0] op_sel_hi:[1,0] neg_lo:[1,0] neg_hi:[1,0]
	v_pk_mul_f32 v[182:183], v[178:179], v[106:107] op_sel:[0,1] op_sel_hi:[1,1] neg_lo:[1,0] neg_hi:[1,0]
	v_pk_mul_f32 v[184:185], v[178:179], v[108:109] op_sel:[0,0] op_sel_hi:[1,0] neg_lo:[1,0] neg_hi:[1,0]
	v_pk_mul_f32 v[186:187], v[178:179], v[108:109] op_sel:[0,1] op_sel_hi:[1,1] neg_lo:[1,0] neg_hi:[1,0]
	v_pk_fma_f32 v[146:147], v[146:147], v[94:95], v[156:157] op_sel:[0,0,0] op_sel_hi:[1,0,1]
	v_pk_fma_f32 v[148:149], v[148:149], v[94:95], v[158:159] op_sel:[0,1,0] op_sel_hi:[1,1,1]
	v_pk_fma_f32 v[150:151], v[150:151], v[96:97], v[160:161] op_sel:[0,0,0] op_sel_hi:[1,0,1]
	v_pk_fma_f32 v[152:153], v[152:153], v[96:97], v[162:163] op_sel:[0,1,0] op_sel_hi:[1,1,1]
	v_pk_fma_f32 v[170:171], v[170:171], v[94:95], v[180:181] op_sel:[0,0,0] op_sel_hi:[1,0,1]
	v_pk_fma_f32 v[172:173], v[172:173], v[94:95], v[182:183] op_sel:[0,1,0] op_sel_hi:[1,1,1]
	v_pk_fma_f32 v[174:175], v[174:175], v[96:97], v[184:185] op_sel:[0,0,0] op_sel_hi:[1,0,1]
	v_pk_fma_f32 v[176:177], v[176:177], v[96:97], v[186:187] op_sel:[0,1,0] op_sel_hi:[1,1,1]
	ds_read_b128 v[94:97], v62 offset:46080
	ds_read_b128 v[98:101], v62 offset:46592
	ds_read_b128 v[102:105], v62 offset:47104
	ds_read_b128 v[106:109], v62 offset:47360
	v_add_u32_e32 v22, 0xb400, v63
	ds_read2_b32 v[22:23], v22 offset0:192 offset1:196
	s_waitcnt lgkmcnt(5)
	v_pk_mul_f32 v[154:155], v[146:147], v[86:87] op_sel:[0,0] op_sel_hi:[1,0]
	v_pk_fma_f32 v[154:155], v[148:149], v[86:87], v[154:155] op_sel:[0,1,0] op_sel_hi:[1,1,1]
	v_pk_fma_f32 v[154:155], v[150:151], v[88:89], v[154:155] op_sel:[0,0,0] op_sel_hi:[1,0,1]
	v_pk_fma_f32 v[154:155], v[152:153], v[88:89], v[154:155] op_sel:[0,1,0] op_sel_hi:[1,1,1]
	v_pk_mul_f32 v[178:179], v[170:171], v[86:87] op_sel:[0,0] op_sel_hi:[1,0]
	v_pk_fma_f32 v[178:179], v[172:173], v[86:87], v[178:179] op_sel:[0,1,0] op_sel_hi:[1,1,1]
	v_pk_fma_f32 v[178:179], v[174:175], v[88:89], v[178:179] op_sel:[0,0,0] op_sel_hi:[1,0,1]
	v_pk_fma_f32 v[178:179], v[176:177], v[88:89], v[178:179] op_sel:[0,1,0] op_sel_hi:[1,1,1]
	v_pk_mul_f32 v[156:157], v[110:111], v[82:83] op_sel:[0,0] op_sel_hi:[1,0]
	v_add_f32_dpp v154, v154, v154 quad_perm:[1,0,3,2] row_mask:0xf bank_mask:0xf bound_ctrl:1
	v_add_f32_dpp v155, v155, v155 quad_perm:[1,0,3,2] row_mask:0xf bank_mask:0xf bound_ctrl:1
	v_add_f32_dpp v178, v178, v178 quad_perm:[1,0,3,2] row_mask:0xf bank_mask:0xf bound_ctrl:1
	v_add_f32_dpp v179, v179, v179 quad_perm:[1,0,3,2] row_mask:0xf bank_mask:0xf bound_ctrl:1
	v_add_f32_dpp v154, v154, v154 quad_perm:[2,3,0,1] row_mask:0xf bank_mask:0xf bound_ctrl:1
	v_add_f32_dpp v155, v155, v155 quad_perm:[2,3,0,1] row_mask:0xf bank_mask:0xf bound_ctrl:1
	v_add_f32_dpp v178, v178, v178 quad_perm:[2,3,0,1] row_mask:0xf bank_mask:0xf bound_ctrl:1
	v_add_f32_dpp v179, v179, v179 quad_perm:[2,3,0,1] row_mask:0xf bank_mask:0xf bound_ctrl:1
	v_add_f32_dpp v154, v154, v154 row_half_mirror row_mask:0xf bank_mask:0xf bound_ctrl:1
	v_add_f32_dpp v155, v155, v155 row_half_mirror row_mask:0xf bank_mask:0xf bound_ctrl:1
	v_add_f32_dpp v178, v178, v178 row_half_mirror row_mask:0xf bank_mask:0xf bound_ctrl:1
	v_add_f32_dpp v179, v179, v179 row_half_mirror row_mask:0xf bank_mask:0xf bound_ctrl:1
	v_add_f32_dpp v154, v154, v154 row_mirror row_mask:0xf bank_mask:0xf bound_ctrl:1
	v_add_f32_dpp v155, v155, v155 row_mirror row_mask:0xf bank_mask:0xf bound_ctrl:1
	v_add_f32_dpp v178, v178, v178 row_mirror row_mask:0xf bank_mask:0xf bound_ctrl:1
	v_add_f32_dpp v179, v179, v179 row_mirror row_mask:0xf bank_mask:0xf bound_ctrl:1
	v_pk_mul_f32 v[158:159], v[110:111], v[82:83] op_sel:[0,1] op_sel_hi:[1,1]
	v_pk_mul_f32 v[160:161], v[110:111], v[84:85] op_sel:[0,0] op_sel_hi:[1,0]
	v_pk_mul_f32 v[162:163], v[110:111], v[84:85] op_sel:[0,1] op_sel_hi:[1,1]
	v_pk_fma_f32 v[156:157], v[154:155], v[90:91], v[156:157] op_sel:[0,0,0] op_sel_hi:[1,0,1] neg_lo:[1,0,0] neg_hi:[1,0,0]
	v_pk_fma_f32 v[158:159], v[154:155], v[90:91], v[158:159] op_sel:[0,1,0] op_sel_hi:[1,1,1] neg_lo:[1,0,0] neg_hi:[1,0,0]
	v_pk_fma_f32 v[160:161], v[154:155], v[92:93], v[160:161] op_sel:[0,0,0] op_sel_hi:[1,0,1] neg_lo:[1,0,0] neg_hi:[1,0,0]
	v_pk_fma_f32 v[162:163], v[154:155], v[92:93], v[162:163] op_sel:[0,1,0] op_sel_hi:[1,1,1] neg_lo:[1,0,0] neg_hi:[1,0,0]
	v_pk_mul_f32 v[180:181], v[178:179], v[90:91] op_sel:[0,0] op_sel_hi:[1,0] neg_lo:[1,0] neg_hi:[1,0]
	v_pk_mul_f32 v[182:183], v[178:179], v[90:91] op_sel:[0,1] op_sel_hi:[1,1] neg_lo:[1,0] neg_hi:[1,0]
	v_pk_mul_f32 v[184:185], v[178:179], v[92:93] op_sel:[0,0] op_sel_hi:[1,0] neg_lo:[1,0] neg_hi:[1,0]
	v_pk_mul_f32 v[186:187], v[178:179], v[92:93] op_sel:[0,1] op_sel_hi:[1,1] neg_lo:[1,0] neg_hi:[1,0]
	v_pk_fma_f32 v[146:147], v[146:147], v[78:79], v[156:157] op_sel:[0,0,0] op_sel_hi:[1,0,1]
	v_pk_fma_f32 v[148:149], v[148:149], v[78:79], v[158:159] op_sel:[0,1,0] op_sel_hi:[1,1,1]
	v_pk_fma_f32 v[150:151], v[150:151], v[80:81], v[160:161] op_sel:[0,0,0] op_sel_hi:[1,0,1]
	v_pk_fma_f32 v[152:153], v[152:153], v[80:81], v[162:163] op_sel:[0,1,0] op_sel_hi:[1,1,1]
	v_pk_fma_f32 v[170:171], v[170:171], v[78:79], v[180:181] op_sel:[0,0,0] op_sel_hi:[1,0,1]
	v_pk_fma_f32 v[172:173], v[172:173], v[78:79], v[182:183] op_sel:[0,1,0] op_sel_hi:[1,1,1]
	v_pk_fma_f32 v[174:175], v[174:175], v[80:81], v[184:185] op_sel:[0,0,0] op_sel_hi:[1,0,1]
	v_pk_fma_f32 v[176:177], v[176:177], v[80:81], v[186:187] op_sel:[0,1,0] op_sel_hi:[1,1,1]
	ds_read_b128 v[78:81], v62 offset:47616
	ds_read_b128 v[82:85], v62 offset:48128
	ds_read_b128 v[86:89], v62 offset:48640
	ds_read_b128 v[90:93], v62 offset:48896
	v_add_u32_e32 v110, 0xbc00, v63
	ds_read2_b32 v[110:111], v110 offset0:64 offset1:68
	s_waitcnt lgkmcnt(5)
	v_pk_mul_f32 v[154:155], v[146:147], v[102:103] op_sel:[0,0] op_sel_hi:[1,0]
	v_pk_fma_f32 v[154:155], v[148:149], v[102:103], v[154:155] op_sel:[0,1,0] op_sel_hi:[1,1,1]
	v_pk_fma_f32 v[154:155], v[150:151], v[104:105], v[154:155] op_sel:[0,0,0] op_sel_hi:[1,0,1]
	v_pk_fma_f32 v[154:155], v[152:153], v[104:105], v[154:155] op_sel:[0,1,0] op_sel_hi:[1,1,1]
	v_pk_mul_f32 v[178:179], v[170:171], v[102:103] op_sel:[0,0] op_sel_hi:[1,0]
	v_pk_fma_f32 v[178:179], v[172:173], v[102:103], v[178:179] op_sel:[0,1,0] op_sel_hi:[1,1,1]
	v_pk_fma_f32 v[178:179], v[174:175], v[104:105], v[178:179] op_sel:[0,0,0] op_sel_hi:[1,0,1]
	v_pk_fma_f32 v[178:179], v[176:177], v[104:105], v[178:179] op_sel:[0,1,0] op_sel_hi:[1,1,1]
	v_pk_mul_f32 v[156:157], v[22:23], v[98:99] op_sel:[0,0] op_sel_hi:[1,0]
	v_add_f32_dpp v154, v154, v154 quad_perm:[1,0,3,2] row_mask:0xf bank_mask:0xf bound_ctrl:1
	v_add_f32_dpp v155, v155, v155 quad_perm:[1,0,3,2] row_mask:0xf bank_mask:0xf bound_ctrl:1
	v_add_f32_dpp v178, v178, v178 quad_perm:[1,0,3,2] row_mask:0xf bank_mask:0xf bound_ctrl:1
	v_add_f32_dpp v179, v179, v179 quad_perm:[1,0,3,2] row_mask:0xf bank_mask:0xf bound_ctrl:1
	v_add_f32_dpp v154, v154, v154 quad_perm:[2,3,0,1] row_mask:0xf bank_mask:0xf bound_ctrl:1
	v_add_f32_dpp v155, v155, v155 quad_perm:[2,3,0,1] row_mask:0xf bank_mask:0xf bound_ctrl:1
	v_add_f32_dpp v178, v178, v178 quad_perm:[2,3,0,1] row_mask:0xf bank_mask:0xf bound_ctrl:1
	v_add_f32_dpp v179, v179, v179 quad_perm:[2,3,0,1] row_mask:0xf bank_mask:0xf bound_ctrl:1
	v_add_f32_dpp v154, v154, v154 row_half_mirror row_mask:0xf bank_mask:0xf bound_ctrl:1
	v_add_f32_dpp v155, v155, v155 row_half_mirror row_mask:0xf bank_mask:0xf bound_ctrl:1
	v_add_f32_dpp v178, v178, v178 row_half_mirror row_mask:0xf bank_mask:0xf bound_ctrl:1
	v_add_f32_dpp v179, v179, v179 row_half_mirror row_mask:0xf bank_mask:0xf bound_ctrl:1
	v_add_f32_dpp v154, v154, v154 row_mirror row_mask:0xf bank_mask:0xf bound_ctrl:1
	v_add_f32_dpp v155, v155, v155 row_mirror row_mask:0xf bank_mask:0xf bound_ctrl:1
	v_add_f32_dpp v178, v178, v178 row_mirror row_mask:0xf bank_mask:0xf bound_ctrl:1
	v_add_f32_dpp v179, v179, v179 row_mirror row_mask:0xf bank_mask:0xf bound_ctrl:1
	v_pk_mul_f32 v[158:159], v[22:23], v[98:99] op_sel:[0,1] op_sel_hi:[1,1]
	v_pk_mul_f32 v[160:161], v[22:23], v[100:101] op_sel:[0,0] op_sel_hi:[1,0]
	v_pk_mul_f32 v[162:163], v[22:23], v[100:101] op_sel:[0,1] op_sel_hi:[1,1]
	v_pk_fma_f32 v[156:157], v[154:155], v[106:107], v[156:157] op_sel:[0,0,0] op_sel_hi:[1,0,1] neg_lo:[1,0,0] neg_hi:[1,0,0]
	v_pk_fma_f32 v[158:159], v[154:155], v[106:107], v[158:159] op_sel:[0,1,0] op_sel_hi:[1,1,1] neg_lo:[1,0,0] neg_hi:[1,0,0]
	v_pk_fma_f32 v[160:161], v[154:155], v[108:109], v[160:161] op_sel:[0,0,0] op_sel_hi:[1,0,1] neg_lo:[1,0,0] neg_hi:[1,0,0]
	v_pk_fma_f32 v[162:163], v[154:155], v[108:109], v[162:163] op_sel:[0,1,0] op_sel_hi:[1,1,1] neg_lo:[1,0,0] neg_hi:[1,0,0]
	v_pk_mul_f32 v[180:181], v[178:179], v[106:107] op_sel:[0,0] op_sel_hi:[1,0] neg_lo:[1,0] neg_hi:[1,0]
	v_pk_mul_f32 v[182:183], v[178:179], v[106:107] op_sel:[0,1] op_sel_hi:[1,1] neg_lo:[1,0] neg_hi:[1,0]
	v_pk_mul_f32 v[184:185], v[178:179], v[108:109] op_sel:[0,0] op_sel_hi:[1,0] neg_lo:[1,0] neg_hi:[1,0]
	v_pk_mul_f32 v[186:187], v[178:179], v[108:109] op_sel:[0,1] op_sel_hi:[1,1] neg_lo:[1,0] neg_hi:[1,0]
	v_pk_fma_f32 v[146:147], v[146:147], v[94:95], v[156:157] op_sel:[0,0,0] op_sel_hi:[1,0,1]
	v_pk_fma_f32 v[148:149], v[148:149], v[94:95], v[158:159] op_sel:[0,1,0] op_sel_hi:[1,1,1]
	v_pk_fma_f32 v[150:151], v[150:151], v[96:97], v[160:161] op_sel:[0,0,0] op_sel_hi:[1,0,1]
	v_pk_fma_f32 v[152:153], v[152:153], v[96:97], v[162:163] op_sel:[0,1,0] op_sel_hi:[1,1,1]
	v_pk_fma_f32 v[170:171], v[170:171], v[94:95], v[180:181] op_sel:[0,0,0] op_sel_hi:[1,0,1]
	v_pk_fma_f32 v[172:173], v[172:173], v[94:95], v[182:183] op_sel:[0,1,0] op_sel_hi:[1,1,1]
	v_pk_fma_f32 v[174:175], v[174:175], v[96:97], v[184:185] op_sel:[0,0,0] op_sel_hi:[1,0,1]
	v_pk_fma_f32 v[176:177], v[176:177], v[96:97], v[186:187] op_sel:[0,1,0] op_sel_hi:[1,1,1]
	s_waitcnt lgkmcnt(0)
	v_pk_mul_f32 v[154:155], v[146:147], v[86:87] op_sel:[0,0] op_sel_hi:[1,0]
	v_pk_fma_f32 v[154:155], v[148:149], v[86:87], v[154:155] op_sel:[0,1,0] op_sel_hi:[1,1,1]
	v_pk_fma_f32 v[154:155], v[150:151], v[88:89], v[154:155] op_sel:[0,0,0] op_sel_hi:[1,0,1]
	v_pk_fma_f32 v[154:155], v[152:153], v[88:89], v[154:155] op_sel:[0,1,0] op_sel_hi:[1,1,1]
	v_pk_mul_f32 v[178:179], v[170:171], v[86:87] op_sel:[0,0] op_sel_hi:[1,0]
	v_pk_fma_f32 v[178:179], v[172:173], v[86:87], v[178:179] op_sel:[0,1,0] op_sel_hi:[1,1,1]
	v_pk_fma_f32 v[178:179], v[174:175], v[88:89], v[178:179] op_sel:[0,0,0] op_sel_hi:[1,0,1]
	v_pk_fma_f32 v[178:179], v[176:177], v[88:89], v[178:179] op_sel:[0,1,0] op_sel_hi:[1,1,1]
	v_pk_mul_f32 v[156:157], v[110:111], v[82:83] op_sel:[0,0] op_sel_hi:[1,0]
	v_add_f32_dpp v154, v154, v154 quad_perm:[1,0,3,2] row_mask:0xf bank_mask:0xf bound_ctrl:1
	v_add_f32_dpp v155, v155, v155 quad_perm:[1,0,3,2] row_mask:0xf bank_mask:0xf bound_ctrl:1
	v_add_f32_dpp v178, v178, v178 quad_perm:[1,0,3,2] row_mask:0xf bank_mask:0xf bound_ctrl:1
	v_add_f32_dpp v179, v179, v179 quad_perm:[1,0,3,2] row_mask:0xf bank_mask:0xf bound_ctrl:1
	v_add_f32_dpp v154, v154, v154 quad_perm:[2,3,0,1] row_mask:0xf bank_mask:0xf bound_ctrl:1
	v_add_f32_dpp v155, v155, v155 quad_perm:[2,3,0,1] row_mask:0xf bank_mask:0xf bound_ctrl:1
	v_add_f32_dpp v178, v178, v178 quad_perm:[2,3,0,1] row_mask:0xf bank_mask:0xf bound_ctrl:1
	v_add_f32_dpp v179, v179, v179 quad_perm:[2,3,0,1] row_mask:0xf bank_mask:0xf bound_ctrl:1
	v_add_f32_dpp v154, v154, v154 row_half_mirror row_mask:0xf bank_mask:0xf bound_ctrl:1
	v_add_f32_dpp v155, v155, v155 row_half_mirror row_mask:0xf bank_mask:0xf bound_ctrl:1
	v_add_f32_dpp v178, v178, v178 row_half_mirror row_mask:0xf bank_mask:0xf bound_ctrl:1
	v_add_f32_dpp v179, v179, v179 row_half_mirror row_mask:0xf bank_mask:0xf bound_ctrl:1
	v_add_f32_dpp v154, v154, v154 row_mirror row_mask:0xf bank_mask:0xf bound_ctrl:1
	v_add_f32_dpp v155, v155, v155 row_mirror row_mask:0xf bank_mask:0xf bound_ctrl:1
	v_add_f32_dpp v178, v178, v178 row_mirror row_mask:0xf bank_mask:0xf bound_ctrl:1
	v_add_f32_dpp v179, v179, v179 row_mirror row_mask:0xf bank_mask:0xf bound_ctrl:1
	v_pk_mul_f32 v[158:159], v[110:111], v[82:83] op_sel:[0,1] op_sel_hi:[1,1]
	v_pk_mul_f32 v[160:161], v[110:111], v[84:85] op_sel:[0,0] op_sel_hi:[1,0]
	v_pk_mul_f32 v[162:163], v[110:111], v[84:85] op_sel:[0,1] op_sel_hi:[1,1]
	v_pk_fma_f32 v[156:157], v[154:155], v[90:91], v[156:157] op_sel:[0,0,0] op_sel_hi:[1,0,1] neg_lo:[1,0,0] neg_hi:[1,0,0]
	v_pk_fma_f32 v[158:159], v[154:155], v[90:91], v[158:159] op_sel:[0,1,0] op_sel_hi:[1,1,1] neg_lo:[1,0,0] neg_hi:[1,0,0]
	v_pk_fma_f32 v[160:161], v[154:155], v[92:93], v[160:161] op_sel:[0,0,0] op_sel_hi:[1,0,1] neg_lo:[1,0,0] neg_hi:[1,0,0]
	v_pk_fma_f32 v[162:163], v[154:155], v[92:93], v[162:163] op_sel:[0,1,0] op_sel_hi:[1,1,1] neg_lo:[1,0,0] neg_hi:[1,0,0]
	v_pk_mul_f32 v[180:181], v[178:179], v[90:91] op_sel:[0,0] op_sel_hi:[1,0] neg_lo:[1,0] neg_hi:[1,0]
	v_pk_mul_f32 v[182:183], v[178:179], v[90:91] op_sel:[0,1] op_sel_hi:[1,1] neg_lo:[1,0] neg_hi:[1,0]
	v_pk_mul_f32 v[184:185], v[178:179], v[92:93] op_sel:[0,0] op_sel_hi:[1,0] neg_lo:[1,0] neg_hi:[1,0]
	v_pk_mul_f32 v[186:187], v[178:179], v[92:93] op_sel:[0,1] op_sel_hi:[1,1] neg_lo:[1,0] neg_hi:[1,0]
	v_pk_fma_f32 v[146:147], v[146:147], v[78:79], v[156:157] op_sel:[0,0,0] op_sel_hi:[1,0,1]
	v_pk_fma_f32 v[148:149], v[148:149], v[78:79], v[158:159] op_sel:[0,1,0] op_sel_hi:[1,1,1]
	v_pk_fma_f32 v[150:151], v[150:151], v[80:81], v[160:161] op_sel:[0,0,0] op_sel_hi:[1,0,1]
	v_pk_fma_f32 v[152:153], v[152:153], v[80:81], v[162:163] op_sel:[0,1,0] op_sel_hi:[1,1,1]
	v_pk_fma_f32 v[170:171], v[170:171], v[78:79], v[180:181] op_sel:[0,0,0] op_sel_hi:[1,0,1]
	v_pk_fma_f32 v[172:173], v[172:173], v[78:79], v[182:183] op_sel:[0,1,0] op_sel_hi:[1,1,1]
	v_pk_fma_f32 v[174:175], v[174:175], v[80:81], v[184:185] op_sel:[0,0,0] op_sel_hi:[1,0,1]
	v_pk_fma_f32 v[176:177], v[176:177], v[80:81], v[186:187] op_sel:[0,1,0] op_sel_hi:[1,1,1]
	s_waitcnt lgkmcnt(0)
	s_barrier
	s_add_u32 s50, s50, 0x7000
	s_addc_u32 s51, s51, 0
	s_cmp_gt_u32 s3, 13
	s_mov_b32 s33, s3
	s_cbranch_scc1 .LBB0_703

.LBB0_747:
	ds_read2_b32 v[22:23], v63 offset0:192 offset1:196
	ds_read_b128 v[78:81], v62 offset:1536
	ds_read_b128 v[82:85], v62 offset:2048
	ds_read_b128 v[86:89], v62 offset:2560
	ds_read_b128 v[90:93], v62 offset:2816
	ds_read_b128 v[94:97], v62 offset:1280
	ds_read_b128 v[98:101], v62 offset:1024
	ds_read_b128 v[102:105], v62 offset:512
	ds_read_b128 v[106:109], v62
	v_add_u32_e32 v110, 0x800, v63
	ds_read2_b32 v[110:111], v110 offset0:64 offset1:68
	s_waitcnt lgkmcnt(1)
	v_pk_mul_f32 v[154:155], v[146:147], v[98:99] op_sel:[0,0] op_sel_hi:[1,0]
	v_pk_fma_f32 v[154:155], v[148:149], v[98:99], v[154:155] op_sel:[0,1,0] op_sel_hi:[1,1,1]
	v_pk_fma_f32 v[154:155], v[150:151], v[100:101], v[154:155] op_sel:[0,0,0] op_sel_hi:[1,0,1]
	v_pk_fma_f32 v[154:155], v[152:153], v[100:101], v[154:155] op_sel:[0,1,0] op_sel_hi:[1,1,1]
	v_pk_mul_f32 v[178:179], v[170:171], v[98:99] op_sel:[0,0] op_sel_hi:[1,0]
	v_pk_fma_f32 v[178:179], v[172:173], v[98:99], v[178:179] op_sel:[0,1,0] op_sel_hi:[1,1,1]
	v_pk_fma_f32 v[178:179], v[174:175], v[100:101], v[178:179] op_sel:[0,0,0] op_sel_hi:[1,0,1]
	v_pk_fma_f32 v[178:179], v[176:177], v[100:101], v[178:179] op_sel:[0,1,0] op_sel_hi:[1,1,1]
	v_pk_mul_f32 v[156:157], v[22:23], v[102:103] op_sel:[0,0] op_sel_hi:[1,0]
	v_add_f32_dpp v154, v154, v154 quad_perm:[1,0,3,2] row_mask:0xf bank_mask:0xf bound_ctrl:1
	v_add_f32_dpp v155, v155, v155 quad_perm:[1,0,3,2] row_mask:0xf bank_mask:0xf bound_ctrl:1
	v_add_f32_dpp v178, v178, v178 quad_perm:[1,0,3,2] row_mask:0xf bank_mask:0xf bound_ctrl:1
	v_add_f32_dpp v179, v179, v179 quad_perm:[1,0,3,2] row_mask:0xf bank_mask:0xf bound_ctrl:1
	v_add_f32_dpp v154, v154, v154 quad_perm:[2,3,0,1] row_mask:0xf bank_mask:0xf bound_ctrl:1
	v_add_f32_dpp v155, v155, v155 quad_perm:[2,3,0,1] row_mask:0xf bank_mask:0xf bound_ctrl:1
	v_add_f32_dpp v178, v178, v178 quad_perm:[2,3,0,1] row_mask:0xf bank_mask:0xf bound_ctrl:1
	v_add_f32_dpp v179, v179, v179 quad_perm:[2,3,0,1] row_mask:0xf bank_mask:0xf bound_ctrl:1
	v_add_f32_dpp v154, v154, v154 row_half_mirror row_mask:0xf bank_mask:0xf bound_ctrl:1
	v_add_f32_dpp v155, v155, v155 row_half_mirror row_mask:0xf bank_mask:0xf bound_ctrl:1
	v_add_f32_dpp v178, v178, v178 row_half_mirror row_mask:0xf bank_mask:0xf bound_ctrl:1
	v_add_f32_dpp v179, v179, v179 row_half_mirror row_mask:0xf bank_mask:0xf bound_ctrl:1
	v_add_f32_dpp v154, v154, v154 row_mirror row_mask:0xf bank_mask:0xf bound_ctrl:1
	v_add_f32_dpp v155, v155, v155 row_mirror row_mask:0xf bank_mask:0xf bound_ctrl:1
	v_add_f32_dpp v178, v178, v178 row_mirror row_mask:0xf bank_mask:0xf bound_ctrl:1
	v_add_f32_dpp v179, v179, v179 row_mirror row_mask:0xf bank_mask:0xf bound_ctrl:1
	v_pk_mul_f32 v[158:159], v[22:23], v[102:103] op_sel:[0,1] op_sel_hi:[1,1]
	v_pk_mul_f32 v[160:161], v[22:23], v[104:105] op_sel:[0,0] op_sel_hi:[1,0]
	v_pk_mul_f32 v[162:163], v[22:23], v[104:105] op_sel:[0,1] op_sel_hi:[1,1]
	v_pk_fma_f32 v[156:157], v[154:155], v[94:95], v[156:157] op_sel:[0,0,0] op_sel_hi:[1,0,1] neg_lo:[1,0,0] neg_hi:[1,0,0]
	v_pk_fma_f32 v[158:159], v[154:155], v[94:95], v[158:159] op_sel:[0,1,0] op_sel_hi:[1,1,1] neg_lo:[1,0,0] neg_hi:[1,0,0]
	v_pk_fma_f32 v[160:161], v[154:155], v[96:97], v[160:161] op_sel:[0,0,0] op_sel_hi:[1,0,1] neg_lo:[1,0,0] neg_hi:[1,0,0]
	v_pk_fma_f32 v[162:163], v[154:155], v[96:97], v[162:163] op_sel:[0,1,0] op_sel_hi:[1,1,1] neg_lo:[1,0,0] neg_hi:[1,0,0]
	v_pk_mul_f32 v[180:181], v[178:179], v[94:95] op_sel:[0,0] op_sel_hi:[1,0] neg_lo:[1,0] neg_hi:[1,0]
	v_pk_mul_f32 v[182:183], v[178:179], v[94:95] op_sel:[0,1] op_sel_hi:[1,1] neg_lo:[1,0] neg_hi:[1,0]
	v_pk_mul_f32 v[184:185], v[178:179], v[96:97] op_sel:[0,0] op_sel_hi:[1,0] neg_lo:[1,0] neg_hi:[1,0]
	v_pk_mul_f32 v[186:187], v[178:179], v[96:97] op_sel:[0,1] op_sel_hi:[1,1] neg_lo:[1,0] neg_hi:[1,0]
	v_pk_fma_f32 v[146:147], v[146:147], v[106:107], v[156:157] op_sel:[0,0,0] op_sel_hi:[1,0,1]
	v_pk_fma_f32 v[148:149], v[148:149], v[106:107], v[158:159] op_sel:[0,1,0] op_sel_hi:[1,1,1]
	v_pk_fma_f32 v[150:151], v[150:151], v[108:109], v[160:161] op_sel:[0,0,0] op_sel_hi:[1,0,1]
	v_pk_fma_f32 v[152:153], v[152:153], v[108:109], v[162:163] op_sel:[0,1,0] op_sel_hi:[1,1,1]
	v_pk_fma_f32 v[170:171], v[170:171], v[106:107], v[180:181] op_sel:[0,0,0] op_sel_hi:[1,0,1]
	v_pk_fma_f32 v[172:173], v[172:173], v[106:107], v[182:183] op_sel:[0,1,0] op_sel_hi:[1,1,1]
	v_pk_fma_f32 v[174:175], v[174:175], v[108:109], v[184:185] op_sel:[0,0,0] op_sel_hi:[1,0,1]
	v_pk_fma_f32 v[176:177], v[176:177], v[108:109], v[186:187] op_sel:[0,1,0] op_sel_hi:[1,1,1]
	ds_read_b128 v[94:97], v62 offset:3072
	ds_read_b128 v[98:101], v62 offset:3584
	ds_read_b128 v[102:105], v62 offset:4096
	ds_read_b128 v[106:109], v62 offset:4352
	v_add_u32_e32 v22, 0xc00, v63
	ds_read2_b32 v[22:23], v22 offset0:192 offset1:196
	s_waitcnt lgkmcnt(5)
	v_pk_mul_f32 v[154:155], v[146:147], v[86:87] op_sel:[0,0] op_sel_hi:[1,0]
	v_pk_fma_f32 v[154:155], v[148:149], v[86:87], v[154:155] op_sel:[0,1,0] op_sel_hi:[1,1,1]
	v_pk_fma_f32 v[154:155], v[150:151], v[88:89], v[154:155] op_sel:[0,0,0] op_sel_hi:[1,0,1]
	v_pk_fma_f32 v[154:155], v[152:153], v[88:89], v[154:155] op_sel:[0,1,0] op_sel_hi:[1,1,1]
	v_pk_mul_f32 v[178:179], v[170:171], v[86:87] op_sel:[0,0] op_sel_hi:[1,0]
	v_pk_fma_f32 v[178:179], v[172:173], v[86:87], v[178:179] op_sel:[0,1,0] op_sel_hi:[1,1,1]
	v_pk_fma_f32 v[178:179], v[174:175], v[88:89], v[178:179] op_sel:[0,0,0] op_sel_hi:[1,0,1]
	v_pk_fma_f32 v[178:179], v[176:177], v[88:89], v[178:179] op_sel:[0,1,0] op_sel_hi:[1,1,1]
	v_pk_mul_f32 v[156:157], v[110:111], v[82:83] op_sel:[0,0] op_sel_hi:[1,0]
	v_add_f32_dpp v154, v154, v154 quad_perm:[1,0,3,2] row_mask:0xf bank_mask:0xf bound_ctrl:1
	v_add_f32_dpp v155, v155, v155 quad_perm:[1,0,3,2] row_mask:0xf bank_mask:0xf bound_ctrl:1
	v_add_f32_dpp v178, v178, v178 quad_perm:[1,0,3,2] row_mask:0xf bank_mask:0xf bound_ctrl:1
	v_add_f32_dpp v179, v179, v179 quad_perm:[1,0,3,2] row_mask:0xf bank_mask:0xf bound_ctrl:1
	v_add_f32_dpp v154, v154, v154 quad_perm:[2,3,0,1] row_mask:0xf bank_mask:0xf bound_ctrl:1
	v_add_f32_dpp v155, v155, v155 quad_perm:[2,3,0,1] row_mask:0xf bank_mask:0xf bound_ctrl:1
	v_add_f32_dpp v178, v178, v178 quad_perm:[2,3,0,1] row_mask:0xf bank_mask:0xf bound_ctrl:1
	v_add_f32_dpp v179, v179, v179 quad_perm:[2,3,0,1] row_mask:0xf bank_mask:0xf bound_ctrl:1
	v_add_f32_dpp v154, v154, v154 row_half_mirror row_mask:0xf bank_mask:0xf bound_ctrl:1
	v_add_f32_dpp v155, v155, v155 row_half_mirror row_mask:0xf bank_mask:0xf bound_ctrl:1
	v_add_f32_dpp v178, v178, v178 row_half_mirror row_mask:0xf bank_mask:0xf bound_ctrl:1
	v_add_f32_dpp v179, v179, v179 row_half_mirror row_mask:0xf bank_mask:0xf bound_ctrl:1
	v_add_f32_dpp v154, v154, v154 row_mirror row_mask:0xf bank_mask:0xf bound_ctrl:1
	v_add_f32_dpp v155, v155, v155 row_mirror row_mask:0xf bank_mask:0xf bound_ctrl:1
	v_add_f32_dpp v178, v178, v178 row_mirror row_mask:0xf bank_mask:0xf bound_ctrl:1
	v_add_f32_dpp v179, v179, v179 row_mirror row_mask:0xf bank_mask:0xf bound_ctrl:1
	v_pk_mul_f32 v[158:159], v[110:111], v[82:83] op_sel:[0,1] op_sel_hi:[1,1]
	v_pk_mul_f32 v[160:161], v[110:111], v[84:85] op_sel:[0,0] op_sel_hi:[1,0]
	v_pk_mul_f32 v[162:163], v[110:111], v[84:85] op_sel:[0,1] op_sel_hi:[1,1]
	v_pk_fma_f32 v[156:157], v[154:155], v[90:91], v[156:157] op_sel:[0,0,0] op_sel_hi:[1,0,1] neg_lo:[1,0,0] neg_hi:[1,0,0]
	v_pk_fma_f32 v[158:159], v[154:155], v[90:91], v[158:159] op_sel:[0,1,0] op_sel_hi:[1,1,1] neg_lo:[1,0,0] neg_hi:[1,0,0]
	v_pk_fma_f32 v[160:161], v[154:155], v[92:93], v[160:161] op_sel:[0,0,0] op_sel_hi:[1,0,1] neg_lo:[1,0,0] neg_hi:[1,0,0]
	v_pk_fma_f32 v[162:163], v[154:155], v[92:93], v[162:163] op_sel:[0,1,0] op_sel_hi:[1,1,1] neg_lo:[1,0,0] neg_hi:[1,0,0]
	v_pk_mul_f32 v[180:181], v[178:179], v[90:91] op_sel:[0,0] op_sel_hi:[1,0] neg_lo:[1,0] neg_hi:[1,0]
	v_pk_mul_f32 v[182:183], v[178:179], v[90:91] op_sel:[0,1] op_sel_hi:[1,1] neg_lo:[1,0] neg_hi:[1,0]
	v_pk_mul_f32 v[184:185], v[178:179], v[92:93] op_sel:[0,0] op_sel_hi:[1,0] neg_lo:[1,0] neg_hi:[1,0]
	v_pk_mul_f32 v[186:187], v[178:179], v[92:93] op_sel:[0,1] op_sel_hi:[1,1] neg_lo:[1,0] neg_hi:[1,0]
	v_pk_fma_f32 v[146:147], v[146:147], v[78:79], v[156:157] op_sel:[0,0,0] op_sel_hi:[1,0,1]
	v_pk_fma_f32 v[148:149], v[148:149], v[78:79], v[158:159] op_sel:[0,1,0] op_sel_hi:[1,1,1]
	v_pk_fma_f32 v[150:151], v[150:151], v[80:81], v[160:161] op_sel:[0,0,0] op_sel_hi:[1,0,1]
	v_pk_fma_f32 v[152:153], v[152:153], v[80:81], v[162:163] op_sel:[0,1,0] op_sel_hi:[1,1,1]
	v_pk_fma_f32 v[170:171], v[170:171], v[78:79], v[180:181] op_sel:[0,0,0] op_sel_hi:[1,0,1]
	v_pk_fma_f32 v[172:173], v[172:173], v[78:79], v[182:183] op_sel:[0,1,0] op_sel_hi:[1,1,1]
	v_pk_fma_f32 v[174:175], v[174:175], v[80:81], v[184:185] op_sel:[0,0,0] op_sel_hi:[1,0,1]
	v_pk_fma_f32 v[176:177], v[176:177], v[80:81], v[186:187] op_sel:[0,1,0] op_sel_hi:[1,1,1]
	ds_read_b128 v[78:81], v62 offset:4608
	ds_read_b128 v[82:85], v62 offset:5120
	ds_read_b128 v[86:89], v62 offset:5632
	ds_read_b128 v[90:93], v62 offset:5888
	v_add_u32_e32 v110, 0x1400, v63
	ds_read2_b32 v[110:111], v110 offset0:64 offset1:68
	s_waitcnt lgkmcnt(5)
	v_pk_mul_f32 v[154:155], v[146:147], v[102:103] op_sel:[0,0] op_sel_hi:[1,0]
	v_pk_fma_f32 v[154:155], v[148:149], v[102:103], v[154:155] op_sel:[0,1,0] op_sel_hi:[1,1,1]
	v_pk_fma_f32 v[154:155], v[150:151], v[104:105], v[154:155] op_sel:[0,0,0] op_sel_hi:[1,0,1]
	v_pk_fma_f32 v[154:155], v[152:153], v[104:105], v[154:155] op_sel:[0,1,0] op_sel_hi:[1,1,1]
	v_pk_mul_f32 v[178:179], v[170:171], v[102:103] op_sel:[0,0] op_sel_hi:[1,0]
	v_pk_fma_f32 v[178:179], v[172:173], v[102:103], v[178:179] op_sel:[0,1,0] op_sel_hi:[1,1,1]
	v_pk_fma_f32 v[178:179], v[174:175], v[104:105], v[178:179] op_sel:[0,0,0] op_sel_hi:[1,0,1]
	v_pk_fma_f32 v[178:179], v[176:177], v[104:105], v[178:179] op_sel:[0,1,0] op_sel_hi:[1,1,1]
	v_pk_mul_f32 v[156:157], v[22:23], v[98:99] op_sel:[0,0] op_sel_hi:[1,0]
	v_add_f32_dpp v154, v154, v154 quad_perm:[1,0,3,2] row_mask:0xf bank_mask:0xf bound_ctrl:1
	v_add_f32_dpp v155, v155, v155 quad_perm:[1,0,3,2] row_mask:0xf bank_mask:0xf bound_ctrl:1
	v_add_f32_dpp v178, v178, v178 quad_perm:[1,0,3,2] row_mask:0xf bank_mask:0xf bound_ctrl:1
	v_add_f32_dpp v179, v179, v179 quad_perm:[1,0,3,2] row_mask:0xf bank_mask:0xf bound_ctrl:1
	v_add_f32_dpp v154, v154, v154 quad_perm:[2,3,0,1] row_mask:0xf bank_mask:0xf bound_ctrl:1
	v_add_f32_dpp v155, v155, v155 quad_perm:[2,3,0,1] row_mask:0xf bank_mask:0xf bound_ctrl:1
	v_add_f32_dpp v178, v178, v178 quad_perm:[2,3,0,1] row_mask:0xf bank_mask:0xf bound_ctrl:1
	v_add_f32_dpp v179, v179, v179 quad_perm:[2,3,0,1] row_mask:0xf bank_mask:0xf bound_ctrl:1
	v_add_f32_dpp v154, v154, v154 row_half_mirror row_mask:0xf bank_mask:0xf bound_ctrl:1
	v_add_f32_dpp v155, v155, v155 row_half_mirror row_mask:0xf bank_mask:0xf bound_ctrl:1
	v_add_f32_dpp v178, v178, v178 row_half_mirror row_mask:0xf bank_mask:0xf bound_ctrl:1
	v_add_f32_dpp v179, v179, v179 row_half_mirror row_mask:0xf bank_mask:0xf bound_ctrl:1
	v_add_f32_dpp v154, v154, v154 row_mirror row_mask:0xf bank_mask:0xf bound_ctrl:1
	v_add_f32_dpp v155, v155, v155 row_mirror row_mask:0xf bank_mask:0xf bound_ctrl:1
	v_add_f32_dpp v178, v178, v178 row_mirror row_mask:0xf bank_mask:0xf bound_ctrl:1
	v_add_f32_dpp v179, v179, v179 row_mirror row_mask:0xf bank_mask:0xf bound_ctrl:1
	v_pk_mul_f32 v[158:159], v[22:23], v[98:99] op_sel:[0,1] op_sel_hi:[1,1]
	v_pk_mul_f32 v[160:161], v[22:23], v[100:101] op_sel:[0,0] op_sel_hi:[1,0]
	v_pk_mul_f32 v[162:163], v[22:23], v[100:101] op_sel:[0,1] op_sel_hi:[1,1]
	v_pk_fma_f32 v[156:157], v[154:155], v[106:107], v[156:157] op_sel:[0,0,0] op_sel_hi:[1,0,1] neg_lo:[1,0,0] neg_hi:[1,0,0]
	v_pk_fma_f32 v[158:159], v[154:155], v[106:107], v[158:159] op_sel:[0,1,0] op_sel_hi:[1,1,1] neg_lo:[1,0,0] neg_hi:[1,0,0]
	v_pk_fma_f32 v[160:161], v[154:155], v[108:109], v[160:161] op_sel:[0,0,0] op_sel_hi:[1,0,1] neg_lo:[1,0,0] neg_hi:[1,0,0]
	v_pk_fma_f32 v[162:163], v[154:155], v[108:109], v[162:163] op_sel:[0,1,0] op_sel_hi:[1,1,1] neg_lo:[1,0,0] neg_hi:[1,0,0]
	v_pk_mul_f32 v[180:181], v[178:179], v[106:107] op_sel:[0,0] op_sel_hi:[1,0] neg_lo:[1,0] neg_hi:[1,0]
	v_pk_mul_f32 v[182:183], v[178:179], v[106:107] op_sel:[0,1] op_sel_hi:[1,1] neg_lo:[1,0] neg_hi:[1,0]
	v_pk_mul_f32 v[184:185], v[178:179], v[108:109] op_sel:[0,0] op_sel_hi:[1,0] neg_lo:[1,0] neg_hi:[1,0]
	v_pk_mul_f32 v[186:187], v[178:179], v[108:109] op_sel:[0,1] op_sel_hi:[1,1] neg_lo:[1,0] neg_hi:[1,0]
	v_pk_fma_f32 v[146:147], v[146:147], v[94:95], v[156:157] op_sel:[0,0,0] op_sel_hi:[1,0,1]
	v_pk_fma_f32 v[148:149], v[148:149], v[94:95], v[158:159] op_sel:[0,1,0] op_sel_hi:[1,1,1]
	v_pk_fma_f32 v[150:151], v[150:151], v[96:97], v[160:161] op_sel:[0,0,0] op_sel_hi:[1,0,1]
	v_pk_fma_f32 v[152:153], v[152:153], v[96:97], v[162:163] op_sel:[0,1,0] op_sel_hi:[1,1,1]
	v_pk_fma_f32 v[170:171], v[170:171], v[94:95], v[180:181] op_sel:[0,0,0] op_sel_hi:[1,0,1]
	v_pk_fma_f32 v[172:173], v[172:173], v[94:95], v[182:183] op_sel:[0,1,0] op_sel_hi:[1,1,1]
	v_pk_fma_f32 v[174:175], v[174:175], v[96:97], v[184:185] op_sel:[0,0,0] op_sel_hi:[1,0,1]
	v_pk_fma_f32 v[176:177], v[176:177], v[96:97], v[186:187] op_sel:[0,1,0] op_sel_hi:[1,1,1]
	ds_read_b128 v[94:97], v62 offset:6144
	ds_read_b128 v[98:101], v62 offset:6656
	ds_read_b128 v[102:105], v62 offset:7168
	ds_read_b128 v[106:109], v62 offset:7424
	v_add_u32_e32 v22, 0x1800, v63
	ds_read2_b32 v[22:23], v22 offset0:192 offset1:196
	s_waitcnt lgkmcnt(5)
	v_pk_mul_f32 v[154:155], v[146:147], v[86:87] op_sel:[0,0] op_sel_hi:[1,0]
	v_pk_fma_f32 v[154:155], v[148:149], v[86:87], v[154:155] op_sel:[0,1,0] op_sel_hi:[1,1,1]
	v_pk_fma_f32 v[154:155], v[150:151], v[88:89], v[154:155] op_sel:[0,0,0] op_sel_hi:[1,0,1]
	v_pk_fma_f32 v[154:155], v[152:153], v[88:89], v[154:155] op_sel:[0,1,0] op_sel_hi:[1,1,1]
	v_pk_mul_f32 v[178:179], v[170:171], v[86:87] op_sel:[0,0] op_sel_hi:[1,0]
	v_pk_fma_f32 v[178:179], v[172:173], v[86:87], v[178:179] op_sel:[0,1,0] op_sel_hi:[1,1,1]
	v_pk_fma_f32 v[178:179], v[174:175], v[88:89], v[178:179] op_sel:[0,0,0] op_sel_hi:[1,0,1]
	v_pk_fma_f32 v[178:179], v[176:177], v[88:89], v[178:179] op_sel:[0,1,0] op_sel_hi:[1,1,1]
	v_pk_mul_f32 v[156:157], v[110:111], v[82:83] op_sel:[0,0] op_sel_hi:[1,0]
	v_add_f32_dpp v154, v154, v154 quad_perm:[1,0,3,2] row_mask:0xf bank_mask:0xf bound_ctrl:1
	v_add_f32_dpp v155, v155, v155 quad_perm:[1,0,3,2] row_mask:0xf bank_mask:0xf bound_ctrl:1
	v_add_f32_dpp v178, v178, v178 quad_perm:[1,0,3,2] row_mask:0xf bank_mask:0xf bound_ctrl:1
	v_add_f32_dpp v179, v179, v179 quad_perm:[1,0,3,2] row_mask:0xf bank_mask:0xf bound_ctrl:1
	v_add_f32_dpp v154, v154, v154 quad_perm:[2,3,0,1] row_mask:0xf bank_mask:0xf bound_ctrl:1
	v_add_f32_dpp v155, v155, v155 quad_perm:[2,3,0,1] row_mask:0xf bank_mask:0xf bound_ctrl:1
	v_add_f32_dpp v178, v178, v178 quad_perm:[2,3,0,1] row_mask:0xf bank_mask:0xf bound_ctrl:1
	v_add_f32_dpp v179, v179, v179 quad_perm:[2,3,0,1] row_mask:0xf bank_mask:0xf bound_ctrl:1
	v_add_f32_dpp v154, v154, v154 row_half_mirror row_mask:0xf bank_mask:0xf bound_ctrl:1
	v_add_f32_dpp v155, v155, v155 row_half_mirror row_mask:0xf bank_mask:0xf bound_ctrl:1
	v_add_f32_dpp v178, v178, v178 row_half_mirror row_mask:0xf bank_mask:0xf bound_ctrl:1
	v_add_f32_dpp v179, v179, v179 row_half_mirror row_mask:0xf bank_mask:0xf bound_ctrl:1
	v_add_f32_dpp v154, v154, v154 row_mirror row_mask:0xf bank_mask:0xf bound_ctrl:1
	v_add_f32_dpp v155, v155, v155 row_mirror row_mask:0xf bank_mask:0xf bound_ctrl:1
	v_add_f32_dpp v178, v178, v178 row_mirror row_mask:0xf bank_mask:0xf bound_ctrl:1
	v_add_f32_dpp v179, v179, v179 row_mirror row_mask:0xf bank_mask:0xf bound_ctrl:1
	v_pk_mul_f32 v[158:159], v[110:111], v[82:83] op_sel:[0,1] op_sel_hi:[1,1]
	v_pk_mul_f32 v[160:161], v[110:111], v[84:85] op_sel:[0,0] op_sel_hi:[1,0]
	v_pk_mul_f32 v[162:163], v[110:111], v[84:85] op_sel:[0,1] op_sel_hi:[1,1]
	v_pk_fma_f32 v[156:157], v[154:155], v[90:91], v[156:157] op_sel:[0,0,0] op_sel_hi:[1,0,1] neg_lo:[1,0,0] neg_hi:[1,0,0]
	v_pk_fma_f32 v[158:159], v[154:155], v[90:91], v[158:159] op_sel:[0,1,0] op_sel_hi:[1,1,1] neg_lo:[1,0,0] neg_hi:[1,0,0]
	v_pk_fma_f32 v[160:161], v[154:155], v[92:93], v[160:161] op_sel:[0,0,0] op_sel_hi:[1,0,1] neg_lo:[1,0,0] neg_hi:[1,0,0]
	v_pk_fma_f32 v[162:163], v[154:155], v[92:93], v[162:163] op_sel:[0,1,0] op_sel_hi:[1,1,1] neg_lo:[1,0,0] neg_hi:[1,0,0]
	v_pk_mul_f32 v[180:181], v[178:179], v[90:91] op_sel:[0,0] op_sel_hi:[1,0] neg_lo:[1,0] neg_hi:[1,0]
	v_pk_mul_f32 v[182:183], v[178:179], v[90:91] op_sel:[0,1] op_sel_hi:[1,1] neg_lo:[1,0] neg_hi:[1,0]
	v_pk_mul_f32 v[184:185], v[178:179], v[92:93] op_sel:[0,0] op_sel_hi:[1,0] neg_lo:[1,0] neg_hi:[1,0]
	v_pk_mul_f32 v[186:187], v[178:179], v[92:93] op_sel:[0,1] op_sel_hi:[1,1] neg_lo:[1,0] neg_hi:[1,0]
	v_pk_fma_f32 v[146:147], v[146:147], v[78:79], v[156:157] op_sel:[0,0,0] op_sel_hi:[1,0,1]
	v_pk_fma_f32 v[148:149], v[148:149], v[78:79], v[158:159] op_sel:[0,1,0] op_sel_hi:[1,1,1]
	v_pk_fma_f32 v[150:151], v[150:151], v[80:81], v[160:161] op_sel:[0,0,0] op_sel_hi:[1,0,1]
	v_pk_fma_f32 v[152:153], v[152:153], v[80:81], v[162:163] op_sel:[0,1,0] op_sel_hi:[1,1,1]
	v_pk_fma_f32 v[170:171], v[170:171], v[78:79], v[180:181] op_sel:[0,0,0] op_sel_hi:[1,0,1]
	v_pk_fma_f32 v[172:173], v[172:173], v[78:79], v[182:183] op_sel:[0,1,0] op_sel_hi:[1,1,1]
	v_pk_fma_f32 v[174:175], v[174:175], v[80:81], v[184:185] op_sel:[0,0,0] op_sel_hi:[1,0,1]
	v_pk_fma_f32 v[176:177], v[176:177], v[80:81], v[186:187] op_sel:[0,1,0] op_sel_hi:[1,1,1]
	ds_read_b128 v[78:81], v62 offset:7680
	ds_read_b128 v[82:85], v62 offset:8192
	ds_read_b128 v[86:89], v62 offset:8704
	ds_read_b128 v[90:93], v62 offset:8960
	v_add_u32_e32 v110, 0x2000, v63
	ds_read2_b32 v[110:111], v110 offset0:64 offset1:68
	s_waitcnt lgkmcnt(5)
	v_pk_mul_f32 v[154:155], v[146:147], v[102:103] op_sel:[0,0] op_sel_hi:[1,0]
	v_pk_fma_f32 v[154:155], v[148:149], v[102:103], v[154:155] op_sel:[0,1,0] op_sel_hi:[1,1,1]
	v_pk_fma_f32 v[154:155], v[150:151], v[104:105], v[154:155] op_sel:[0,0,0] op_sel_hi:[1,0,1]
	v_pk_fma_f32 v[154:155], v[152:153], v[104:105], v[154:155] op_sel:[0,1,0] op_sel_hi:[1,1,1]
	v_pk_mul_f32 v[178:179], v[170:171], v[102:103] op_sel:[0,0] op_sel_hi:[1,0]
	v_pk_fma_f32 v[178:179], v[172:173], v[102:103], v[178:179] op_sel:[0,1,0] op_sel_hi:[1,1,1]
	v_pk_fma_f32 v[178:179], v[174:175], v[104:105], v[178:179] op_sel:[0,0,0] op_sel_hi:[1,0,1]
	v_pk_fma_f32 v[178:179], v[176:177], v[104:105], v[178:179] op_sel:[0,1,0] op_sel_hi:[1,1,1]
	v_pk_mul_f32 v[156:157], v[22:23], v[98:99] op_sel:[0,0] op_sel_hi:[1,0]
	v_add_f32_dpp v154, v154, v154 quad_perm:[1,0,3,2] row_mask:0xf bank_mask:0xf bound_ctrl:1
	v_add_f32_dpp v155, v155, v155 quad_perm:[1,0,3,2] row_mask:0xf bank_mask:0xf bound_ctrl:1
	v_add_f32_dpp v178, v178, v178 quad_perm:[1,0,3,2] row_mask:0xf bank_mask:0xf bound_ctrl:1
	v_add_f32_dpp v179, v179, v179 quad_perm:[1,0,3,2] row_mask:0xf bank_mask:0xf bound_ctrl:1
	v_add_f32_dpp v154, v154, v154 quad_perm:[2,3,0,1] row_mask:0xf bank_mask:0xf bound_ctrl:1
	v_add_f32_dpp v155, v155, v155 quad_perm:[2,3,0,1] row_mask:0xf bank_mask:0xf bound_ctrl:1
	v_add_f32_dpp v178, v178, v178 quad_perm:[2,3,0,1] row_mask:0xf bank_mask:0xf bound_ctrl:1
	v_add_f32_dpp v179, v179, v179 quad_perm:[2,3,0,1] row_mask:0xf bank_mask:0xf bound_ctrl:1
	v_add_f32_dpp v154, v154, v154 row_half_mirror row_mask:0xf bank_mask:0xf bound_ctrl:1
	v_add_f32_dpp v155, v155, v155 row_half_mirror row_mask:0xf bank_mask:0xf bound_ctrl:1
	v_add_f32_dpp v178, v178, v178 row_half_mirror row_mask:0xf bank_mask:0xf bound_ctrl:1
	v_add_f32_dpp v179, v179, v179 row_half_mirror row_mask:0xf bank_mask:0xf bound_ctrl:1
	v_add_f32_dpp v154, v154, v154 row_mirror row_mask:0xf bank_mask:0xf bound_ctrl:1
	v_add_f32_dpp v155, v155, v155 row_mirror row_mask:0xf bank_mask:0xf bound_ctrl:1
	v_add_f32_dpp v178, v178, v178 row_mirror row_mask:0xf bank_mask:0xf bound_ctrl:1
	v_add_f32_dpp v179, v179, v179 row_mirror row_mask:0xf bank_mask:0xf bound_ctrl:1
	v_pk_mul_f32 v[158:159], v[22:23], v[98:99] op_sel:[0,1] op_sel_hi:[1,1]
	v_pk_mul_f32 v[160:161], v[22:23], v[100:101] op_sel:[0,0] op_sel_hi:[1,0]
	v_pk_mul_f32 v[162:163], v[22:23], v[100:101] op_sel:[0,1] op_sel_hi:[1,1]
	v_pk_fma_f32 v[156:157], v[154:155], v[106:107], v[156:157] op_sel:[0,0,0] op_sel_hi:[1,0,1] neg_lo:[1,0,0] neg_hi:[1,0,0]
	v_pk_fma_f32 v[158:159], v[154:155], v[106:107], v[158:159] op_sel:[0,1,0] op_sel_hi:[1,1,1] neg_lo:[1,0,0] neg_hi:[1,0,0]
	v_pk_fma_f32 v[160:161], v[154:155], v[108:109], v[160:161] op_sel:[0,0,0] op_sel_hi:[1,0,1] neg_lo:[1,0,0] neg_hi:[1,0,0]
	v_pk_fma_f32 v[162:163], v[154:155], v[108:109], v[162:163] op_sel:[0,1,0] op_sel_hi:[1,1,1] neg_lo:[1,0,0] neg_hi:[1,0,0]
	v_pk_mul_f32 v[180:181], v[178:179], v[106:107] op_sel:[0,0] op_sel_hi:[1,0] neg_lo:[1,0] neg_hi:[1,0]
	v_pk_mul_f32 v[182:183], v[178:179], v[106:107] op_sel:[0,1] op_sel_hi:[1,1] neg_lo:[1,0] neg_hi:[1,0]
	v_pk_mul_f32 v[184:185], v[178:179], v[108:109] op_sel:[0,0] op_sel_hi:[1,0] neg_lo:[1,0] neg_hi:[1,0]
	v_pk_mul_f32 v[186:187], v[178:179], v[108:109] op_sel:[0,1] op_sel_hi:[1,1] neg_lo:[1,0] neg_hi:[1,0]
	v_pk_fma_f32 v[146:147], v[146:147], v[94:95], v[156:157] op_sel:[0,0,0] op_sel_hi:[1,0,1]
	v_pk_fma_f32 v[148:149], v[148:149], v[94:95], v[158:159] op_sel:[0,1,0] op_sel_hi:[1,1,1]
	v_pk_fma_f32 v[150:151], v[150:151], v[96:97], v[160:161] op_sel:[0,0,0] op_sel_hi:[1,0,1]
	v_pk_fma_f32 v[152:153], v[152:153], v[96:97], v[162:163] op_sel:[0,1,0] op_sel_hi:[1,1,1]
	v_pk_fma_f32 v[170:171], v[170:171], v[94:95], v[180:181] op_sel:[0,0,0] op_sel_hi:[1,0,1]
	v_pk_fma_f32 v[172:173], v[172:173], v[94:95], v[182:183] op_sel:[0,1,0] op_sel_hi:[1,1,1]
	v_pk_fma_f32 v[174:175], v[174:175], v[96:97], v[184:185] op_sel:[0,0,0] op_sel_hi:[1,0,1]
	v_pk_fma_f32 v[176:177], v[176:177], v[96:97], v[186:187] op_sel:[0,1,0] op_sel_hi:[1,1,1]
	ds_read_b128 v[94:97], v62 offset:9216
	ds_read_b128 v[98:101], v62 offset:9728
	ds_read_b128 v[102:105], v62 offset:10240
	ds_read_b128 v[106:109], v62 offset:10496
	v_add_u32_e32 v22, 0x2400, v63
	ds_read2_b32 v[22:23], v22 offset0:192 offset1:196
	s_waitcnt lgkmcnt(5)
	v_pk_mul_f32 v[154:155], v[146:147], v[86:87] op_sel:[0,0] op_sel_hi:[1,0]
	v_pk_fma_f32 v[154:155], v[148:149], v[86:87], v[154:155] op_sel:[0,1,0] op_sel_hi:[1,1,1]
	v_pk_fma_f32 v[154:155], v[150:151], v[88:89], v[154:155] op_sel:[0,0,0] op_sel_hi:[1,0,1]
	v_pk_fma_f32 v[154:155], v[152:153], v[88:89], v[154:155] op_sel:[0,1,0] op_sel_hi:[1,1,1]
	v_pk_mul_f32 v[178:179], v[170:171], v[86:87] op_sel:[0,0] op_sel_hi:[1,0]
	v_pk_fma_f32 v[178:179], v[172:173], v[86:87], v[178:179] op_sel:[0,1,0] op_sel_hi:[1,1,1]
	v_pk_fma_f32 v[178:179], v[174:175], v[88:89], v[178:179] op_sel:[0,0,0] op_sel_hi:[1,0,1]
	v_pk_fma_f32 v[178:179], v[176:177], v[88:89], v[178:179] op_sel:[0,1,0] op_sel_hi:[1,1,1]
	v_pk_mul_f32 v[156:157], v[110:111], v[82:83] op_sel:[0,0] op_sel_hi:[1,0]
	v_add_f32_dpp v154, v154, v154 quad_perm:[1,0,3,2] row_mask:0xf bank_mask:0xf bound_ctrl:1
	v_add_f32_dpp v155, v155, v155 quad_perm:[1,0,3,2] row_mask:0xf bank_mask:0xf bound_ctrl:1
	v_add_f32_dpp v178, v178, v178 quad_perm:[1,0,3,2] row_mask:0xf bank_mask:0xf bound_ctrl:1
	v_add_f32_dpp v179, v179, v179 quad_perm:[1,0,3,2] row_mask:0xf bank_mask:0xf bound_ctrl:1
	v_add_f32_dpp v154, v154, v154 quad_perm:[2,3,0,1] row_mask:0xf bank_mask:0xf bound_ctrl:1
	v_add_f32_dpp v155, v155, v155 quad_perm:[2,3,0,1] row_mask:0xf bank_mask:0xf bound_ctrl:1
	v_add_f32_dpp v178, v178, v178 quad_perm:[2,3,0,1] row_mask:0xf bank_mask:0xf bound_ctrl:1
	v_add_f32_dpp v179, v179, v179 quad_perm:[2,3,0,1] row_mask:0xf bank_mask:0xf bound_ctrl:1
	v_add_f32_dpp v154, v154, v154 row_half_mirror row_mask:0xf bank_mask:0xf bound_ctrl:1
	v_add_f32_dpp v155, v155, v155 row_half_mirror row_mask:0xf bank_mask:0xf bound_ctrl:1
	v_add_f32_dpp v178, v178, v178 row_half_mirror row_mask:0xf bank_mask:0xf bound_ctrl:1
	v_add_f32_dpp v179, v179, v179 row_half_mirror row_mask:0xf bank_mask:0xf bound_ctrl:1
	v_add_f32_dpp v154, v154, v154 row_mirror row_mask:0xf bank_mask:0xf bound_ctrl:1
	v_add_f32_dpp v155, v155, v155 row_mirror row_mask:0xf bank_mask:0xf bound_ctrl:1
	v_add_f32_dpp v178, v178, v178 row_mirror row_mask:0xf bank_mask:0xf bound_ctrl:1
	v_add_f32_dpp v179, v179, v179 row_mirror row_mask:0xf bank_mask:0xf bound_ctrl:1
	v_pk_mul_f32 v[158:159], v[110:111], v[82:83] op_sel:[0,1] op_sel_hi:[1,1]
	v_pk_mul_f32 v[160:161], v[110:111], v[84:85] op_sel:[0,0] op_sel_hi:[1,0]
	v_pk_mul_f32 v[162:163], v[110:111], v[84:85] op_sel:[0,1] op_sel_hi:[1,1]
	v_pk_fma_f32 v[156:157], v[154:155], v[90:91], v[156:157] op_sel:[0,0,0] op_sel_hi:[1,0,1] neg_lo:[1,0,0] neg_hi:[1,0,0]
	v_pk_fma_f32 v[158:159], v[154:155], v[90:91], v[158:159] op_sel:[0,1,0] op_sel_hi:[1,1,1] neg_lo:[1,0,0] neg_hi:[1,0,0]
	v_pk_fma_f32 v[160:161], v[154:155], v[92:93], v[160:161] op_sel:[0,0,0] op_sel_hi:[1,0,1] neg_lo:[1,0,0] neg_hi:[1,0,0]
	v_pk_fma_f32 v[162:163], v[154:155], v[92:93], v[162:163] op_sel:[0,1,0] op_sel_hi:[1,1,1] neg_lo:[1,0,0] neg_hi:[1,0,0]
	v_pk_mul_f32 v[180:181], v[178:179], v[90:91] op_sel:[0,0] op_sel_hi:[1,0] neg_lo:[1,0] neg_hi:[1,0]
	v_pk_mul_f32 v[182:183], v[178:179], v[90:91] op_sel:[0,1] op_sel_hi:[1,1] neg_lo:[1,0] neg_hi:[1,0]
	v_pk_mul_f32 v[184:185], v[178:179], v[92:93] op_sel:[0,0] op_sel_hi:[1,0] neg_lo:[1,0] neg_hi:[1,0]
	v_pk_mul_f32 v[186:187], v[178:179], v[92:93] op_sel:[0,1] op_sel_hi:[1,1] neg_lo:[1,0] neg_hi:[1,0]
	v_pk_fma_f32 v[146:147], v[146:147], v[78:79], v[156:157] op_sel:[0,0,0] op_sel_hi:[1,0,1]
	v_pk_fma_f32 v[148:149], v[148:149], v[78:79], v[158:159] op_sel:[0,1,0] op_sel_hi:[1,1,1]
	v_pk_fma_f32 v[150:151], v[150:151], v[80:81], v[160:161] op_sel:[0,0,0] op_sel_hi:[1,0,1]
	v_pk_fma_f32 v[152:153], v[152:153], v[80:81], v[162:163] op_sel:[0,1,0] op_sel_hi:[1,1,1]
	v_pk_fma_f32 v[170:171], v[170:171], v[78:79], v[180:181] op_sel:[0,0,0] op_sel_hi:[1,0,1]
	v_pk_fma_f32 v[172:173], v[172:173], v[78:79], v[182:183] op_sel:[0,1,0] op_sel_hi:[1,1,1]
	v_pk_fma_f32 v[174:175], v[174:175], v[80:81], v[184:185] op_sel:[0,0,0] op_sel_hi:[1,0,1]
	v_pk_fma_f32 v[176:177], v[176:177], v[80:81], v[186:187] op_sel:[0,1,0] op_sel_hi:[1,1,1]
	ds_read_b128 v[78:81], v62 offset:10752
	ds_read_b128 v[82:85], v62 offset:11264
	ds_read_b128 v[86:89], v62 offset:11776
	ds_read_b128 v[90:93], v62 offset:12032
	v_add_u32_e32 v110, 0x2c00, v63
	ds_read2_b32 v[110:111], v110 offset0:64 offset1:68
	s_waitcnt lgkmcnt(5)
	v_pk_mul_f32 v[154:155], v[146:147], v[102:103] op_sel:[0,0] op_sel_hi:[1,0]
	v_pk_fma_f32 v[154:155], v[148:149], v[102:103], v[154:155] op_sel:[0,1,0] op_sel_hi:[1,1,1]
	v_pk_fma_f32 v[154:155], v[150:151], v[104:105], v[154:155] op_sel:[0,0,0] op_sel_hi:[1,0,1]
	v_pk_fma_f32 v[154:155], v[152:153], v[104:105], v[154:155] op_sel:[0,1,0] op_sel_hi:[1,1,1]
	v_pk_mul_f32 v[178:179], v[170:171], v[102:103] op_sel:[0,0] op_sel_hi:[1,0]
	v_pk_fma_f32 v[178:179], v[172:173], v[102:103], v[178:179] op_sel:[0,1,0] op_sel_hi:[1,1,1]
	v_pk_fma_f32 v[178:179], v[174:175], v[104:105], v[178:179] op_sel:[0,0,0] op_sel_hi:[1,0,1]
	v_pk_fma_f32 v[178:179], v[176:177], v[104:105], v[178:179] op_sel:[0,1,0] op_sel_hi:[1,1,1]
	v_pk_mul_f32 v[156:157], v[22:23], v[98:99] op_sel:[0,0] op_sel_hi:[1,0]
	v_add_f32_dpp v154, v154, v154 quad_perm:[1,0,3,2] row_mask:0xf bank_mask:0xf bound_ctrl:1
	v_add_f32_dpp v155, v155, v155 quad_perm:[1,0,3,2] row_mask:0xf bank_mask:0xf bound_ctrl:1
	v_add_f32_dpp v178, v178, v178 quad_perm:[1,0,3,2] row_mask:0xf bank_mask:0xf bound_ctrl:1
	v_add_f32_dpp v179, v179, v179 quad_perm:[1,0,3,2] row_mask:0xf bank_mask:0xf bound_ctrl:1
	v_add_f32_dpp v154, v154, v154 quad_perm:[2,3,0,1] row_mask:0xf bank_mask:0xf bound_ctrl:1
	v_add_f32_dpp v155, v155, v155 quad_perm:[2,3,0,1] row_mask:0xf bank_mask:0xf bound_ctrl:1
	v_add_f32_dpp v178, v178, v178 quad_perm:[2,3,0,1] row_mask:0xf bank_mask:0xf bound_ctrl:1
	v_add_f32_dpp v179, v179, v179 quad_perm:[2,3,0,1] row_mask:0xf bank_mask:0xf bound_ctrl:1
	v_add_f32_dpp v154, v154, v154 row_half_mirror row_mask:0xf bank_mask:0xf bound_ctrl:1
	v_add_f32_dpp v155, v155, v155 row_half_mirror row_mask:0xf bank_mask:0xf bound_ctrl:1
	v_add_f32_dpp v178, v178, v178 row_half_mirror row_mask:0xf bank_mask:0xf bound_ctrl:1
	v_add_f32_dpp v179, v179, v179 row_half_mirror row_mask:0xf bank_mask:0xf bound_ctrl:1
	v_add_f32_dpp v154, v154, v154 row_mirror row_mask:0xf bank_mask:0xf bound_ctrl:1
	v_add_f32_dpp v155, v155, v155 row_mirror row_mask:0xf bank_mask:0xf bound_ctrl:1
	v_add_f32_dpp v178, v178, v178 row_mirror row_mask:0xf bank_mask:0xf bound_ctrl:1
	v_add_f32_dpp v179, v179, v179 row_mirror row_mask:0xf bank_mask:0xf bound_ctrl:1
	v_pk_mul_f32 v[158:159], v[22:23], v[98:99] op_sel:[0,1] op_sel_hi:[1,1]
	v_pk_mul_f32 v[160:161], v[22:23], v[100:101] op_sel:[0,0] op_sel_hi:[1,0]
	v_pk_mul_f32 v[162:163], v[22:23], v[100:101] op_sel:[0,1] op_sel_hi:[1,1]
	v_pk_fma_f32 v[156:157], v[154:155], v[106:107], v[156:157] op_sel:[0,0,0] op_sel_hi:[1,0,1] neg_lo:[1,0,0] neg_hi:[1,0,0]
	v_pk_fma_f32 v[158:159], v[154:155], v[106:107], v[158:159] op_sel:[0,1,0] op_sel_hi:[1,1,1] neg_lo:[1,0,0] neg_hi:[1,0,0]
	v_pk_fma_f32 v[160:161], v[154:155], v[108:109], v[160:161] op_sel:[0,0,0] op_sel_hi:[1,0,1] neg_lo:[1,0,0] neg_hi:[1,0,0]
	v_pk_fma_f32 v[162:163], v[154:155], v[108:109], v[162:163] op_sel:[0,1,0] op_sel_hi:[1,1,1] neg_lo:[1,0,0] neg_hi:[1,0,0]
	v_pk_mul_f32 v[180:181], v[178:179], v[106:107] op_sel:[0,0] op_sel_hi:[1,0] neg_lo:[1,0] neg_hi:[1,0]
	v_pk_mul_f32 v[182:183], v[178:179], v[106:107] op_sel:[0,1] op_sel_hi:[1,1] neg_lo:[1,0] neg_hi:[1,0]
	v_pk_mul_f32 v[184:185], v[178:179], v[108:109] op_sel:[0,0] op_sel_hi:[1,0] neg_lo:[1,0] neg_hi:[1,0]
	v_pk_mul_f32 v[186:187], v[178:179], v[108:109] op_sel:[0,1] op_sel_hi:[1,1] neg_lo:[1,0] neg_hi:[1,0]
	v_pk_fma_f32 v[146:147], v[146:147], v[94:95], v[156:157] op_sel:[0,0,0] op_sel_hi:[1,0,1]
	v_pk_fma_f32 v[148:149], v[148:149], v[94:95], v[158:159] op_sel:[0,1,0] op_sel_hi:[1,1,1]
	v_pk_fma_f32 v[150:151], v[150:151], v[96:97], v[160:161] op_sel:[0,0,0] op_sel_hi:[1,0,1]
	v_pk_fma_f32 v[152:153], v[152:153], v[96:97], v[162:163] op_sel:[0,1,0] op_sel_hi:[1,1,1]
	v_pk_fma_f32 v[170:171], v[170:171], v[94:95], v[180:181] op_sel:[0,0,0] op_sel_hi:[1,0,1]
	v_pk_fma_f32 v[172:173], v[172:173], v[94:95], v[182:183] op_sel:[0,1,0] op_sel_hi:[1,1,1]
	v_pk_fma_f32 v[174:175], v[174:175], v[96:97], v[184:185] op_sel:[0,0,0] op_sel_hi:[1,0,1]
	v_pk_fma_f32 v[176:177], v[176:177], v[96:97], v[186:187] op_sel:[0,1,0] op_sel_hi:[1,1,1]
	ds_read_b128 v[94:97], v62 offset:12288
	ds_read_b128 v[98:101], v62 offset:12800
	ds_read_b128 v[102:105], v62 offset:13312
	ds_read_b128 v[106:109], v62 offset:13568
	v_add_u32_e32 v22, 0x3000, v63
	ds_read2_b32 v[22:23], v22 offset0:192 offset1:196
	s_waitcnt lgkmcnt(5)
	v_pk_mul_f32 v[154:155], v[146:147], v[86:87] op_sel:[0,0] op_sel_hi:[1,0]
	v_pk_fma_f32 v[154:155], v[148:149], v[86:87], v[154:155] op_sel:[0,1,0] op_sel_hi:[1,1,1]
	v_pk_fma_f32 v[154:155], v[150:151], v[88:89], v[154:155] op_sel:[0,0,0] op_sel_hi:[1,0,1]
	v_pk_fma_f32 v[154:155], v[152:153], v[88:89], v[154:155] op_sel:[0,1,0] op_sel_hi:[1,1,1]
	v_pk_mul_f32 v[178:179], v[170:171], v[86:87] op_sel:[0,0] op_sel_hi:[1,0]
	v_pk_fma_f32 v[178:179], v[172:173], v[86:87], v[178:179] op_sel:[0,1,0] op_sel_hi:[1,1,1]
	v_pk_fma_f32 v[178:179], v[174:175], v[88:89], v[178:179] op_sel:[0,0,0] op_sel_hi:[1,0,1]
	v_pk_fma_f32 v[178:179], v[176:177], v[88:89], v[178:179] op_sel:[0,1,0] op_sel_hi:[1,1,1]
	v_pk_mul_f32 v[156:157], v[110:111], v[82:83] op_sel:[0,0] op_sel_hi:[1,0]
	v_add_f32_dpp v154, v154, v154 quad_perm:[1,0,3,2] row_mask:0xf bank_mask:0xf bound_ctrl:1
	v_add_f32_dpp v155, v155, v155 quad_perm:[1,0,3,2] row_mask:0xf bank_mask:0xf bound_ctrl:1
	v_add_f32_dpp v178, v178, v178 quad_perm:[1,0,3,2] row_mask:0xf bank_mask:0xf bound_ctrl:1
	v_add_f32_dpp v179, v179, v179 quad_perm:[1,0,3,2] row_mask:0xf bank_mask:0xf bound_ctrl:1
	v_add_f32_dpp v154, v154, v154 quad_perm:[2,3,0,1] row_mask:0xf bank_mask:0xf bound_ctrl:1
	v_add_f32_dpp v155, v155, v155 quad_perm:[2,3,0,1] row_mask:0xf bank_mask:0xf bound_ctrl:1
	v_add_f32_dpp v178, v178, v178 quad_perm:[2,3,0,1] row_mask:0xf bank_mask:0xf bound_ctrl:1
	v_add_f32_dpp v179, v179, v179 quad_perm:[2,3,0,1] row_mask:0xf bank_mask:0xf bound_ctrl:1
	v_add_f32_dpp v154, v154, v154 row_half_mirror row_mask:0xf bank_mask:0xf bound_ctrl:1
	v_add_f32_dpp v155, v155, v155 row_half_mirror row_mask:0xf bank_mask:0xf bound_ctrl:1
	v_add_f32_dpp v178, v178, v178 row_half_mirror row_mask:0xf bank_mask:0xf bound_ctrl:1
	v_add_f32_dpp v179, v179, v179 row_half_mirror row_mask:0xf bank_mask:0xf bound_ctrl:1
	v_add_f32_dpp v154, v154, v154 row_mirror row_mask:0xf bank_mask:0xf bound_ctrl:1
	v_add_f32_dpp v155, v155, v155 row_mirror row_mask:0xf bank_mask:0xf bound_ctrl:1
	v_add_f32_dpp v178, v178, v178 row_mirror row_mask:0xf bank_mask:0xf bound_ctrl:1
	v_add_f32_dpp v179, v179, v179 row_mirror row_mask:0xf bank_mask:0xf bound_ctrl:1
	v_pk_mul_f32 v[158:159], v[110:111], v[82:83] op_sel:[0,1] op_sel_hi:[1,1]
	v_pk_mul_f32 v[160:161], v[110:111], v[84:85] op_sel:[0,0] op_sel_hi:[1,0]
	v_pk_mul_f32 v[162:163], v[110:111], v[84:85] op_sel:[0,1] op_sel_hi:[1,1]
	v_pk_fma_f32 v[156:157], v[154:155], v[90:91], v[156:157] op_sel:[0,0,0] op_sel_hi:[1,0,1] neg_lo:[1,0,0] neg_hi:[1,0,0]
	v_pk_fma_f32 v[158:159], v[154:155], v[90:91], v[158:159] op_sel:[0,1,0] op_sel_hi:[1,1,1] neg_lo:[1,0,0] neg_hi:[1,0,0]
	v_pk_fma_f32 v[160:161], v[154:155], v[92:93], v[160:161] op_sel:[0,0,0] op_sel_hi:[1,0,1] neg_lo:[1,0,0] neg_hi:[1,0,0]
	v_pk_fma_f32 v[162:163], v[154:155], v[92:93], v[162:163] op_sel:[0,1,0] op_sel_hi:[1,1,1] neg_lo:[1,0,0] neg_hi:[1,0,0]
	v_pk_mul_f32 v[180:181], v[178:179], v[90:91] op_sel:[0,0] op_sel_hi:[1,0] neg_lo:[1,0] neg_hi:[1,0]
	v_pk_mul_f32 v[182:183], v[178:179], v[90:91] op_sel:[0,1] op_sel_hi:[1,1] neg_lo:[1,0] neg_hi:[1,0]
	v_pk_mul_f32 v[184:185], v[178:179], v[92:93] op_sel:[0,0] op_sel_hi:[1,0] neg_lo:[1,0] neg_hi:[1,0]
	v_pk_mul_f32 v[186:187], v[178:179], v[92:93] op_sel:[0,1] op_sel_hi:[1,1] neg_lo:[1,0] neg_hi:[1,0]
	v_pk_fma_f32 v[146:147], v[146:147], v[78:79], v[156:157] op_sel:[0,0,0] op_sel_hi:[1,0,1]
	v_pk_fma_f32 v[148:149], v[148:149], v[78:79], v[158:159] op_sel:[0,1,0] op_sel_hi:[1,1,1]
	v_pk_fma_f32 v[150:151], v[150:151], v[80:81], v[160:161] op_sel:[0,0,0] op_sel_hi:[1,0,1]
	v_pk_fma_f32 v[152:153], v[152:153], v[80:81], v[162:163] op_sel:[0,1,0] op_sel_hi:[1,1,1]
	v_pk_fma_f32 v[170:171], v[170:171], v[78:79], v[180:181] op_sel:[0,0,0] op_sel_hi:[1,0,1]
	v_pk_fma_f32 v[172:173], v[172:173], v[78:79], v[182:183] op_sel:[0,1,0] op_sel_hi:[1,1,1]
	v_pk_fma_f32 v[174:175], v[174:175], v[80:81], v[184:185] op_sel:[0,0,0] op_sel_hi:[1,0,1]
	v_pk_fma_f32 v[176:177], v[176:177], v[80:81], v[186:187] op_sel:[0,1,0] op_sel_hi:[1,1,1]
	ds_read_b128 v[78:81], v62 offset:13824
	ds_read_b128 v[82:85], v62 offset:14336
	ds_read_b128 v[86:89], v62 offset:14848
	ds_read_b128 v[90:93], v62 offset:15104
	v_add_u32_e32 v110, 0x3800, v63
	ds_read2_b32 v[110:111], v110 offset0:64 offset1:68
	s_waitcnt lgkmcnt(5)
	v_pk_mul_f32 v[154:155], v[146:147], v[102:103] op_sel:[0,0] op_sel_hi:[1,0]
	v_pk_fma_f32 v[154:155], v[148:149], v[102:103], v[154:155] op_sel:[0,1,0] op_sel_hi:[1,1,1]
	v_pk_fma_f32 v[154:155], v[150:151], v[104:105], v[154:155] op_sel:[0,0,0] op_sel_hi:[1,0,1]
	v_pk_fma_f32 v[154:155], v[152:153], v[104:105], v[154:155] op_sel:[0,1,0] op_sel_hi:[1,1,1]
	v_pk_mul_f32 v[178:179], v[170:171], v[102:103] op_sel:[0,0] op_sel_hi:[1,0]
	v_pk_fma_f32 v[178:179], v[172:173], v[102:103], v[178:179] op_sel:[0,1,0] op_sel_hi:[1,1,1]
	v_pk_fma_f32 v[178:179], v[174:175], v[104:105], v[178:179] op_sel:[0,0,0] op_sel_hi:[1,0,1]
	v_pk_fma_f32 v[178:179], v[176:177], v[104:105], v[178:179] op_sel:[0,1,0] op_sel_hi:[1,1,1]
	v_pk_mul_f32 v[156:157], v[22:23], v[98:99] op_sel:[0,0] op_sel_hi:[1,0]
	v_add_f32_dpp v154, v154, v154 quad_perm:[1,0,3,2] row_mask:0xf bank_mask:0xf bound_ctrl:1
	v_add_f32_dpp v155, v155, v155 quad_perm:[1,0,3,2] row_mask:0xf bank_mask:0xf bound_ctrl:1
	v_add_f32_dpp v178, v178, v178 quad_perm:[1,0,3,2] row_mask:0xf bank_mask:0xf bound_ctrl:1
	v_add_f32_dpp v179, v179, v179 quad_perm:[1,0,3,2] row_mask:0xf bank_mask:0xf bound_ctrl:1
	v_add_f32_dpp v154, v154, v154 quad_perm:[2,3,0,1] row_mask:0xf bank_mask:0xf bound_ctrl:1
	v_add_f32_dpp v155, v155, v155 quad_perm:[2,3,0,1] row_mask:0xf bank_mask:0xf bound_ctrl:1
	v_add_f32_dpp v178, v178, v178 quad_perm:[2,3,0,1] row_mask:0xf bank_mask:0xf bound_ctrl:1
	v_add_f32_dpp v179, v179, v179 quad_perm:[2,3,0,1] row_mask:0xf bank_mask:0xf bound_ctrl:1
	v_add_f32_dpp v154, v154, v154 row_half_mirror row_mask:0xf bank_mask:0xf bound_ctrl:1
	v_add_f32_dpp v155, v155, v155 row_half_mirror row_mask:0xf bank_mask:0xf bound_ctrl:1
	v_add_f32_dpp v178, v178, v178 row_half_mirror row_mask:0xf bank_mask:0xf bound_ctrl:1
	v_add_f32_dpp v179, v179, v179 row_half_mirror row_mask:0xf bank_mask:0xf bound_ctrl:1
	v_add_f32_dpp v154, v154, v154 row_mirror row_mask:0xf bank_mask:0xf bound_ctrl:1
	v_add_f32_dpp v155, v155, v155 row_mirror row_mask:0xf bank_mask:0xf bound_ctrl:1
	v_add_f32_dpp v178, v178, v178 row_mirror row_mask:0xf bank_mask:0xf bound_ctrl:1
	v_add_f32_dpp v179, v179, v179 row_mirror row_mask:0xf bank_mask:0xf bound_ctrl:1
	v_pk_mul_f32 v[158:159], v[22:23], v[98:99] op_sel:[0,1] op_sel_hi:[1,1]
	v_pk_mul_f32 v[160:161], v[22:23], v[100:101] op_sel:[0,0] op_sel_hi:[1,0]
	v_pk_mul_f32 v[162:163], v[22:23], v[100:101] op_sel:[0,1] op_sel_hi:[1,1]
	v_pk_fma_f32 v[156:157], v[154:155], v[106:107], v[156:157] op_sel:[0,0,0] op_sel_hi:[1,0,1] neg_lo:[1,0,0] neg_hi:[1,0,0]
	v_pk_fma_f32 v[158:159], v[154:155], v[106:107], v[158:159] op_sel:[0,1,0] op_sel_hi:[1,1,1] neg_lo:[1,0,0] neg_hi:[1,0,0]
	v_pk_fma_f32 v[160:161], v[154:155], v[108:109], v[160:161] op_sel:[0,0,0] op_sel_hi:[1,0,1] neg_lo:[1,0,0] neg_hi:[1,0,0]
	v_pk_fma_f32 v[162:163], v[154:155], v[108:109], v[162:163] op_sel:[0,1,0] op_sel_hi:[1,1,1] neg_lo:[1,0,0] neg_hi:[1,0,0]
	v_pk_mul_f32 v[180:181], v[178:179], v[106:107] op_sel:[0,0] op_sel_hi:[1,0] neg_lo:[1,0] neg_hi:[1,0]
	v_pk_mul_f32 v[182:183], v[178:179], v[106:107] op_sel:[0,1] op_sel_hi:[1,1] neg_lo:[1,0] neg_hi:[1,0]
	v_pk_mul_f32 v[184:185], v[178:179], v[108:109] op_sel:[0,0] op_sel_hi:[1,0] neg_lo:[1,0] neg_hi:[1,0]
	v_pk_mul_f32 v[186:187], v[178:179], v[108:109] op_sel:[0,1] op_sel_hi:[1,1] neg_lo:[1,0] neg_hi:[1,0]
	v_pk_fma_f32 v[146:147], v[146:147], v[94:95], v[156:157] op_sel:[0,0,0] op_sel_hi:[1,0,1]
	v_pk_fma_f32 v[148:149], v[148:149], v[94:95], v[158:159] op_sel:[0,1,0] op_sel_hi:[1,1,1]
	v_pk_fma_f32 v[150:151], v[150:151], v[96:97], v[160:161] op_sel:[0,0,0] op_sel_hi:[1,0,1]
	v_pk_fma_f32 v[152:153], v[152:153], v[96:97], v[162:163] op_sel:[0,1,0] op_sel_hi:[1,1,1]
	v_pk_fma_f32 v[170:171], v[170:171], v[94:95], v[180:181] op_sel:[0,0,0] op_sel_hi:[1,0,1]
	v_pk_fma_f32 v[172:173], v[172:173], v[94:95], v[182:183] op_sel:[0,1,0] op_sel_hi:[1,1,1]
	v_pk_fma_f32 v[174:175], v[174:175], v[96:97], v[184:185] op_sel:[0,0,0] op_sel_hi:[1,0,1]
	v_pk_fma_f32 v[176:177], v[176:177], v[96:97], v[186:187] op_sel:[0,1,0] op_sel_hi:[1,1,1]
	ds_read_b128 v[94:97], v62 offset:15360
	ds_read_b128 v[98:101], v62 offset:15872
	ds_read_b128 v[102:105], v62 offset:16384
	ds_read_b128 v[106:109], v62 offset:16640
	v_add_u32_e32 v22, 0x3c00, v63
	ds_read2_b32 v[22:23], v22 offset0:192 offset1:196
	s_waitcnt lgkmcnt(5)
	v_pk_mul_f32 v[154:155], v[146:147], v[86:87] op_sel:[0,0] op_sel_hi:[1,0]
	v_pk_fma_f32 v[154:155], v[148:149], v[86:87], v[154:155] op_sel:[0,1,0] op_sel_hi:[1,1,1]
	v_pk_fma_f32 v[154:155], v[150:151], v[88:89], v[154:155] op_sel:[0,0,0] op_sel_hi:[1,0,1]
	v_pk_fma_f32 v[154:155], v[152:153], v[88:89], v[154:155] op_sel:[0,1,0] op_sel_hi:[1,1,1]
	v_pk_mul_f32 v[178:179], v[170:171], v[86:87] op_sel:[0,0] op_sel_hi:[1,0]
	v_pk_fma_f32 v[178:179], v[172:173], v[86:87], v[178:179] op_sel:[0,1,0] op_sel_hi:[1,1,1]
	v_pk_fma_f32 v[178:179], v[174:175], v[88:89], v[178:179] op_sel:[0,0,0] op_sel_hi:[1,0,1]
	v_pk_fma_f32 v[178:179], v[176:177], v[88:89], v[178:179] op_sel:[0,1,0] op_sel_hi:[1,1,1]
	v_pk_mul_f32 v[156:157], v[110:111], v[82:83] op_sel:[0,0] op_sel_hi:[1,0]
	v_add_f32_dpp v154, v154, v154 quad_perm:[1,0,3,2] row_mask:0xf bank_mask:0xf bound_ctrl:1
	v_add_f32_dpp v155, v155, v155 quad_perm:[1,0,3,2] row_mask:0xf bank_mask:0xf bound_ctrl:1
	v_add_f32_dpp v178, v178, v178 quad_perm:[1,0,3,2] row_mask:0xf bank_mask:0xf bound_ctrl:1
	v_add_f32_dpp v179, v179, v179 quad_perm:[1,0,3,2] row_mask:0xf bank_mask:0xf bound_ctrl:1
	v_add_f32_dpp v154, v154, v154 quad_perm:[2,3,0,1] row_mask:0xf bank_mask:0xf bound_ctrl:1
	v_add_f32_dpp v155, v155, v155 quad_perm:[2,3,0,1] row_mask:0xf bank_mask:0xf bound_ctrl:1
	v_add_f32_dpp v178, v178, v178 quad_perm:[2,3,0,1] row_mask:0xf bank_mask:0xf bound_ctrl:1
	v_add_f32_dpp v179, v179, v179 quad_perm:[2,3,0,1] row_mask:0xf bank_mask:0xf bound_ctrl:1
	v_add_f32_dpp v154, v154, v154 row_half_mirror row_mask:0xf bank_mask:0xf bound_ctrl:1
	v_add_f32_dpp v155, v155, v155 row_half_mirror row_mask:0xf bank_mask:0xf bound_ctrl:1
	v_add_f32_dpp v178, v178, v178 row_half_mirror row_mask:0xf bank_mask:0xf bound_ctrl:1
	v_add_f32_dpp v179, v179, v179 row_half_mirror row_mask:0xf bank_mask:0xf bound_ctrl:1
	v_add_f32_dpp v154, v154, v154 row_mirror row_mask:0xf bank_mask:0xf bound_ctrl:1
	v_add_f32_dpp v155, v155, v155 row_mirror row_mask:0xf bank_mask:0xf bound_ctrl:1
	v_add_f32_dpp v178, v178, v178 row_mirror row_mask:0xf bank_mask:0xf bound_ctrl:1
	v_add_f32_dpp v179, v179, v179 row_mirror row_mask:0xf bank_mask:0xf bound_ctrl:1
	v_pk_mul_f32 v[158:159], v[110:111], v[82:83] op_sel:[0,1] op_sel_hi:[1,1]
	v_pk_mul_f32 v[160:161], v[110:111], v[84:85] op_sel:[0,0] op_sel_hi:[1,0]
	v_pk_mul_f32 v[162:163], v[110:111], v[84:85] op_sel:[0,1] op_sel_hi:[1,1]
	v_pk_fma_f32 v[156:157], v[154:155], v[90:91], v[156:157] op_sel:[0,0,0] op_sel_hi:[1,0,1] neg_lo:[1,0,0] neg_hi:[1,0,0]
	v_pk_fma_f32 v[158:159], v[154:155], v[90:91], v[158:159] op_sel:[0,1,0] op_sel_hi:[1,1,1] neg_lo:[1,0,0] neg_hi:[1,0,0]
	v_pk_fma_f32 v[160:161], v[154:155], v[92:93], v[160:161] op_sel:[0,0,0] op_sel_hi:[1,0,1] neg_lo:[1,0,0] neg_hi:[1,0,0]
	v_pk_fma_f32 v[162:163], v[154:155], v[92:93], v[162:163] op_sel:[0,1,0] op_sel_hi:[1,1,1] neg_lo:[1,0,0] neg_hi:[1,0,0]
	v_pk_mul_f32 v[180:181], v[178:179], v[90:91] op_sel:[0,0] op_sel_hi:[1,0] neg_lo:[1,0] neg_hi:[1,0]
	v_pk_mul_f32 v[182:183], v[178:179], v[90:91] op_sel:[0,1] op_sel_hi:[1,1] neg_lo:[1,0] neg_hi:[1,0]
	v_pk_mul_f32 v[184:185], v[178:179], v[92:93] op_sel:[0,0] op_sel_hi:[1,0] neg_lo:[1,0] neg_hi:[1,0]
	v_pk_mul_f32 v[186:187], v[178:179], v[92:93] op_sel:[0,1] op_sel_hi:[1,1] neg_lo:[1,0] neg_hi:[1,0]
	v_pk_fma_f32 v[146:147], v[146:147], v[78:79], v[156:157] op_sel:[0,0,0] op_sel_hi:[1,0,1]
	v_pk_fma_f32 v[148:149], v[148:149], v[78:79], v[158:159] op_sel:[0,1,0] op_sel_hi:[1,1,1]
	v_pk_fma_f32 v[150:151], v[150:151], v[80:81], v[160:161] op_sel:[0,0,0] op_sel_hi:[1,0,1]
	v_pk_fma_f32 v[152:153], v[152:153], v[80:81], v[162:163] op_sel:[0,1,0] op_sel_hi:[1,1,1]
	v_pk_fma_f32 v[170:171], v[170:171], v[78:79], v[180:181] op_sel:[0,0,0] op_sel_hi:[1,0,1]
	v_pk_fma_f32 v[172:173], v[172:173], v[78:79], v[182:183] op_sel:[0,1,0] op_sel_hi:[1,1,1]
	v_pk_fma_f32 v[174:175], v[174:175], v[80:81], v[184:185] op_sel:[0,0,0] op_sel_hi:[1,0,1]
	v_pk_fma_f32 v[176:177], v[176:177], v[80:81], v[186:187] op_sel:[0,1,0] op_sel_hi:[1,1,1]
	ds_read_b128 v[78:81], v62 offset:16896
	ds_read_b128 v[82:85], v62 offset:17408
	ds_read_b128 v[86:89], v62 offset:17920
	ds_read_b128 v[90:93], v62 offset:18176
	v_add_u32_e32 v110, 0x4400, v63
	ds_read2_b32 v[110:111], v110 offset0:64 offset1:68
	s_waitcnt lgkmcnt(5)
	v_pk_mul_f32 v[154:155], v[146:147], v[102:103] op_sel:[0,0] op_sel_hi:[1,0]
	v_pk_fma_f32 v[154:155], v[148:149], v[102:103], v[154:155] op_sel:[0,1,0] op_sel_hi:[1,1,1]
	v_pk_fma_f32 v[154:155], v[150:151], v[104:105], v[154:155] op_sel:[0,0,0] op_sel_hi:[1,0,1]
	v_pk_fma_f32 v[154:155], v[152:153], v[104:105], v[154:155] op_sel:[0,1,0] op_sel_hi:[1,1,1]
	v_pk_mul_f32 v[178:179], v[170:171], v[102:103] op_sel:[0,0] op_sel_hi:[1,0]
	v_pk_fma_f32 v[178:179], v[172:173], v[102:103], v[178:179] op_sel:[0,1,0] op_sel_hi:[1,1,1]
	v_pk_fma_f32 v[178:179], v[174:175], v[104:105], v[178:179] op_sel:[0,0,0] op_sel_hi:[1,0,1]
	v_pk_fma_f32 v[178:179], v[176:177], v[104:105], v[178:179] op_sel:[0,1,0] op_sel_hi:[1,1,1]
	v_pk_mul_f32 v[156:157], v[22:23], v[98:99] op_sel:[0,0] op_sel_hi:[1,0]
	v_add_f32_dpp v154, v154, v154 quad_perm:[1,0,3,2] row_mask:0xf bank_mask:0xf bound_ctrl:1
	v_add_f32_dpp v155, v155, v155 quad_perm:[1,0,3,2] row_mask:0xf bank_mask:0xf bound_ctrl:1
	v_add_f32_dpp v178, v178, v178 quad_perm:[1,0,3,2] row_mask:0xf bank_mask:0xf bound_ctrl:1
	v_add_f32_dpp v179, v179, v179 quad_perm:[1,0,3,2] row_mask:0xf bank_mask:0xf bound_ctrl:1
	v_add_f32_dpp v154, v154, v154 quad_perm:[2,3,0,1] row_mask:0xf bank_mask:0xf bound_ctrl:1
	v_add_f32_dpp v155, v155, v155 quad_perm:[2,3,0,1] row_mask:0xf bank_mask:0xf bound_ctrl:1
	v_add_f32_dpp v178, v178, v178 quad_perm:[2,3,0,1] row_mask:0xf bank_mask:0xf bound_ctrl:1
	v_add_f32_dpp v179, v179, v179 quad_perm:[2,3,0,1] row_mask:0xf bank_mask:0xf bound_ctrl:1
	v_add_f32_dpp v154, v154, v154 row_half_mirror row_mask:0xf bank_mask:0xf bound_ctrl:1
	v_add_f32_dpp v155, v155, v155 row_half_mirror row_mask:0xf bank_mask:0xf bound_ctrl:1
	v_add_f32_dpp v178, v178, v178 row_half_mirror row_mask:0xf bank_mask:0xf bound_ctrl:1
	v_add_f32_dpp v179, v179, v179 row_half_mirror row_mask:0xf bank_mask:0xf bound_ctrl:1
	v_add_f32_dpp v154, v154, v154 row_mirror row_mask:0xf bank_mask:0xf bound_ctrl:1
	v_add_f32_dpp v155, v155, v155 row_mirror row_mask:0xf bank_mask:0xf bound_ctrl:1
	v_add_f32_dpp v178, v178, v178 row_mirror row_mask:0xf bank_mask:0xf bound_ctrl:1
	v_add_f32_dpp v179, v179, v179 row_mirror row_mask:0xf bank_mask:0xf bound_ctrl:1
	v_pk_mul_f32 v[158:159], v[22:23], v[98:99] op_sel:[0,1] op_sel_hi:[1,1]
	v_pk_mul_f32 v[160:161], v[22:23], v[100:101] op_sel:[0,0] op_sel_hi:[1,0]
	v_pk_mul_f32 v[162:163], v[22:23], v[100:101] op_sel:[0,1] op_sel_hi:[1,1]
	v_pk_fma_f32 v[156:157], v[154:155], v[106:107], v[156:157] op_sel:[0,0,0] op_sel_hi:[1,0,1] neg_lo:[1,0,0] neg_hi:[1,0,0]
	v_pk_fma_f32 v[158:159], v[154:155], v[106:107], v[158:159] op_sel:[0,1,0] op_sel_hi:[1,1,1] neg_lo:[1,0,0] neg_hi:[1,0,0]
	v_pk_fma_f32 v[160:161], v[154:155], v[108:109], v[160:161] op_sel:[0,0,0] op_sel_hi:[1,0,1] neg_lo:[1,0,0] neg_hi:[1,0,0]
	v_pk_fma_f32 v[162:163], v[154:155], v[108:109], v[162:163] op_sel:[0,1,0] op_sel_hi:[1,1,1] neg_lo:[1,0,0] neg_hi:[1,0,0]
	v_pk_mul_f32 v[180:181], v[178:179], v[106:107] op_sel:[0,0] op_sel_hi:[1,0] neg_lo:[1,0] neg_hi:[1,0]
	v_pk_mul_f32 v[182:183], v[178:179], v[106:107] op_sel:[0,1] op_sel_hi:[1,1] neg_lo:[1,0] neg_hi:[1,0]
	v_pk_mul_f32 v[184:185], v[178:179], v[108:109] op_sel:[0,0] op_sel_hi:[1,0] neg_lo:[1,0] neg_hi:[1,0]
	v_pk_mul_f32 v[186:187], v[178:179], v[108:109] op_sel:[0,1] op_sel_hi:[1,1] neg_lo:[1,0] neg_hi:[1,0]
	v_pk_fma_f32 v[146:147], v[146:147], v[94:95], v[156:157] op_sel:[0,0,0] op_sel_hi:[1,0,1]
	v_pk_fma_f32 v[148:149], v[148:149], v[94:95], v[158:159] op_sel:[0,1,0] op_sel_hi:[1,1,1]
	v_pk_fma_f32 v[150:151], v[150:151], v[96:97], v[160:161] op_sel:[0,0,0] op_sel_hi:[1,0,1]
	v_pk_fma_f32 v[152:153], v[152:153], v[96:97], v[162:163] op_sel:[0,1,0] op_sel_hi:[1,1,1]
	v_pk_fma_f32 v[170:171], v[170:171], v[94:95], v[180:181] op_sel:[0,0,0] op_sel_hi:[1,0,1]
	v_pk_fma_f32 v[172:173], v[172:173], v[94:95], v[182:183] op_sel:[0,1,0] op_sel_hi:[1,1,1]
	v_pk_fma_f32 v[174:175], v[174:175], v[96:97], v[184:185] op_sel:[0,0,0] op_sel_hi:[1,0,1]
	v_pk_fma_f32 v[176:177], v[176:177], v[96:97], v[186:187] op_sel:[0,1,0] op_sel_hi:[1,1,1]
	ds_read_b128 v[94:97], v62 offset:18432
	ds_read_b128 v[98:101], v62 offset:18944
	ds_read_b128 v[102:105], v62 offset:19456
	ds_read_b128 v[106:109], v62 offset:19712
	v_add_u32_e32 v22, 0x4800, v63
	ds_read2_b32 v[22:23], v22 offset0:192 offset1:196
	s_waitcnt lgkmcnt(5)
	v_pk_mul_f32 v[154:155], v[146:147], v[86:87] op_sel:[0,0] op_sel_hi:[1,0]
	v_pk_fma_f32 v[154:155], v[148:149], v[86:87], v[154:155] op_sel:[0,1,0] op_sel_hi:[1,1,1]
	v_pk_fma_f32 v[154:155], v[150:151], v[88:89], v[154:155] op_sel:[0,0,0] op_sel_hi:[1,0,1]
	v_pk_fma_f32 v[154:155], v[152:153], v[88:89], v[154:155] op_sel:[0,1,0] op_sel_hi:[1,1,1]
	v_pk_mul_f32 v[178:179], v[170:171], v[86:87] op_sel:[0,0] op_sel_hi:[1,0]
	v_pk_fma_f32 v[178:179], v[172:173], v[86:87], v[178:179] op_sel:[0,1,0] op_sel_hi:[1,1,1]
	v_pk_fma_f32 v[178:179], v[174:175], v[88:89], v[178:179] op_sel:[0,0,0] op_sel_hi:[1,0,1]
	v_pk_fma_f32 v[178:179], v[176:177], v[88:89], v[178:179] op_sel:[0,1,0] op_sel_hi:[1,1,1]
	v_pk_mul_f32 v[156:157], v[110:111], v[82:83] op_sel:[0,0] op_sel_hi:[1,0]
	v_add_f32_dpp v154, v154, v154 quad_perm:[1,0,3,2] row_mask:0xf bank_mask:0xf bound_ctrl:1
	v_add_f32_dpp v155, v155, v155 quad_perm:[1,0,3,2] row_mask:0xf bank_mask:0xf bound_ctrl:1
	v_add_f32_dpp v178, v178, v178 quad_perm:[1,0,3,2] row_mask:0xf bank_mask:0xf bound_ctrl:1
	v_add_f32_dpp v179, v179, v179 quad_perm:[1,0,3,2] row_mask:0xf bank_mask:0xf bound_ctrl:1
	v_add_f32_dpp v154, v154, v154 quad_perm:[2,3,0,1] row_mask:0xf bank_mask:0xf bound_ctrl:1
	v_add_f32_dpp v155, v155, v155 quad_perm:[2,3,0,1] row_mask:0xf bank_mask:0xf bound_ctrl:1
	v_add_f32_dpp v178, v178, v178 quad_perm:[2,3,0,1] row_mask:0xf bank_mask:0xf bound_ctrl:1
	v_add_f32_dpp v179, v179, v179 quad_perm:[2,3,0,1] row_mask:0xf bank_mask:0xf bound_ctrl:1
	v_add_f32_dpp v154, v154, v154 row_half_mirror row_mask:0xf bank_mask:0xf bound_ctrl:1
	v_add_f32_dpp v155, v155, v155 row_half_mirror row_mask:0xf bank_mask:0xf bound_ctrl:1
	v_add_f32_dpp v178, v178, v178 row_half_mirror row_mask:0xf bank_mask:0xf bound_ctrl:1
	v_add_f32_dpp v179, v179, v179 row_half_mirror row_mask:0xf bank_mask:0xf bound_ctrl:1
	v_add_f32_dpp v154, v154, v154 row_mirror row_mask:0xf bank_mask:0xf bound_ctrl:1
	v_add_f32_dpp v155, v155, v155 row_mirror row_mask:0xf bank_mask:0xf bound_ctrl:1
	v_add_f32_dpp v178, v178, v178 row_mirror row_mask:0xf bank_mask:0xf bound_ctrl:1
	v_add_f32_dpp v179, v179, v179 row_mirror row_mask:0xf bank_mask:0xf bound_ctrl:1
	v_pk_mul_f32 v[158:159], v[110:111], v[82:83] op_sel:[0,1] op_sel_hi:[1,1]
	v_pk_mul_f32 v[160:161], v[110:111], v[84:85] op_sel:[0,0] op_sel_hi:[1,0]
	v_pk_mul_f32 v[162:163], v[110:111], v[84:85] op_sel:[0,1] op_sel_hi:[1,1]
	v_pk_fma_f32 v[156:157], v[154:155], v[90:91], v[156:157] op_sel:[0,0,0] op_sel_hi:[1,0,1] neg_lo:[1,0,0] neg_hi:[1,0,0]
	v_pk_fma_f32 v[158:159], v[154:155], v[90:91], v[158:159] op_sel:[0,1,0] op_sel_hi:[1,1,1] neg_lo:[1,0,0] neg_hi:[1,0,0]
	v_pk_fma_f32 v[160:161], v[154:155], v[92:93], v[160:161] op_sel:[0,0,0] op_sel_hi:[1,0,1] neg_lo:[1,0,0] neg_hi:[1,0,0]
	v_pk_fma_f32 v[162:163], v[154:155], v[92:93], v[162:163] op_sel:[0,1,0] op_sel_hi:[1,1,1] neg_lo:[1,0,0] neg_hi:[1,0,0]
	v_pk_mul_f32 v[180:181], v[178:179], v[90:91] op_sel:[0,0] op_sel_hi:[1,0] neg_lo:[1,0] neg_hi:[1,0]
	v_pk_mul_f32 v[182:183], v[178:179], v[90:91] op_sel:[0,1] op_sel_hi:[1,1] neg_lo:[1,0] neg_hi:[1,0]
	v_pk_mul_f32 v[184:185], v[178:179], v[92:93] op_sel:[0,0] op_sel_hi:[1,0] neg_lo:[1,0] neg_hi:[1,0]
	v_pk_mul_f32 v[186:187], v[178:179], v[92:93] op_sel:[0,1] op_sel_hi:[1,1] neg_lo:[1,0] neg_hi:[1,0]
	v_pk_fma_f32 v[146:147], v[146:147], v[78:79], v[156:157] op_sel:[0,0,0] op_sel_hi:[1,0,1]
	v_pk_fma_f32 v[148:149], v[148:149], v[78:79], v[158:159] op_sel:[0,1,0] op_sel_hi:[1,1,1]
	v_pk_fma_f32 v[150:151], v[150:151], v[80:81], v[160:161] op_sel:[0,0,0] op_sel_hi:[1,0,1]
	v_pk_fma_f32 v[152:153], v[152:153], v[80:81], v[162:163] op_sel:[0,1,0] op_sel_hi:[1,1,1]
	v_pk_fma_f32 v[170:171], v[170:171], v[78:79], v[180:181] op_sel:[0,0,0] op_sel_hi:[1,0,1]
	v_pk_fma_f32 v[172:173], v[172:173], v[78:79], v[182:183] op_sel:[0,1,0] op_sel_hi:[1,1,1]
	v_pk_fma_f32 v[174:175], v[174:175], v[80:81], v[184:185] op_sel:[0,0,0] op_sel_hi:[1,0,1]
	v_pk_fma_f32 v[176:177], v[176:177], v[80:81], v[186:187] op_sel:[0,1,0] op_sel_hi:[1,1,1]
	ds_read_b128 v[78:81], v62 offset:19968
	ds_read_b128 v[82:85], v62 offset:20480
	ds_read_b128 v[86:89], v62 offset:20992
	ds_read_b128 v[90:93], v62 offset:21248
	v_add_u32_e32 v110, 0x5000, v63
	ds_read2_b32 v[110:111], v110 offset0:64 offset1:68
	s_waitcnt lgkmcnt(5)
	v_pk_mul_f32 v[154:155], v[146:147], v[102:103] op_sel:[0,0] op_sel_hi:[1,0]
	v_pk_fma_f32 v[154:155], v[148:149], v[102:103], v[154:155] op_sel:[0,1,0] op_sel_hi:[1,1,1]
	v_pk_fma_f32 v[154:155], v[150:151], v[104:105], v[154:155] op_sel:[0,0,0] op_sel_hi:[1,0,1]
	v_pk_fma_f32 v[154:155], v[152:153], v[104:105], v[154:155] op_sel:[0,1,0] op_sel_hi:[1,1,1]
	v_pk_mul_f32 v[178:179], v[170:171], v[102:103] op_sel:[0,0] op_sel_hi:[1,0]
	v_pk_fma_f32 v[178:179], v[172:173], v[102:103], v[178:179] op_sel:[0,1,0] op_sel_hi:[1,1,1]
	v_pk_fma_f32 v[178:179], v[174:175], v[104:105], v[178:179] op_sel:[0,0,0] op_sel_hi:[1,0,1]
	v_pk_fma_f32 v[178:179], v[176:177], v[104:105], v[178:179] op_sel:[0,1,0] op_sel_hi:[1,1,1]
	v_pk_mul_f32 v[156:157], v[22:23], v[98:99] op_sel:[0,0] op_sel_hi:[1,0]
	v_add_f32_dpp v154, v154, v154 quad_perm:[1,0,3,2] row_mask:0xf bank_mask:0xf bound_ctrl:1
	v_add_f32_dpp v155, v155, v155 quad_perm:[1,0,3,2] row_mask:0xf bank_mask:0xf bound_ctrl:1
	v_add_f32_dpp v178, v178, v178 quad_perm:[1,0,3,2] row_mask:0xf bank_mask:0xf bound_ctrl:1
	v_add_f32_dpp v179, v179, v179 quad_perm:[1,0,3,2] row_mask:0xf bank_mask:0xf bound_ctrl:1
	v_add_f32_dpp v154, v154, v154 quad_perm:[2,3,0,1] row_mask:0xf bank_mask:0xf bound_ctrl:1
	v_add_f32_dpp v155, v155, v155 quad_perm:[2,3,0,1] row_mask:0xf bank_mask:0xf bound_ctrl:1
	v_add_f32_dpp v178, v178, v178 quad_perm:[2,3,0,1] row_mask:0xf bank_mask:0xf bound_ctrl:1
	v_add_f32_dpp v179, v179, v179 quad_perm:[2,3,0,1] row_mask:0xf bank_mask:0xf bound_ctrl:1
	v_add_f32_dpp v154, v154, v154 row_half_mirror row_mask:0xf bank_mask:0xf bound_ctrl:1
	v_add_f32_dpp v155, v155, v155 row_half_mirror row_mask:0xf bank_mask:0xf bound_ctrl:1
	v_add_f32_dpp v178, v178, v178 row_half_mirror row_mask:0xf bank_mask:0xf bound_ctrl:1
	v_add_f32_dpp v179, v179, v179 row_half_mirror row_mask:0xf bank_mask:0xf bound_ctrl:1
	v_add_f32_dpp v154, v154, v154 row_mirror row_mask:0xf bank_mask:0xf bound_ctrl:1
	v_add_f32_dpp v155, v155, v155 row_mirror row_mask:0xf bank_mask:0xf bound_ctrl:1
	v_add_f32_dpp v178, v178, v178 row_mirror row_mask:0xf bank_mask:0xf bound_ctrl:1
	v_add_f32_dpp v179, v179, v179 row_mirror row_mask:0xf bank_mask:0xf bound_ctrl:1
	v_pk_mul_f32 v[158:159], v[22:23], v[98:99] op_sel:[0,1] op_sel_hi:[1,1]
	v_pk_mul_f32 v[160:161], v[22:23], v[100:101] op_sel:[0,0] op_sel_hi:[1,0]
	v_pk_mul_f32 v[162:163], v[22:23], v[100:101] op_sel:[0,1] op_sel_hi:[1,1]
	v_pk_fma_f32 v[156:157], v[154:155], v[106:107], v[156:157] op_sel:[0,0,0] op_sel_hi:[1,0,1] neg_lo:[1,0,0] neg_hi:[1,0,0]
	v_pk_fma_f32 v[158:159], v[154:155], v[106:107], v[158:159] op_sel:[0,1,0] op_sel_hi:[1,1,1] neg_lo:[1,0,0] neg_hi:[1,0,0]
	v_pk_fma_f32 v[160:161], v[154:155], v[108:109], v[160:161] op_sel:[0,0,0] op_sel_hi:[1,0,1] neg_lo:[1,0,0] neg_hi:[1,0,0]
	v_pk_fma_f32 v[162:163], v[154:155], v[108:109], v[162:163] op_sel:[0,1,0] op_sel_hi:[1,1,1] neg_lo:[1,0,0] neg_hi:[1,0,0]
	v_pk_mul_f32 v[180:181], v[178:179], v[106:107] op_sel:[0,0] op_sel_hi:[1,0] neg_lo:[1,0] neg_hi:[1,0]
	v_pk_mul_f32 v[182:183], v[178:179], v[106:107] op_sel:[0,1] op_sel_hi:[1,1] neg_lo:[1,0] neg_hi:[1,0]
	v_pk_mul_f32 v[184:185], v[178:179], v[108:109] op_sel:[0,0] op_sel_hi:[1,0] neg_lo:[1,0] neg_hi:[1,0]
	v_pk_mul_f32 v[186:187], v[178:179], v[108:109] op_sel:[0,1] op_sel_hi:[1,1] neg_lo:[1,0] neg_hi:[1,0]
	v_pk_fma_f32 v[146:147], v[146:147], v[94:95], v[156:157] op_sel:[0,0,0] op_sel_hi:[1,0,1]
	v_pk_fma_f32 v[148:149], v[148:149], v[94:95], v[158:159] op_sel:[0,1,0] op_sel_hi:[1,1,1]
	v_pk_fma_f32 v[150:151], v[150:151], v[96:97], v[160:161] op_sel:[0,0,0] op_sel_hi:[1,0,1]
	v_pk_fma_f32 v[152:153], v[152:153], v[96:97], v[162:163] op_sel:[0,1,0] op_sel_hi:[1,1,1]
	v_pk_fma_f32 v[170:171], v[170:171], v[94:95], v[180:181] op_sel:[0,0,0] op_sel_hi:[1,0,1]
	v_pk_fma_f32 v[172:173], v[172:173], v[94:95], v[182:183] op_sel:[0,1,0] op_sel_hi:[1,1,1]
	v_pk_fma_f32 v[174:175], v[174:175], v[96:97], v[184:185] op_sel:[0,0,0] op_sel_hi:[1,0,1]
	v_pk_fma_f32 v[176:177], v[176:177], v[96:97], v[186:187] op_sel:[0,1,0] op_sel_hi:[1,1,1]
	ds_read_b128 v[94:97], v62 offset:21504
	ds_read_b128 v[98:101], v62 offset:22016
	ds_read_b128 v[102:105], v62 offset:22528
	ds_read_b128 v[106:109], v62 offset:22784
	v_add_u32_e32 v22, 0x5400, v63
	ds_read2_b32 v[22:23], v22 offset0:192 offset1:196
	s_waitcnt lgkmcnt(5)
	v_pk_mul_f32 v[154:155], v[146:147], v[86:87] op_sel:[0,0] op_sel_hi:[1,0]
	v_pk_fma_f32 v[154:155], v[148:149], v[86:87], v[154:155] op_sel:[0,1,0] op_sel_hi:[1,1,1]
	v_pk_fma_f32 v[154:155], v[150:151], v[88:89], v[154:155] op_sel:[0,0,0] op_sel_hi:[1,0,1]
	v_pk_fma_f32 v[154:155], v[152:153], v[88:89], v[154:155] op_sel:[0,1,0] op_sel_hi:[1,1,1]
	v_pk_mul_f32 v[178:179], v[170:171], v[86:87] op_sel:[0,0] op_sel_hi:[1,0]
	v_pk_fma_f32 v[178:179], v[172:173], v[86:87], v[178:179] op_sel:[0,1,0] op_sel_hi:[1,1,1]
	v_pk_fma_f32 v[178:179], v[174:175], v[88:89], v[178:179] op_sel:[0,0,0] op_sel_hi:[1,0,1]
	v_pk_fma_f32 v[178:179], v[176:177], v[88:89], v[178:179] op_sel:[0,1,0] op_sel_hi:[1,1,1]
	v_pk_mul_f32 v[156:157], v[110:111], v[82:83] op_sel:[0,0] op_sel_hi:[1,0]
	v_add_f32_dpp v154, v154, v154 quad_perm:[1,0,3,2] row_mask:0xf bank_mask:0xf bound_ctrl:1
	v_add_f32_dpp v155, v155, v155 quad_perm:[1,0,3,2] row_mask:0xf bank_mask:0xf bound_ctrl:1
	v_add_f32_dpp v178, v178, v178 quad_perm:[1,0,3,2] row_mask:0xf bank_mask:0xf bound_ctrl:1
	v_add_f32_dpp v179, v179, v179 quad_perm:[1,0,3,2] row_mask:0xf bank_mask:0xf bound_ctrl:1
	v_add_f32_dpp v154, v154, v154 quad_perm:[2,3,0,1] row_mask:0xf bank_mask:0xf bound_ctrl:1
	v_add_f32_dpp v155, v155, v155 quad_perm:[2,3,0,1] row_mask:0xf bank_mask:0xf bound_ctrl:1
	v_add_f32_dpp v178, v178, v178 quad_perm:[2,3,0,1] row_mask:0xf bank_mask:0xf bound_ctrl:1
	v_add_f32_dpp v179, v179, v179 quad_perm:[2,3,0,1] row_mask:0xf bank_mask:0xf bound_ctrl:1
	v_add_f32_dpp v154, v154, v154 row_half_mirror row_mask:0xf bank_mask:0xf bound_ctrl:1
	v_add_f32_dpp v155, v155, v155 row_half_mirror row_mask:0xf bank_mask:0xf bound_ctrl:1
	v_add_f32_dpp v178, v178, v178 row_half_mirror row_mask:0xf bank_mask:0xf bound_ctrl:1
	v_add_f32_dpp v179, v179, v179 row_half_mirror row_mask:0xf bank_mask:0xf bound_ctrl:1
	v_add_f32_dpp v154, v154, v154 row_mirror row_mask:0xf bank_mask:0xf bound_ctrl:1
	v_add_f32_dpp v155, v155, v155 row_mirror row_mask:0xf bank_mask:0xf bound_ctrl:1
	v_add_f32_dpp v178, v178, v178 row_mirror row_mask:0xf bank_mask:0xf bound_ctrl:1
	v_add_f32_dpp v179, v179, v179 row_mirror row_mask:0xf bank_mask:0xf bound_ctrl:1
	v_pk_mul_f32 v[158:159], v[110:111], v[82:83] op_sel:[0,1] op_sel_hi:[1,1]
	v_pk_mul_f32 v[160:161], v[110:111], v[84:85] op_sel:[0,0] op_sel_hi:[1,0]
	v_pk_mul_f32 v[162:163], v[110:111], v[84:85] op_sel:[0,1] op_sel_hi:[1,1]
	v_pk_fma_f32 v[156:157], v[154:155], v[90:91], v[156:157] op_sel:[0,0,0] op_sel_hi:[1,0,1] neg_lo:[1,0,0] neg_hi:[1,0,0]
	v_pk_fma_f32 v[158:159], v[154:155], v[90:91], v[158:159] op_sel:[0,1,0] op_sel_hi:[1,1,1] neg_lo:[1,0,0] neg_hi:[1,0,0]
	v_pk_fma_f32 v[160:161], v[154:155], v[92:93], v[160:161] op_sel:[0,0,0] op_sel_hi:[1,0,1] neg_lo:[1,0,0] neg_hi:[1,0,0]
	v_pk_fma_f32 v[162:163], v[154:155], v[92:93], v[162:163] op_sel:[0,1,0] op_sel_hi:[1,1,1] neg_lo:[1,0,0] neg_hi:[1,0,0]
	v_pk_mul_f32 v[180:181], v[178:179], v[90:91] op_sel:[0,0] op_sel_hi:[1,0] neg_lo:[1,0] neg_hi:[1,0]
	v_pk_mul_f32 v[182:183], v[178:179], v[90:91] op_sel:[0,1] op_sel_hi:[1,1] neg_lo:[1,0] neg_hi:[1,0]
	v_pk_mul_f32 v[184:185], v[178:179], v[92:93] op_sel:[0,0] op_sel_hi:[1,0] neg_lo:[1,0] neg_hi:[1,0]
	v_pk_mul_f32 v[186:187], v[178:179], v[92:93] op_sel:[0,1] op_sel_hi:[1,1] neg_lo:[1,0] neg_hi:[1,0]
	v_pk_fma_f32 v[146:147], v[146:147], v[78:79], v[156:157] op_sel:[0,0,0] op_sel_hi:[1,0,1]
	v_pk_fma_f32 v[148:149], v[148:149], v[78:79], v[158:159] op_sel:[0,1,0] op_sel_hi:[1,1,1]
	v_pk_fma_f32 v[150:151], v[150:151], v[80:81], v[160:161] op_sel:[0,0,0] op_sel_hi:[1,0,1]
	v_pk_fma_f32 v[152:153], v[152:153], v[80:81], v[162:163] op_sel:[0,1,0] op_sel_hi:[1,1,1]
	v_pk_fma_f32 v[170:171], v[170:171], v[78:79], v[180:181] op_sel:[0,0,0] op_sel_hi:[1,0,1]
	v_pk_fma_f32 v[172:173], v[172:173], v[78:79], v[182:183] op_sel:[0,1,0] op_sel_hi:[1,1,1]
	v_pk_fma_f32 v[174:175], v[174:175], v[80:81], v[184:185] op_sel:[0,0,0] op_sel_hi:[1,0,1]
	v_pk_fma_f32 v[176:177], v[176:177], v[80:81], v[186:187] op_sel:[0,1,0] op_sel_hi:[1,1,1]
	ds_read_b128 v[78:81], v62 offset:23040
	ds_read_b128 v[82:85], v62 offset:23552
	ds_read_b128 v[86:89], v62 offset:24064
	ds_read_b128 v[90:93], v62 offset:24320
	v_add_u32_e32 v110, 0x5c00, v63
	ds_read2_b32 v[110:111], v110 offset0:64 offset1:68
	s_waitcnt lgkmcnt(5)
	v_pk_mul_f32 v[154:155], v[146:147], v[102:103] op_sel:[0,0] op_sel_hi:[1,0]
	v_pk_fma_f32 v[154:155], v[148:149], v[102:103], v[154:155] op_sel:[0,1,0] op_sel_hi:[1,1,1]
	v_pk_fma_f32 v[154:155], v[150:151], v[104:105], v[154:155] op_sel:[0,0,0] op_sel_hi:[1,0,1]
	v_pk_fma_f32 v[154:155], v[152:153], v[104:105], v[154:155] op_sel:[0,1,0] op_sel_hi:[1,1,1]
	v_pk_mul_f32 v[178:179], v[170:171], v[102:103] op_sel:[0,0] op_sel_hi:[1,0]
	v_pk_fma_f32 v[178:179], v[172:173], v[102:103], v[178:179] op_sel:[0,1,0] op_sel_hi:[1,1,1]
	v_pk_fma_f32 v[178:179], v[174:175], v[104:105], v[178:179] op_sel:[0,0,0] op_sel_hi:[1,0,1]
	v_pk_fma_f32 v[178:179], v[176:177], v[104:105], v[178:179] op_sel:[0,1,0] op_sel_hi:[1,1,1]
	v_pk_mul_f32 v[156:157], v[22:23], v[98:99] op_sel:[0,0] op_sel_hi:[1,0]
	v_add_f32_dpp v154, v154, v154 quad_perm:[1,0,3,2] row_mask:0xf bank_mask:0xf bound_ctrl:1
	v_add_f32_dpp v155, v155, v155 quad_perm:[1,0,3,2] row_mask:0xf bank_mask:0xf bound_ctrl:1
	v_add_f32_dpp v178, v178, v178 quad_perm:[1,0,3,2] row_mask:0xf bank_mask:0xf bound_ctrl:1
	v_add_f32_dpp v179, v179, v179 quad_perm:[1,0,3,2] row_mask:0xf bank_mask:0xf bound_ctrl:1
	v_add_f32_dpp v154, v154, v154 quad_perm:[2,3,0,1] row_mask:0xf bank_mask:0xf bound_ctrl:1
	v_add_f32_dpp v155, v155, v155 quad_perm:[2,3,0,1] row_mask:0xf bank_mask:0xf bound_ctrl:1
	v_add_f32_dpp v178, v178, v178 quad_perm:[2,3,0,1] row_mask:0xf bank_mask:0xf bound_ctrl:1
	v_add_f32_dpp v179, v179, v179 quad_perm:[2,3,0,1] row_mask:0xf bank_mask:0xf bound_ctrl:1
	v_add_f32_dpp v154, v154, v154 row_half_mirror row_mask:0xf bank_mask:0xf bound_ctrl:1
	v_add_f32_dpp v155, v155, v155 row_half_mirror row_mask:0xf bank_mask:0xf bound_ctrl:1
	v_add_f32_dpp v178, v178, v178 row_half_mirror row_mask:0xf bank_mask:0xf bound_ctrl:1
	v_add_f32_dpp v179, v179, v179 row_half_mirror row_mask:0xf bank_mask:0xf bound_ctrl:1
	v_add_f32_dpp v154, v154, v154 row_mirror row_mask:0xf bank_mask:0xf bound_ctrl:1
	v_add_f32_dpp v155, v155, v155 row_mirror row_mask:0xf bank_mask:0xf bound_ctrl:1
	v_add_f32_dpp v178, v178, v178 row_mirror row_mask:0xf bank_mask:0xf bound_ctrl:1
	v_add_f32_dpp v179, v179, v179 row_mirror row_mask:0xf bank_mask:0xf bound_ctrl:1
	v_pk_mul_f32 v[158:159], v[22:23], v[98:99] op_sel:[0,1] op_sel_hi:[1,1]
	v_pk_mul_f32 v[160:161], v[22:23], v[100:101] op_sel:[0,0] op_sel_hi:[1,0]
	v_pk_mul_f32 v[162:163], v[22:23], v[100:101] op_sel:[0,1] op_sel_hi:[1,1]
	v_pk_fma_f32 v[156:157], v[154:155], v[106:107], v[156:157] op_sel:[0,0,0] op_sel_hi:[1,0,1] neg_lo:[1,0,0] neg_hi:[1,0,0]
	v_pk_fma_f32 v[158:159], v[154:155], v[106:107], v[158:159] op_sel:[0,1,0] op_sel_hi:[1,1,1] neg_lo:[1,0,0] neg_hi:[1,0,0]
	v_pk_fma_f32 v[160:161], v[154:155], v[108:109], v[160:161] op_sel:[0,0,0] op_sel_hi:[1,0,1] neg_lo:[1,0,0] neg_hi:[1,0,0]
	v_pk_fma_f32 v[162:163], v[154:155], v[108:109], v[162:163] op_sel:[0,1,0] op_sel_hi:[1,1,1] neg_lo:[1,0,0] neg_hi:[1,0,0]
	v_pk_mul_f32 v[180:181], v[178:179], v[106:107] op_sel:[0,0] op_sel_hi:[1,0] neg_lo:[1,0] neg_hi:[1,0]
	v_pk_mul_f32 v[182:183], v[178:179], v[106:107] op_sel:[0,1] op_sel_hi:[1,1] neg_lo:[1,0] neg_hi:[1,0]
	v_pk_mul_f32 v[184:185], v[178:179], v[108:109] op_sel:[0,0] op_sel_hi:[1,0] neg_lo:[1,0] neg_hi:[1,0]
	v_pk_mul_f32 v[186:187], v[178:179], v[108:109] op_sel:[0,1] op_sel_hi:[1,1] neg_lo:[1,0] neg_hi:[1,0]
	v_pk_fma_f32 v[146:147], v[146:147], v[94:95], v[156:157] op_sel:[0,0,0] op_sel_hi:[1,0,1]
	v_pk_fma_f32 v[148:149], v[148:149], v[94:95], v[158:159] op_sel:[0,1,0] op_sel_hi:[1,1,1]
	v_pk_fma_f32 v[150:151], v[150:151], v[96:97], v[160:161] op_sel:[0,0,0] op_sel_hi:[1,0,1]
	v_pk_fma_f32 v[152:153], v[152:153], v[96:97], v[162:163] op_sel:[0,1,0] op_sel_hi:[1,1,1]
	v_pk_fma_f32 v[170:171], v[170:171], v[94:95], v[180:181] op_sel:[0,0,0] op_sel_hi:[1,0,1]
	v_pk_fma_f32 v[172:173], v[172:173], v[94:95], v[182:183] op_sel:[0,1,0] op_sel_hi:[1,1,1]
	v_pk_fma_f32 v[174:175], v[174:175], v[96:97], v[184:185] op_sel:[0,0,0] op_sel_hi:[1,0,1]
	v_pk_fma_f32 v[176:177], v[176:177], v[96:97], v[186:187] op_sel:[0,1,0] op_sel_hi:[1,1,1]
	s_waitcnt lgkmcnt(0)
	v_pk_mul_f32 v[154:155], v[146:147], v[86:87] op_sel:[0,0] op_sel_hi:[1,0]
	v_pk_fma_f32 v[154:155], v[148:149], v[86:87], v[154:155] op_sel:[0,1,0] op_sel_hi:[1,1,1]
	v_pk_fma_f32 v[154:155], v[150:151], v[88:89], v[154:155] op_sel:[0,0,0] op_sel_hi:[1,0,1]
	v_pk_fma_f32 v[154:155], v[152:153], v[88:89], v[154:155] op_sel:[0,1,0] op_sel_hi:[1,1,1]
	v_pk_mul_f32 v[178:179], v[170:171], v[86:87] op_sel:[0,0] op_sel_hi:[1,0]
	v_pk_fma_f32 v[178:179], v[172:173], v[86:87], v[178:179] op_sel:[0,1,0] op_sel_hi:[1,1,1]
	v_pk_fma_f32 v[178:179], v[174:175], v[88:89], v[178:179] op_sel:[0,0,0] op_sel_hi:[1,0,1]
	v_pk_fma_f32 v[178:179], v[176:177], v[88:89], v[178:179] op_sel:[0,1,0] op_sel_hi:[1,1,1]
	v_pk_mul_f32 v[156:157], v[110:111], v[82:83] op_sel:[0,0] op_sel_hi:[1,0]
	v_add_f32_dpp v154, v154, v154 quad_perm:[1,0,3,2] row_mask:0xf bank_mask:0xf bound_ctrl:1
	v_add_f32_dpp v155, v155, v155 quad_perm:[1,0,3,2] row_mask:0xf bank_mask:0xf bound_ctrl:1
	v_add_f32_dpp v178, v178, v178 quad_perm:[1,0,3,2] row_mask:0xf bank_mask:0xf bound_ctrl:1
	v_add_f32_dpp v179, v179, v179 quad_perm:[1,0,3,2] row_mask:0xf bank_mask:0xf bound_ctrl:1
	v_add_f32_dpp v154, v154, v154 quad_perm:[2,3,0,1] row_mask:0xf bank_mask:0xf bound_ctrl:1
	v_add_f32_dpp v155, v155, v155 quad_perm:[2,3,0,1] row_mask:0xf bank_mask:0xf bound_ctrl:1
	v_add_f32_dpp v178, v178, v178 quad_perm:[2,3,0,1] row_mask:0xf bank_mask:0xf bound_ctrl:1
	v_add_f32_dpp v179, v179, v179 quad_perm:[2,3,0,1] row_mask:0xf bank_mask:0xf bound_ctrl:1
	v_add_f32_dpp v154, v154, v154 row_half_mirror row_mask:0xf bank_mask:0xf bound_ctrl:1
	v_add_f32_dpp v155, v155, v155 row_half_mirror row_mask:0xf bank_mask:0xf bound_ctrl:1
	v_add_f32_dpp v178, v178, v178 row_half_mirror row_mask:0xf bank_mask:0xf bound_ctrl:1
	v_add_f32_dpp v179, v179, v179 row_half_mirror row_mask:0xf bank_mask:0xf bound_ctrl:1
	v_add_f32_dpp v154, v154, v154 row_mirror row_mask:0xf bank_mask:0xf bound_ctrl:1
	v_add_f32_dpp v155, v155, v155 row_mirror row_mask:0xf bank_mask:0xf bound_ctrl:1
	v_add_f32_dpp v178, v178, v178 row_mirror row_mask:0xf bank_mask:0xf bound_ctrl:1
	v_add_f32_dpp v179, v179, v179 row_mirror row_mask:0xf bank_mask:0xf bound_ctrl:1
	v_pk_mul_f32 v[158:159], v[110:111], v[82:83] op_sel:[0,1] op_sel_hi:[1,1]
	v_pk_mul_f32 v[160:161], v[110:111], v[84:85] op_sel:[0,0] op_sel_hi:[1,0]
	v_pk_mul_f32 v[162:163], v[110:111], v[84:85] op_sel:[0,1] op_sel_hi:[1,1]
	v_pk_fma_f32 v[156:157], v[154:155], v[90:91], v[156:157] op_sel:[0,0,0] op_sel_hi:[1,0,1] neg_lo:[1,0,0] neg_hi:[1,0,0]
	v_pk_fma_f32 v[158:159], v[154:155], v[90:91], v[158:159] op_sel:[0,1,0] op_sel_hi:[1,1,1] neg_lo:[1,0,0] neg_hi:[1,0,0]
	v_pk_fma_f32 v[160:161], v[154:155], v[92:93], v[160:161] op_sel:[0,0,0] op_sel_hi:[1,0,1] neg_lo:[1,0,0] neg_hi:[1,0,0]
	v_pk_fma_f32 v[162:163], v[154:155], v[92:93], v[162:163] op_sel:[0,1,0] op_sel_hi:[1,1,1] neg_lo:[1,0,0] neg_hi:[1,0,0]
	v_pk_mul_f32 v[180:181], v[178:179], v[90:91] op_sel:[0,0] op_sel_hi:[1,0] neg_lo:[1,0] neg_hi:[1,0]
	v_pk_mul_f32 v[182:183], v[178:179], v[90:91] op_sel:[0,1] op_sel_hi:[1,1] neg_lo:[1,0] neg_hi:[1,0]
	v_pk_mul_f32 v[184:185], v[178:179], v[92:93] op_sel:[0,0] op_sel_hi:[1,0] neg_lo:[1,0] neg_hi:[1,0]
	v_pk_mul_f32 v[186:187], v[178:179], v[92:93] op_sel:[0,1] op_sel_hi:[1,1] neg_lo:[1,0] neg_hi:[1,0]
	v_pk_fma_f32 v[146:147], v[146:147], v[78:79], v[156:157] op_sel:[0,0,0] op_sel_hi:[1,0,1]
	v_pk_fma_f32 v[148:149], v[148:149], v[78:79], v[158:159] op_sel:[0,1,0] op_sel_hi:[1,1,1]
	v_pk_fma_f32 v[150:151], v[150:151], v[80:81], v[160:161] op_sel:[0,0,0] op_sel_hi:[1,0,1]
	v_pk_fma_f32 v[152:153], v[152:153], v[80:81], v[162:163] op_sel:[0,1,0] op_sel_hi:[1,1,1]
	v_pk_fma_f32 v[170:171], v[170:171], v[78:79], v[180:181] op_sel:[0,0,0] op_sel_hi:[1,0,1]
	v_pk_fma_f32 v[172:173], v[172:173], v[78:79], v[182:183] op_sel:[0,1,0] op_sel_hi:[1,1,1]
	v_pk_fma_f32 v[174:175], v[174:175], v[80:81], v[184:185] op_sel:[0,0,0] op_sel_hi:[1,0,1]
	v_pk_fma_f32 v[176:177], v[176:177], v[80:81], v[186:187] op_sel:[0,1,0] op_sel_hi:[1,1,1]
	s_waitcnt lgkmcnt(0)
	s_barrier
	s_add_i32 s33, s33, 3
	s_cmp_gt_u32 s33, 14
	s_cbranch_scc1 .LBB0_730
	s_and_saveexec_b64 s[52:53], s[20:21]
	s_cbranch_execz .LBB0_753
	s_and_saveexec_b64 s[36:37], s[26:27]
	s_xor_b64 s[54:55], exec, s[36:37]
	s_cbranch_execz .LBB0_751
	s_waitcnt vmcnt(0)
	v_cvt_f32_f16_sdwa v79, v0 dst_sel:DWORD dst_unused:UNUSED_PAD src0_sel:WORD_1
	v_cvt_f32_f16_e32 v78, v0
	v_cvt_f32_f16_sdwa v81, v1 dst_sel:DWORD dst_unused:UNUSED_PAD src0_sel:WORD_1
	v_cvt_f32_f16_e32 v80, v1
	v_cvt_f32_f16_sdwa v83, v2 dst_sel:DWORD dst_unused:UNUSED_PAD src0_sel:WORD_1
	v_cvt_f32_f16_e32 v82, v2
	v_cvt_f32_f16_sdwa v85, v3 dst_sel:DWORD dst_unused:UNUSED_PAD src0_sel:WORD_1
	v_cvt_f32_f16_e32 v84, v3
	ds_write_b128 v55, v[78:81]
	ds_write_b128 v55, v[82:85] offset:16

.LBB0_2409:
	s_cmp_lt_i32 s42, 18
	s_cselect_b64 s[0:1], -1, 0
	s_cmp_gt_i32 s43, 17
	s_cselect_b64 s[2:3], -1, 0
	s_and_b64 s[0:1], s[0:1], s[2:3]
	s_andn2_b64 vcc, exec, s[0:1]
	s_cbranch_vccnz .LBB0_2829
	v_mbcnt_hi_u32_b32 v0, -1, v210
	v_add_u32_e32 v64, s91, v0
	s_load_dword s60, s[88:89], 0x160
	s_mov_b32 s61, s90
	s_mov_b64 s[44:45], s[88:89]
	s_add_u32 s38, s88, 0x160
	v_readfirstlane_b32 s0, v64
	s_waitcnt lgkmcnt(0)
	s_mov_b32 s62, s60
	s_load_dwordx2 s[46:47], s[44:45], 0x150
	s_addc_u32 s39, s89, 0
	s_ashr_i32 s63, s0, 6
	v_and_b32_e32 v66, 63, v64
	v_and_b32_e32 v67, 15, v64
	s_waitcnt lgkmcnt(0)
	s_add_u32 s56, s46, 0x6200000
	s_addc_u32 s57, s47, 0
	s_add_u32 s58, s46, 0xfa00000
	s_addc_u32 s59, s47, 0
	s_add_u32 s64, s46, 0xfe00000
	s_addc_u32 s65, s47, 0
	s_cmpk_gt_i32 s61, 0x1ff
	v_lshrrev_b32_e32 v39, 4, v66
	s_cbranch_scc1 .LBB0_2474
	v_lshl_or_b32 v0, s63, 3, v39
	v_lshlrev_b32_e32 v2, 2, v67
	v_or_b32_e32 v1, 1, v2
	v_or_b32_e32 v5, 3, v2
	v_or_b32_e32 v4, 4, v0
	s_mov_b32 s1, 0x92492493
	v_cmp_eq_u32_e64 s[6:7], v1, v0
	v_cmp_eq_u32_e64 s[10:11], v5, v0
	v_cmp_eq_u32_e64 s[14:15], v1, v4
	v_cmp_eq_u32_e64 s[18:19], v5, v4
	v_mul_hi_i32 v1, v64, s1
	v_add_u32_e32 v5, 0x200, v64
	v_or_b32_e32 v3, 2, v2
	v_add_u32_e32 v1, v1, v64
	v_mul_hi_i32 v6, v5, s1
	v_cmp_eq_u32_e64 s[8:9], v3, v0
	v_cmp_eq_u32_e64 s[16:17], v3, v4
	v_lshrrev_b32_e32 v3, 31, v1
	v_ashrrev_i32_e32 v1, 5, v1
	v_add_u32_e32 v6, v6, v5
	v_add_u32_e32 v3, v1, v3
	v_lshrrev_b32_e32 v7, 31, v6
	v_ashrrev_i32_e32 v6, 5, v6
	v_mul_lo_u32 v1, v3, 56
	v_add_u32_e32 v6, v6, v7
	s_movk_i32 s0, 0x380
	v_sub_u32_e32 v1, v64, v1
	v_mul_lo_u32 v7, v6, 56
	s_movk_i32 s1, 0x600
	v_mad_i64_i32 v[24:25], s[2:3], v3, s0, 0
	v_lshlrev_b32_e32 v26, 4, v1
	v_sub_u32_e32 v52, v5, v7
	v_cmp_lt_i32_e64 s[26:27], 15, v1
	v_mul_lo_u32 v7, v3, s1
	v_lshlrev_b32_e32 v1, 5, v1
	s_movk_i32 s2, 0x180
	v_add_u32_e32 v53, 0, v7
	v_and_b32_e32 v7, 0xffffff00, v1
	v_and_b32_e32 v1, 0xe0, v1
	v_cmp_gt_i32_e64 s[22:23], s2, v64
	s_movk_i32 s2, 0x17f
	v_add3_u32 v54, v53, v7, v1
	v_mul_lo_u32 v56, v6, s1
	v_lshlrev_b32_e32 v1, 3, v52
	v_cmp_lt_i32_e64 s[24:25], s2, v64
	v_mad_i64_i32 v[28:29], s[2:3], v6, s0, 0
	v_add_u32_e32 v57, 0, v56
	v_and_b32_e32 v58, 0x7fffffc0, v1
	v_and_b32_e32 v59, 56, v1
	s_movk_i32 s2, 0xff00
	v_lshl_add_u32 v7, v58, 2, v57
	v_lshlrev_b32_e32 v1, 2, v59
	v_add3_u32 v60, v7, v1, s2
	v_add_u32_e32 v1, 16, v3
	v_mad_i64_i32 v[32:33], s[2:3], v1, s0, 0
	v_add_u32_e32 v1, 16, v6
	v_mad_i64_i32 v[34:35], s[2:3], v1, s0, 0
	v_add_u32_e32 v1, 32, v3
	v_mad_i64_i32 v[36:37], s[2:3], v1, s0, 0
	v_lshrrev_b32_e32 v1, 3, v5
	s_mov_b32 s2, 0x24924925
	v_mul_hi_u32 v38, v1, s2
	v_mul_lo_u32 v1, v38, 56
	v_sub_u32_e32 v61, v5, v1
	v_add_u32_e32 v1, 32, v6
	v_mad_i64_i32 v[44:45], s[2:3], v1, s0, 0
	v_ashrrev_i32_e32 v1, 31, v0
	v_cmp_eq_u32_e64 s[4:5], v2, v0
	v_ashrrev_i32_e32 v27, 31, v26
	v_lshlrev_b32_e32 v30, 4, v52
	v_mov_b32_e32 v43, 0
	v_lshl_add_u32 v63, v0, 2, 0
	v_ashrrev_i32_e32 v5, 31, v4
	v_lshlrev_b64 v[48:49], 8, v[0:1]
	v_lshlrev_b32_e32 v0, 3, v61
	v_cmp_eq_u32_e64 s[12:13], v2, v4
	v_cmp_gt_i32_e64 s[20:21], s0, v64
	v_ashrrev_i32_e32 v31, 31, v30
	v_add_u32_e32 v55, 0xffffff00, v54
	v_cmp_lt_i32_e64 s[28:29], 15, v52
	v_lshlrev_b32_e32 v40, 4, v61
	v_mov_b32_e32 v41, v43
	v_lshl_add_u32 v62, v67, 4, 0
	v_lshlrev_b64 v[46:47], 8, v[4:5]
	v_mul_lo_u32 v65, v38, s1
	v_and_b32_e32 v68, 0x1c0, v0
	v_and_b32_e32 v69, 56, v0
	v_mad_i64_i32 v[50:51], s[2:3], v3, s0, v[26:27]
	v_lshlrev_b32_e32 v42, 2, v2
	s_lshl_b32 s1, s61, 1
	s_branch .LBB0_2414

	.amdhsa_kernel _Z6mk_fwd4Args
		.amdhsa_group_segment_fixed_size 0
		.amdhsa_private_segment_fixed_size 0
		.amdhsa_kernarg_size 608
		.amdhsa_user_sgpr_count 2
		.amdhsa_user_sgpr_dispatch_ptr 0
		.amdhsa_user_sgpr_queue_ptr 0
		.amdhsa_user_sgpr_kernarg_segment_ptr 1
		.amdhsa_user_sgpr_dispatch_id 0
		.amdhsa_user_sgpr_kernarg_preload_length 0
		.amdhsa_user_sgpr_kernarg_preload_offset 0
		.amdhsa_user_sgpr_private_segment_size 0
		.amdhsa_uses_dynamic_stack 0
		.amdhsa_enable_private_segment 0
		.amdhsa_system_sgpr_workgroup_id_x 1
		.amdhsa_system_sgpr_workgroup_id_y 0
		.amdhsa_system_sgpr_workgroup_id_z 0
		.amdhsa_system_sgpr_workgroup_info 0
		.amdhsa_system_vgpr_workitem_id 2
		.amdhsa_next_free_vgpr 255
		.amdhsa_next_free_sgpr 100
		.amdhsa_accum_offset 256
		.amdhsa_reserve_vcc 1
		.amdhsa_float_round_mode_32 0
		.amdhsa_float_round_mode_16_64 0
		.amdhsa_float_denorm_mode_32 3
		.amdhsa_float_denorm_mode_16_64 3
		.amdhsa_dx10_clamp 1
		.amdhsa_ieee_mode 1
		.amdhsa_fp16_overflow 0
		.amdhsa_tg_split 0
		.amdhsa_exception_fp_ieee_invalid_op 0
		.amdhsa_exception_fp_denorm_src 0
		.amdhsa_exception_fp_ieee_div_zero 0
		.amdhsa_exception_fp_ieee_overflow 0
		.amdhsa_exception_fp_ieee_underflow 0
		.amdhsa_exception_fp_ieee_inexact 0
		.amdhsa_exception_int_div_zero 0
	.end_amdhsa_kernel

amdhsa.kernels:
  - .agpr_count:     0
    .args:
      - .offset:         0
        .size:           352
        .value_kind:     by_value
      - .offset:         352
        .size:           4
        .value_kind:     hidden_block_count_x
      - .offset:         356
        .size:           4
        .value_kind:     hidden_block_count_y
      - .offset:         360
        .size:           4
        .value_kind:     hidden_block_count_z
      - .offset:         364
        .size:           2
        .value_kind:     hidden_group_size_x
      - .offset:         366
        .size:           2
        .value_kind:     hidden_group_size_y
      - .offset:         368
        .size:           2
        .value_kind:     hidden_group_size_z
      - .offset:         370
        .size:           2
        .value_kind:     hidden_remainder_x
      - .offset:         372
        .size:           2
        .value_kind:     hidden_remainder_y
      - .offset:         374
        .size:           2
        .value_kind:     hidden_remainder_z
      - .offset:         392
        .size:           8
        .value_kind:     hidden_global_offset_x
      - .offset:         400
        .size:           8
        .value_kind:     hidden_global_offset_y
      - .offset:         408
        .size:           8
        .value_kind:     hidden_global_offset_z
      - .offset:         416
        .size:           2
        .value_kind:     hidden_grid_dims
      - .offset:         440
        .size:           8
        .value_kind:     hidden_multigrid_sync_arg
      - .offset:         472
        .size:           4
        .value_kind:     hidden_dynamic_lds_size
    .group_segment_fixed_size: 0
    .kernarg_segment_align: 8
    .kernarg_segment_size: 608
    .language:       OpenCL C
    .language_version:
      - 2
      - 0
    .max_flat_workgroup_size: 512
    .name:           _Z6mk_fwd4Args
    .private_segment_fixed_size: 0
    .sgpr_count:     106
    .sgpr_spill_count: 11
    .symbol:         _Z6mk_fwd4Args.kd
    .uniform_work_group_size: 1
    .uses_dynamic_stack: false
    .vgpr_count:     255
    .vgpr_spill_count: 0
    .wavefront_size: 64
